# k9 with ONE kernel-wide static priority raise for waves 0-3 at entry and every other s_setprio removed
# speedup vs baseline: 1.0116x; 1.0023x over previous
; #define LAS __attribute__((address_space(3)))
; __device__ __forceinline__ int opaque(int x) { asm volatile("" : "+v"(x)); return x; }
;     __device__ __forceinline__ const float* in(int k) const { return (const float*)(const __attribute__((address_space(1))) float*)get(k); }
;     __device__ __forceinline__ unsigned char* ws() const { return (unsigned char*)(__attribute__((address_space(1))) unsigned char*)get(21); }
; #define FRESH() do { ws = opaque_p(A.ws()); tid = opaque(TID()); lane = tid & 63; wave = __builtin_amdgcn_readfirstlane(tid >> 6); G = opaque_s(gridDim.x); c = opaque_s(blockIdx.x); gw = c * 8 + wave; NGW = G * 8; } while (0)
; __device__ __forceinline__ void convert_weights(const Ptrs& A, int l, LAS unsigned char* lds, int gw, int NGW, int wave, int lane_) {
;     const int lane = opaque(lane_);
;     LAS float* scr = (LAS float*)(lds + wave * 16384);
;     unsigned char* ws = A.ws();
;     constexpr int I_IN = 32 * 416, I_BR = 16 * 64, I_O = 32 * 64, I_GU = 32 * 352, I_DN = 88 * 64, I_MK = 32 * 64;
;     const int total = I_IN + 3 * I_BR + I_O + I_GU + I_DN + (l == 0 ? 2 * I_MK : 0);
;     for (int it = gw; it < total; it += NGW) {
;         int r = it;
;         if (r < I_IN) { const int kb = r / 416, nb = r % 416, dn = 32 * nb; transpose_item(A.in(3) + (size_t)l * DM * INW, INW, dn + (dn >= 3072 ? 16 : 0), 64 * kb, (bf16*)(ws + WS_WIN), DM, dn, scr, lane); continue; } r -= I_IN;
; template <int l>
; __device__ __forceinline__ void layer_body(const Ptrs& A, LAS unsigned char* lds, unsigned char* lds_raw, const int wv0) {
;     ...
;         FRESH();
;         if (PH(1)) {
;             convert_weights(A, l, lds, gw, NGW, wave, lane);
.LBB0_7:
	s_or_b64 exec, exec, s[2:3]
	s_add_i32 s77, 0, 0x23f00
	v_mov_b32 v2, s77
	ds_read_b64 v[2:3], v2 offset:168
	v_mbcnt_lo_u32_b32 v205, -1, 0
	s_andn2_b32 s34, s34, 63
	s_cmp_lt_u32 s34, 0x100
	s_cbranch_scc0 .Lprio_kernel
	s_setprio 1
.Lprio_kernel:
	s_mov_b32 s3, 0
	s_waitcnt lgkmcnt(0)
	v_readfirstlane_b32 s10, v2
	v_mbcnt_hi_u32_b32 v2, -1, v205
	v_add_u32_e32 v204, s34, v2
	v_readfirstlane_b32 s11, v3
	v_mov_b32_e32 v2, v204
	s_load_dword s76, s[0:1], 0xb0
	v_readfirstlane_b32 s2, v2
	v_and_b32_e32 v34, 63, v2
	s_ashr_i32 s4, s2, 6
	s_add_u32 s70, s0, 0xb0
	s_waitcnt lgkmcnt(0)
	s_mov_b32 s2, s76
	s_mov_b32 s0, s33
	v_mov_b32_e32 v4, v34
	v_mov_b32 v3, s77
	ds_read_b64 v[6:7], v3 offset:168
	s_addc_u32 s71, s1, 0
	s_lshl_b32 s0, s0, 3
	s_add_i32 s6, s0, s4
	s_lshl_b32 s8, s2, 3
	s_waitcnt lgkmcnt(0)
	v_readfirstlane_b32 s1, v7
	s_cmp_gt_i32 s6, 0x99ff
	v_readfirstlane_b32 s0, v6
	s_cbranch_scc1 .LBB0_38
	s_lshl_b32 s4, s4, 14
	v_ashrrev_i32_e32 v3, 5, v4
	v_and_b32_e32 v24, 31, v4
	s_movk_i32 s5, 0x84
	v_ashrrev_i32_e32 v19, 3, v4
	v_lshlrev_b32_e32 v4, 3, v4
	s_add_i32 s4, s4, 0
	v_lshlrev_b32_e32 v6, 2, v24
	v_mul_lo_u32 v7, v3, s5
	v_and_b32_e32 v16, 56, v4
	v_add3_u32 v18, s4, v6, v7
	v_mul_u32_u24_e32 v4, 0x84, v16
	v_lshlrev_b32_e32 v6, 2, v19
	s_add_u32 s7, s0, 0x8a00000
	v_mov_b32_e32 v5, 0
	v_add3_u32 v20, s4, v4, v6
	v_lshlrev_b32_e32 v4, 1, v16
	s_addc_u32 s9, s1, 0
	v_lshl_add_u64 v[6:7], s[0:1], 0, v[4:5]
	s_mov_b64 s[0:1], 0x7400000
	v_lshl_add_u64 v[8:9], v[6:7], 0, s[0:1]
	s_mov_b64 s[0:1], 0x4800000
	v_lshl_add_u64 v[10:11], v[6:7], 0, s[0:1]
	s_mov_b64 s[0:1], 0x4000000
	v_lshl_add_u64 v[12:13], v[6:7], 0, s[0:1]
	s_mov_b64 s[0:1], 0x3400000
	v_add_u32_e32 v21, 8, v19
	v_add_u32_e32 v22, 16, v19
	v_add_u32_e32 v23, 24, v19
	v_lshl_add_u64 v[14:15], v[6:7], 0, s[0:1]
	s_lshl_b32 s12, s6, 5
	s_lshl_b32 s13, s2, 8
	s_movk_i32 s14, 0x4000
	s_mov_b32 s15, 0x8000
	s_mov_b32 s16, 0xc000
	s_mov_b32 s17, 0x10000
	s_mov_b32 s18, 0x14000
	s_mov_b32 s19, 0x18000
	s_mov_b32 s20, 0x1c000
	s_mov_b32 s21, 0x20000
	s_mov_b32 s22, 0x24000
	s_mov_b32 s23, 0x28000
	s_mov_b32 s24, 0x2c000
	s_mov_b32 s25, 0x30000
	s_mov_b32 s26, 0x34000
	s_mov_b32 s27, 0x38000
	s_mov_b32 s28, 0x3c000
	s_mov_b32 s29, 0x40000
	s_mov_b32 s30, 0x44000
	s_mov_b32 s31, 0x48000
	s_mov_b32 s34, 0x4c000
	s_mov_b32 s35, 0x50000
	s_mov_b32 s36, 0x54000
	s_mov_b32 s37, 0x58000
	s_mov_b32 s38, 0x5c000
	s_mov_b32 s39, 0x60000
	s_mov_b32 s40, 0x64000
	s_mov_b32 s41, 0x68000
	s_mov_b32 s42, 0x6c000
	s_mov_b32 s43, 0x70000
	s_mov_b32 s44, 0x74000
	s_mov_b32 s45, 0x78000
	s_mov_b32 s46, 0x7c000
	v_lshlrev_b32_e32 v16, 1, v16
	s_movk_i32 s47, 0x7fff
	s_mov_b32 s48, 0xffff0000
	s_movk_i32 s49, 0x2c00
	s_mov_b32 s50, 0xb000
	s_mov_b32 s51, 0xd040
	v_lshlrev_b32_e32 v4, 2, v24
	v_add_u32_e32 v24, 0x400, v18
	v_add_u32_e32 v25, 0x800, v18
	v_add_u32_e32 v26, 0xc00, v18
	v_add_u32_e32 v27, 0x1000, v18
	v_add_u32_e32 v28, 0x1400, v18
	v_add_u32_e32 v29, 0x1800, v18
	v_add_u32_e32 v30, 0x1c00, v18
	s_mov_b32 s52, s6
	s_branch .LBB0_10

;     __device__ __forceinline__ bool next(int i, Unit& u) const { int pm, pn; if (!to.get((long)i * G + c, pm, pn)) return false; u.pm = pm; u.pn = pn; u.aux = 0; u.a = A + (size_t)pm * ta; u.b = B + (size_t)pn * tb; return true; }
; template <class Epi, class Sched, bool ALIGN_EPI = false, bool SP2 = false>
; __device__ __forceinline__ void gemm_phase(PG8_LAS unsigned char* lds, const Gemm g, const Sched& S, const Epi& E, const int wv0) {
;     ...
;         PG8_STAGE(PG8_SB(0, 0), cB, voffB); PG8_STAGE(PG8_SB(0, 1), cB + hstepB, voffB); PG8_STAGE(PG8_SA(0, 0), cA, voffA); PG8_STAGE(PG8_SA(0, 1), cA + hstepA, voffA);
;         if (wr == 1) PG8_BAR;
;         PG8_WAIT_V(2); PG8_BAR;
;         PG8_STAGE(PG8_SB(1, 0), cB + kstep, voffB); PG8_STAGE(PG8_SA(1, 0), cA + kstep, voffA); PG8_STAGE(PG8_SB(1, 1), cB + hstepB + kstep, voffB);
;         PG8_WAIT_V(6); PG8_BAR;
;     } else {
;         PG8_STAGE(PG8_SB(0, 0), cB, voffB); PG8_STAGE(PG8_SA(0, 0), cA, voffA); PG8_STAGE(PG8_SB(0, 1), cB + hstepB, voffB); PG8_STAGE(PG8_SA(0, 1), cA + hstepA, voffA);
;         if (wr == 1) PG8_BAR;
;         PG8_WAIT_V(4); PG8_BAR;
;         PG8_STAGE(PG8_SB(1, 0), cB + kstep, voffB); PG8_STAGE(PG8_SA(1, 0), cA + kstep, voffA); PG8_STAGE(PG8_SB(1, 1), cB + hstepB + kstep, voffB);
;         PG8_WAIT_V(6); PG8_BAR;
;     }
;     for (;;) {
;         const bool has_next = S.next(ui + 1, nxt);
;         const char* nA = has_next ? nxt.a : cA; const char* nB = has_next ? nxt.b : cB;
;         for (int t = 0; t < nt; t += 2) {
;             const bool last = (t == nt - 2);
;             const char* a1 = cA + (size_t)(t + 1) * kstep;
;             const char* a2 = last ? nA : cA + (size_t)(t + 2) * kstep; const char* b2 = last ? nB : cB + (size_t)(t + 2) * kstep;
;             const char* a3 = a2 + kstep; const char* b3 = b2 + kstep;
;             if constexpr (SP2) {
;             PG8_LDB(B0, 0, 0); PG8_LDB(B1, 0, 1); PG8_SCHED; PG8_LDA(At, 0, 0); PG8_STAGE(PG8_SA(1, 1), a1 + hstepA, voffA);
;             PG8_WAIT_V(8); PG8_WAIT_L(0); PG8_BAR; PG8_MMA(0, 0, At, B0); PG8_MMA(0, 1, At, B1); PG8_BAR; PG8_SCHED;
;             PG8_LDA(At, 0, 1); PG8_STAGE(PG8_SB(0, 0), b2, voffB); PG8_STAGE(PG8_SB(0, 1), b2 + hstepB, voffB); PG8_STAGE(PG8_SA(0, 0), a2, voffA);
;             PG8_WAIT_V(8); PG8_WAIT_L(0); PG8_BAR; PG8_MMA(1, 0, At, B0); PG8_MMA(1, 1, At, B1); PG8_BAR; PG8_SCHED;
.LBB0_358:
	s_add_i32 s53, s36, s66
	s_and_b32 s51, s47, 3
	v_lshl_add_u64 v[2:3], v[26:27], 0, s[8:9]
	s_mov_b32 m0, s53
	s_add_i32 s55, s53, 0x2000
	s_lshl_b32 s63, s50, 13
	s_lshl_b32 s47, s51, 12
	s_waitcnt vmcnt(2)
	s_barrier
	global_load_lds_dwordx4 v[2:3], off
	v_lshl_add_u64 v[4:5], v[28:29], 0, s[8:9]
	s_mov_b32 m0, s55
	s_add_i32 s54, s61, 0x8000
	s_add_i32 s56, s61, 0xa000
	global_load_lds_dwordx4 v[4:5], off
	v_lshl_add_u64 v[0:1], v[20:21], 0, s[8:9]
	s_mov_b32 m0, s54
	s_add_u32 s64, s24, 0x10080
	global_load_lds_dwordx4 v[0:1], off
	v_lshl_add_u64 v[6:7], v[22:23], 0, s[8:9]
	s_mov_b32 m0, s56
	s_addc_u32 s65, s25, 0
	s_add_i32 s58, s37, s66
	global_load_lds_dwordx4 v[6:7], off
	v_lshl_add_u64 v[8:9], s[64:65], 0, v[128:129]
	s_mov_b32 m0, s58
	s_add_i32 s60, s58, 0x2000
	global_load_lds_dwordx4 v[8:9], off
	v_lshl_add_u64 v[10:11], s[64:65], 0, v[32:33]
	s_mov_b32 m0, s60
	v_bfe_u32 v144, v34, 4, 2
	global_load_lds_dwordx4 v[10:11], off
	v_and_b32_e32 v143, 15, v34
	v_lshlrev_b32_e32 v35, 4, v144
	v_lshlrev_b32_e32 v34, 2, v34
	v_lshl_or_b32 v66, v143, 6, v35
	v_and_b32_e32 v67, 32, v34
	v_bitop3_b32 v68, v66, s47, v67 bitop3:0xde
	s_add_i32 s48, 0, 0x10000
	s_add_i32 s47, 0, 0x14000
	v_add_u32_e32 v202, s48, v68
	s_waitcnt vmcnt(6)
	s_barrier
	v_add_u32_e32 v145, s47, v68
	ds_read_b128 v[34:37], v202
	ds_read_b128 v[38:41], v202 offset:1024
	ds_read_b128 v[42:45], v202 offset:2048
	ds_read_b128 v[46:49], v202 offset:3072
	ds_read_b128 v[50:53], v145
	ds_read_b128 v[54:57], v145 offset:1024
	ds_read_b128 v[58:61], v145 offset:2048
	ds_read_b128 v[62:65], v145 offset:3072
	v_bitop3_b32 v66, v66, s63, v67 bitop3:0xde
	v_add_u32_e32 v203, 0, v66
	v_add_u32_e32 v246, s37, v68
	v_add_u32_e32 v247, s36, v68
	s_add_u32 s64, s22, 0x40080
	s_addc_u32 s65, s23, 0
	s_add_i32 s68, s61, 0xc000
	v_lshl_add_u64 v[98:99], s[64:65], 0, v[16:17]
	s_mov_b32 m0, s68
	s_add_i32 s63, s61, 0xe000
	ds_read_b128 v[66:69], v203
	ds_read_b128 v[70:73], v203 offset:1024
	ds_read_b128 v[74:77], v203 offset:2048
	ds_read_b128 v[78:81], v203 offset:3072
	ds_read_b128 v[82:85], v203 offset:4096
	ds_read_b128 v[86:89], v203 offset:5120
	ds_read_b128 v[90:93], v203 offset:6144
	ds_read_b128 v[94:97], v203 offset:7168
	global_load_lds_dwordx4 v[98:99], off
	v_lshl_add_u64 v[98:99], s[64:65], 0, v[30:31]
	s_mov_b32 m0, s63
	s_nop 0
	global_load_lds_dwordx4 v[98:99], off
	s_waitcnt vmcnt(8)
	s_waitcnt lgkmcnt(0)
	s_barrier
	v_mfma_f32_16x16x32_bf16 v[98:101], v[34:37], v[66:69], 0
	v_mfma_f32_16x16x32_bf16 v[102:105], v[42:45], v[66:69], 0
	v_mfma_f32_16x16x32_bf16 v[106:109], v[34:37], v[74:77], 0
	v_mfma_f32_16x16x32_bf16 v[110:113], v[42:45], v[74:77], 0
	v_mfma_f32_16x16x32_bf16 v[114:117], v[34:37], v[82:85], 0
	v_mfma_f32_16x16x32_bf16 v[118:121], v[42:45], v[82:85], 0
	v_mfma_f32_16x16x32_bf16 v[122:125], v[34:37], v[90:93], 0
	v_mfma_f32_16x16x32_bf16 v[98:101], v[38:41], v[70:73], v[98:101]
	v_mfma_f32_16x16x32_bf16 v[102:105], v[46:49], v[70:73], v[102:105]
	v_mfma_f32_16x16x32_bf16 v[106:109], v[38:41], v[78:81], v[106:109]
	v_mfma_f32_16x16x32_bf16 v[110:113], v[46:49], v[78:81], v[110:113]
	v_mfma_f32_16x16x32_bf16 v[114:117], v[38:41], v[86:89], v[114:117]
	v_mfma_f32_16x16x32_bf16 v[118:121], v[46:49], v[86:89], v[118:121]
	v_mfma_f32_16x16x32_bf16 v[122:125], v[38:41], v[94:97], v[122:125]
	v_mfma_f32_16x16x32_bf16 v[130:133], v[42:45], v[90:93], 0
	v_mfma_f32_16x16x32_bf16 v[130:133], v[46:49], v[94:97], v[130:133]
	v_mfma_f32_16x16x32_bf16 v[134:137], v[50:53], v[66:69], 0
	v_mfma_f32_16x16x32_bf16 v[66:69], v[58:61], v[66:69], 0
	v_mfma_f32_16x16x32_bf16 v[134:137], v[54:57], v[70:73], v[134:137]
	v_mfma_f32_16x16x32_bf16 v[66:69], v[62:65], v[70:73], v[66:69]
	v_mfma_f32_16x16x32_bf16 v[70:73], v[50:53], v[74:77], 0
	v_mfma_f32_16x16x32_bf16 v[74:77], v[58:61], v[74:77], 0
	v_mfma_f32_16x16x32_bf16 v[70:73], v[54:57], v[78:81], v[70:73]
	v_mfma_f32_16x16x32_bf16 v[74:77], v[62:65], v[78:81], v[74:77]
	v_mfma_f32_16x16x32_bf16 v[78:81], v[50:53], v[82:85], 0
	v_mfma_f32_16x16x32_bf16 v[82:85], v[58:61], v[82:85], 0
	v_mfma_f32_16x16x32_bf16 v[78:81], v[54:57], v[86:89], v[78:81]
	v_mfma_f32_16x16x32_bf16 v[82:85], v[62:65], v[86:89], v[82:85]
	v_mfma_f32_16x16x32_bf16 v[86:89], v[50:53], v[90:93], 0
	v_mfma_f32_16x16x32_bf16 v[90:93], v[58:61], v[90:93], 0
	v_mfma_f32_16x16x32_bf16 v[86:89], v[54:57], v[94:97], v[86:89]
	v_mfma_f32_16x16x32_bf16 v[90:93], v[62:65], v[94:97], v[90:93]
	s_barrier
	s_add_i32 s64, s48, s66
	s_add_i32 s65, s64, 0x2000
	v_lshl_add_u64 v[126:127], v[26:27], 0, s[10:11]
	s_mov_b32 m0, s64
	s_add_u32 s70, s24, 0x10100
	ds_read_b128 v[94:97], v203 offset:16384
	ds_read_b128 v[138:141], v203 offset:17408
	ds_read_b128 v[146:149], v203 offset:18432
	ds_read_b128 v[150:153], v203 offset:19456
	ds_read_b128 v[154:157], v203 offset:20480
	ds_read_b128 v[158:161], v203 offset:21504
	ds_read_b128 v[162:165], v203 offset:22528
	ds_read_b128 v[166:169], v203 offset:23552
	global_load_lds_dwordx4 v[126:127], off
	v_lshl_add_u64 v[126:127], v[28:29], 0, s[10:11]
	s_mov_b32 m0, s65
	s_addc_u32 s71, s25, 0
	s_add_i32 s66, s47, s66
	global_load_lds_dwordx4 v[126:127], off
	v_lshl_add_u64 v[126:127], s[70:71], 0, v[128:129]
	s_mov_b32 m0, s66
	s_add_i32 s67, s66, 0x2000
	global_load_lds_dwordx4 v[126:127], off
	v_lshl_add_u64 v[126:127], s[70:71], 0, v[32:33]
	s_mov_b32 m0, s67
	s_nop 0
	global_load_lds_dwordx4 v[126:127], off
	v_lshl_add_u64 v[126:127], v[20:21], 0, s[10:11]
	s_mov_b32 m0, s61
	s_nop 0
	global_load_lds_dwordx4 v[126:127], off
	v_lshl_add_u64 v[126:127], v[22:23], 0, s[10:11]
	s_mov_b32 m0, s62
	s_nop 0
	global_load_lds_dwordx4 v[126:127], off
	s_waitcnt vmcnt(8)
	s_waitcnt lgkmcnt(0)
	s_barrier
; #define PG8_STAGE(bufoff, gbase, voff) do { _Pragma("unroll") for (int _i = 0; _i < 2; ++_i) \
;         __builtin_amdgcn_global_load_lds((const unsigned*)((const char*)(gbase) + (voff)[_i]), (PG8_LAS unsigned*)(lds + (bufoff) + ldsw + _i * 8192), 16, 0, 0); } while (0)
; #define PG8_LDA(dst, b, h) do { _Pragma("unroll") for (int m = 0; m < 4; ++m) _Pragma("unroll") for (int k = 0; k < 2; ++k) dst[m][k] = *(const PG8_LAS bf16x8*)(lds + PG8_SA(b, h) + aoff + m * 2048 + k * 1024); } while (0)
; #define PG8_LDB(dst, b, h) do { _Pragma("unroll") for (int n = 0; n < 2; ++n) _Pragma("unroll") for (int k = 0; k < 2; ++k) dst[n][k] = *(const PG8_LAS bf16x8*)(lds + PG8_SB(b, h) + boff + n * 2048 + k * 1024); } while (0)
; #define PG8_MMA(ai, bj, At, Bt) do { __builtin_amdgcn_s_setprio(1); _Pragma("unroll") for (int m = 0; m < 4; ++m) _Pragma("unroll") for (int n = 0; n < 2; ++n) _Pragma("unroll") for (int k = 0; k < 2; ++k) \
;         acc[ai][bj][m][n] = __builtin_amdgcn_mfma_f32_16x16x32_bf16(Bt[n][k], At[m][k], acc[ai][bj][m][n], 0, 0, 0); __builtin_amdgcn_s_setprio(0); } while (0)
; #define PG8_WAIT_V(n) asm volatile("s_waitcnt vmcnt(" #n ")" ::: "memory")
; #define PG8_WAIT_L(n) asm volatile("s_waitcnt lgkmcnt(" #n ")" ::: "memory")
; #define PG8_BAR __builtin_amdgcn_s_barrier()
; #define PG8_SCHED __builtin_amdgcn_sched_barrier(0)
; template <class Epi, class Sched, bool ALIGN_EPI = false, bool SP2 = false>
; __device__ __forceinline__ void gemm_phase(PG8_LAS unsigned char* lds, const Gemm g, const Sched& S, const Epi& E, const int wv0) {
;     ...
;             PG8_LDA(At, 0, 1); PG8_STAGE(PG8_SB(0, 0), b2, voffB); PG8_STAGE(PG8_SB(0, 1), b2 + hstepB, voffB); PG8_STAGE(PG8_SA(0, 0), a2, voffA);
;             PG8_WAIT_V(8); PG8_WAIT_L(0); PG8_BAR; PG8_MMA(1, 0, At, B0); PG8_MMA(1, 1, At, B1); PG8_BAR; PG8_SCHED;
;             PG8_LDB(B0, 1, 0); PG8_LDB(B1, 1, 1); PG8_SCHED; PG8_LDA(At, 1, 0); PG8_STAGE(PG8_SA(0, 1), a2 + hstepA, voffA);
;             PG8_WAIT_V(8); PG8_WAIT_L(0); PG8_BAR; PG8_MMA(0, 0, At, B0); PG8_MMA(0, 1, At, B1); PG8_BAR; PG8_SCHED;
	v_mfma_f32_16x16x32_bf16 v[170:173], v[34:37], v[94:97], 0
	v_mfma_f32_16x16x32_bf16 v[178:181], v[34:37], v[146:149], 0
	v_mfma_f32_16x16x32_bf16 v[186:189], v[34:37], v[154:157], 0
	v_mfma_f32_16x16x32_bf16 v[34:37], v[34:37], v[162:165], 0
	v_mfma_f32_16x16x32_bf16 v[170:173], v[38:41], v[138:141], v[170:173]
	v_mfma_f32_16x16x32_bf16 v[178:181], v[38:41], v[150:153], v[178:181]
	v_mfma_f32_16x16x32_bf16 v[186:189], v[38:41], v[158:161], v[186:189]
	v_mfma_f32_16x16x32_bf16 v[34:37], v[38:41], v[166:169], v[34:37]
	v_mfma_f32_16x16x32_bf16 v[38:41], v[42:45], v[162:165], 0
	v_mfma_f32_16x16x32_bf16 v[174:177], v[42:45], v[94:97], 0
	v_mfma_f32_16x16x32_bf16 v[182:185], v[42:45], v[146:149], 0
	v_mfma_f32_16x16x32_bf16 v[190:193], v[42:45], v[154:157], 0
	v_mfma_f32_16x16x32_bf16 v[38:41], v[46:49], v[166:169], v[38:41]
	v_mfma_f32_16x16x32_bf16 v[174:177], v[46:49], v[138:141], v[174:177]
	v_mfma_f32_16x16x32_bf16 v[182:185], v[46:49], v[150:153], v[182:185]
	v_mfma_f32_16x16x32_bf16 v[190:193], v[46:49], v[158:161], v[190:193]
	v_mfma_f32_16x16x32_bf16 v[42:45], v[50:53], v[94:97], 0
	v_mfma_f32_16x16x32_bf16 v[46:49], v[58:61], v[94:97], 0
	v_mfma_f32_16x16x32_bf16 v[42:45], v[54:57], v[138:141], v[42:45]
	v_mfma_f32_16x16x32_bf16 v[46:49], v[62:65], v[138:141], v[46:49]
	v_mfma_f32_16x16x32_bf16 v[94:97], v[50:53], v[146:149], 0
	v_mfma_f32_16x16x32_bf16 v[138:141], v[58:61], v[146:149], 0
	v_mfma_f32_16x16x32_bf16 v[146:149], v[50:53], v[154:157], 0
	v_mfma_f32_16x16x32_bf16 v[50:53], v[50:53], v[162:165], 0
	v_mfma_f32_16x16x32_bf16 v[94:97], v[54:57], v[150:153], v[94:97]
	v_mfma_f32_16x16x32_bf16 v[146:149], v[54:57], v[158:161], v[146:149]
	v_mfma_f32_16x16x32_bf16 v[50:53], v[54:57], v[166:169], v[50:53]
	v_mfma_f32_16x16x32_bf16 v[54:57], v[58:61], v[162:165], 0
	v_mfma_f32_16x16x32_bf16 v[138:141], v[62:65], v[150:153], v[138:141]
	v_mfma_f32_16x16x32_bf16 v[150:153], v[58:61], v[154:157], 0
	v_mfma_f32_16x16x32_bf16 v[54:57], v[62:65], v[166:169], v[54:57]
	v_mfma_f32_16x16x32_bf16 v[150:153], v[62:65], v[158:161], v[150:153]
	s_barrier
	ds_read_b128 v[58:61], v247
	ds_read_b128 v[62:65], v247 offset:1024
	ds_read_b128 v[154:157], v247 offset:2048
	ds_read_b128 v[158:161], v247 offset:3072
	ds_read_b128 v[162:165], v246
	ds_read_b128 v[166:169], v246 offset:1024
	ds_read_b128 v[194:197], v246 offset:2048
	ds_read_b128 v[198:201], v246 offset:3072
	s_add_u32 s70, s22, 0x40100
	s_addc_u32 s71, s23, 0
	s_mov_b32 m0, s57
	v_lshl_add_u64 v[126:127], s[70:71], 0, v[16:17]
	ds_read_b128 v[206:209], v203 offset:32768
	ds_read_b128 v[210:213], v203 offset:33792
	ds_read_b128 v[214:217], v203 offset:34816
	ds_read_b128 v[218:221], v203 offset:35840
	ds_read_b128 v[222:225], v203 offset:36864
	ds_read_b128 v[226:229], v203 offset:37888
	ds_read_b128 v[230:233], v203 offset:38912
	ds_read_b128 v[234:237], v203 offset:39936
	global_load_lds_dwordx4 v[126:127], off
	v_lshl_add_u64 v[126:127], s[70:71], 0, v[30:31]
	s_mov_b32 m0, s59
	s_nop 0
	global_load_lds_dwordx4 v[126:127], off
	s_waitcnt vmcnt(8)
	s_waitcnt lgkmcnt(0)
	s_barrier
	v_mfma_f32_16x16x32_bf16 v[98:101], v[58:61], v[206:209], v[98:101]
	v_mfma_f32_16x16x32_bf16 v[102:105], v[154:157], v[206:209], v[102:105]
	v_mfma_f32_16x16x32_bf16 v[106:109], v[58:61], v[214:217], v[106:109]
	v_mfma_f32_16x16x32_bf16 v[110:113], v[154:157], v[214:217], v[110:113]
	v_mfma_f32_16x16x32_bf16 v[114:117], v[58:61], v[222:225], v[114:117]
	v_mfma_f32_16x16x32_bf16 v[118:121], v[154:157], v[222:225], v[118:121]
	v_mfma_f32_16x16x32_bf16 v[122:125], v[58:61], v[230:233], v[122:125]
	v_mfma_f32_16x16x32_bf16 v[98:101], v[62:65], v[210:213], v[98:101]
	v_mfma_f32_16x16x32_bf16 v[102:105], v[158:161], v[210:213], v[102:105]
	v_mfma_f32_16x16x32_bf16 v[106:109], v[62:65], v[218:221], v[106:109]
	v_mfma_f32_16x16x32_bf16 v[110:113], v[158:161], v[218:221], v[110:113]
	v_mfma_f32_16x16x32_bf16 v[114:117], v[62:65], v[226:229], v[114:117]
	v_mfma_f32_16x16x32_bf16 v[118:121], v[158:161], v[226:229], v[118:121]
	v_mfma_f32_16x16x32_bf16 v[122:125], v[62:65], v[234:237], v[122:125]
	v_mfma_f32_16x16x32_bf16 v[130:133], v[154:157], v[230:233], v[130:133]
	v_mfma_f32_16x16x32_bf16 v[130:133], v[158:161], v[234:237], v[130:133]
	v_mfma_f32_16x16x32_bf16 v[66:69], v[194:197], v[206:209], v[66:69]
	v_mfma_f32_16x16x32_bf16 v[70:73], v[162:165], v[214:217], v[70:73]
	v_mfma_f32_16x16x32_bf16 v[74:77], v[194:197], v[214:217], v[74:77]
	v_mfma_f32_16x16x32_bf16 v[78:81], v[162:165], v[222:225], v[78:81]
	v_mfma_f32_16x16x32_bf16 v[82:85], v[194:197], v[222:225], v[82:85]
	v_mfma_f32_16x16x32_bf16 v[86:89], v[162:165], v[230:233], v[86:89]
	v_mfma_f32_16x16x32_bf16 v[90:93], v[194:197], v[230:233], v[90:93]
	v_mfma_f32_16x16x32_bf16 v[134:137], v[162:165], v[206:209], v[134:137]
	v_mfma_f32_16x16x32_bf16 v[66:69], v[198:201], v[210:213], v[66:69]
	v_mfma_f32_16x16x32_bf16 v[70:73], v[166:169], v[218:221], v[70:73]
	v_mfma_f32_16x16x32_bf16 v[74:77], v[198:201], v[218:221], v[74:77]
	v_mfma_f32_16x16x32_bf16 v[78:81], v[166:169], v[226:229], v[78:81]
	v_mfma_f32_16x16x32_bf16 v[82:85], v[198:201], v[226:229], v[82:85]
	v_mfma_f32_16x16x32_bf16 v[86:89], v[166:169], v[234:237], v[86:89]
	v_mfma_f32_16x16x32_bf16 v[90:93], v[198:201], v[234:237], v[90:93]
	v_mfma_f32_16x16x32_bf16 v[134:137], v[166:169], v[210:213], v[134:137]
	s_barrier
; #define PG8_STAGE(bufoff, gbase, voff) do { _Pragma("unroll") for (int _i = 0; _i < 2; ++_i) \
;         __builtin_amdgcn_global_load_lds((const unsigned*)((const char*)(gbase) + (voff)[_i]), (PG8_LAS unsigned*)(lds + (bufoff) + ldsw + _i * 8192), 16, 0, 0); } while (0)
; #define PG8_LDA(dst, b, h) do { _Pragma("unroll") for (int m = 0; m < 4; ++m) _Pragma("unroll") for (int k = 0; k < 2; ++k) dst[m][k] = *(const PG8_LAS bf16x8*)(lds + PG8_SA(b, h) + aoff + m * 2048 + k * 1024); } while (0)
; #define PG8_MMA(ai, bj, At, Bt) do { __builtin_amdgcn_s_setprio(1); _Pragma("unroll") for (int m = 0; m < 4; ++m) _Pragma("unroll") for (int n = 0; n < 2; ++n) _Pragma("unroll") for (int k = 0; k < 2; ++k) \
;         acc[ai][bj][m][n] = __builtin_amdgcn_mfma_f32_16x16x32_bf16(Bt[n][k], At[m][k], acc[ai][bj][m][n], 0, 0, 0); __builtin_amdgcn_s_setprio(0); } while (0)
; #define PG8_WAIT_V(n) asm volatile("s_waitcnt vmcnt(" #n ")" ::: "memory")
; #define PG8_WAIT_L(n) asm volatile("s_waitcnt lgkmcnt(" #n ")" ::: "memory")
; #define PG8_BAR __builtin_amdgcn_s_barrier()
; #define PG8_SCHED __builtin_amdgcn_sched_barrier(0)
; template <class Epi, class Sched, bool ALIGN_EPI = false, bool SP2 = false>
; __device__ __forceinline__ void gemm_phase(PG8_LAS unsigned char* lds, const Gemm g, const Sched& S, const Epi& E, const int wv0) {
;     ...
;             PG8_WAIT_V(8); PG8_WAIT_L(0); PG8_BAR; PG8_MMA(0, 0, At, B0); PG8_MMA(0, 1, At, B1); PG8_BAR; PG8_SCHED;
;             PG8_LDA(At, 1, 1); PG8_STAGE(PG8_SB(1, 0), b3, voffB); PG8_STAGE(PG8_SB(1, 1), b3 + hstepB, voffB); PG8_STAGE(PG8_SA(1, 0), a3, voffA);
;             PG8_WAIT_V(8); PG8_WAIT_L(0); PG8_BAR; PG8_MMA(1, 0, At, B0); PG8_MMA(1, 1, At, B1); PG8_BAR; PG8_SCHED;
	s_mov_b32 m0, s53
	v_lshl_add_u64 v[126:127], v[26:27], 0, s[12:13]
	s_add_u32 s24, s24, 0x10180
	ds_read_b128 v[206:209], v203 offset:49152
	ds_read_b128 v[210:213], v203 offset:50176
	ds_read_b128 v[214:217], v203 offset:51200
	ds_read_b128 v[218:221], v203 offset:52224
	ds_read_b128 v[222:225], v203 offset:53248
	ds_read_b128 v[226:229], v203 offset:54272
	ds_read_b128 v[230:233], v203 offset:55296
	ds_read_b128 v[234:237], v203 offset:56320
	global_load_lds_dwordx4 v[126:127], off
	v_lshl_add_u64 v[126:127], v[28:29], 0, s[12:13]
	s_mov_b32 m0, s55
	s_addc_u32 s25, s25, 0
	global_load_lds_dwordx4 v[126:127], off
	v_lshl_add_u64 v[126:127], s[24:25], 0, v[128:129]
	s_mov_b32 m0, s58
	v_lshl_add_u64 v[32:33], s[24:25], 0, v[32:33]
	global_load_lds_dwordx4 v[126:127], off
	s_mov_b32 m0, s60
	s_nop 0
	global_load_lds_dwordx4 v[32:33], off
	v_lshl_add_u64 v[32:33], v[20:21], 0, s[12:13]
	s_mov_b32 m0, s54
	s_nop 0
	global_load_lds_dwordx4 v[32:33], off
	v_lshl_add_u64 v[32:33], v[22:23], 0, s[12:13]
	s_mov_b32 m0, s56
	s_nop 0
	global_load_lds_dwordx4 v[32:33], off
	s_waitcnt vmcnt(8)
	s_waitcnt lgkmcnt(0)
	s_barrier
	v_mfma_f32_16x16x32_bf16 v[32:35], v[58:61], v[230:233], v[34:37]
	v_mfma_f32_16x16x32_bf16 v[36:39], v[154:157], v[230:233], v[38:41]
	v_mfma_f32_16x16x32_bf16 v[170:173], v[58:61], v[206:209], v[170:173]
	v_mfma_f32_16x16x32_bf16 v[174:177], v[154:157], v[206:209], v[174:177]
	v_mfma_f32_16x16x32_bf16 v[178:181], v[58:61], v[214:217], v[178:181]
	v_mfma_f32_16x16x32_bf16 v[182:185], v[154:157], v[214:217], v[182:185]
	v_mfma_f32_16x16x32_bf16 v[186:189], v[58:61], v[222:225], v[186:189]
	v_mfma_f32_16x16x32_bf16 v[190:193], v[154:157], v[222:225], v[190:193]
	v_mfma_f32_16x16x32_bf16 v[32:35], v[62:65], v[234:237], v[32:35]
	v_mfma_f32_16x16x32_bf16 v[36:39], v[158:161], v[234:237], v[36:39]
	v_mfma_f32_16x16x32_bf16 v[170:173], v[62:65], v[210:213], v[170:173]
	v_mfma_f32_16x16x32_bf16 v[174:177], v[158:161], v[210:213], v[174:177]
	v_mfma_f32_16x16x32_bf16 v[178:181], v[62:65], v[218:221], v[178:181]
	v_mfma_f32_16x16x32_bf16 v[182:185], v[158:161], v[218:221], v[182:185]
	v_mfma_f32_16x16x32_bf16 v[186:189], v[62:65], v[226:229], v[186:189]
	v_mfma_f32_16x16x32_bf16 v[190:193], v[158:161], v[226:229], v[190:193]
	v_mfma_f32_16x16x32_bf16 v[40:43], v[162:165], v[206:209], v[42:45]
	v_mfma_f32_16x16x32_bf16 v[44:47], v[194:197], v[206:209], v[46:49]
	v_mfma_f32_16x16x32_bf16 v[58:61], v[162:165], v[214:217], v[94:97]
	v_mfma_f32_16x16x32_bf16 v[62:65], v[194:197], v[214:217], v[138:141]
	v_mfma_f32_16x16x32_bf16 v[94:97], v[162:165], v[222:225], v[146:149]
	v_mfma_f32_16x16x32_bf16 v[48:51], v[162:165], v[230:233], v[50:53]
	v_mfma_f32_16x16x32_bf16 v[52:55], v[194:197], v[230:233], v[54:57]
	v_mfma_f32_16x16x32_bf16 v[40:43], v[166:169], v[210:213], v[40:43]
	v_mfma_f32_16x16x32_bf16 v[44:47], v[198:201], v[210:213], v[44:47]
	v_mfma_f32_16x16x32_bf16 v[58:61], v[166:169], v[218:221], v[58:61]
	v_mfma_f32_16x16x32_bf16 v[62:65], v[198:201], v[218:221], v[62:65]
	v_mfma_f32_16x16x32_bf16 v[94:97], v[166:169], v[226:229], v[94:97]
	v_mfma_f32_16x16x32_bf16 v[138:141], v[194:197], v[222:225], v[150:153]
	v_mfma_f32_16x16x32_bf16 v[48:51], v[166:169], v[234:237], v[48:51]
	v_mfma_f32_16x16x32_bf16 v[52:55], v[198:201], v[234:237], v[52:55]
	v_mfma_f32_16x16x32_bf16 v[138:141], v[198:201], v[226:229], v[138:141]
	s_barrier
	ds_read_b128 v[146:149], v202
	ds_read_b128 v[150:153], v202 offset:1024
	ds_read_b128 v[154:157], v202 offset:2048
	ds_read_b128 v[158:161], v202 offset:3072
	ds_read_b128 v[162:165], v145
	ds_read_b128 v[166:169], v145 offset:1024
	ds_read_b128 v[194:197], v145 offset:2048
	ds_read_b128 v[198:201], v145 offset:3072
	s_add_u32 s22, s22, 0x40180
	s_addc_u32 s23, s23, 0
	s_mov_b32 m0, s68
	v_lshl_add_u64 v[16:17], s[22:23], 0, v[16:17]
	ds_read_b128 v[206:209], v203
	ds_read_b128 v[210:213], v203 offset:1024
	ds_read_b128 v[214:217], v203 offset:2048
	ds_read_b128 v[218:221], v203 offset:3072
	ds_read_b128 v[222:225], v203 offset:4096
	ds_read_b128 v[226:229], v203 offset:5120
	ds_read_b128 v[230:233], v203 offset:6144
	ds_read_b128 v[234:237], v203 offset:7168
	global_load_lds_dwordx4 v[16:17], off
	v_lshl_add_u64 v[16:17], s[22:23], 0, v[30:31]
	s_mov_b32 m0, s63
	s_nop 0
	global_load_lds_dwordx4 v[16:17], off
	s_waitcnt vmcnt(8)
	s_waitcnt lgkmcnt(0)
	s_barrier
	v_mfma_f32_16x16x32_bf16 v[114:117], v[146:149], v[222:225], v[114:117]
	v_mfma_f32_16x16x32_bf16 v[238:241], v[150:153], v[226:229], v[114:117]
	v_mfma_f32_16x16x32_bf16 v[114:117], v[154:157], v[222:225], v[118:121]
	v_mfma_f32_16x16x32_bf16 v[98:101], v[146:149], v[206:209], v[98:101]
	v_mfma_f32_16x16x32_bf16 v[102:105], v[154:157], v[206:209], v[102:105]
	v_mfma_f32_16x16x32_bf16 v[106:109], v[146:149], v[214:217], v[106:109]
	v_mfma_f32_16x16x32_bf16 v[110:113], v[154:157], v[214:217], v[110:113]
	v_mfma_f32_16x16x32_bf16 v[242:245], v[158:161], v[226:229], v[114:117]
	v_mfma_f32_16x16x32_bf16 v[114:117], v[146:149], v[230:233], v[122:125]
	v_mfma_f32_16x16x32_bf16 v[98:101], v[150:153], v[210:213], v[98:101]
	v_mfma_f32_16x16x32_bf16 v[102:105], v[158:161], v[210:213], v[102:105]
	v_mfma_f32_16x16x32_bf16 v[106:109], v[150:153], v[218:221], v[106:109]
	v_mfma_f32_16x16x32_bf16 v[110:113], v[158:161], v[218:221], v[110:113]
	v_mfma_f32_16x16x32_bf16 v[124:127], v[150:153], v[234:237], v[114:117]
	v_mfma_f32_16x16x32_bf16 v[114:117], v[154:157], v[230:233], v[130:133]
	v_mfma_f32_16x16x32_bf16 v[130:133], v[158:161], v[234:237], v[114:117]
	v_mfma_f32_16x16x32_bf16 v[66:69], v[194:197], v[206:209], v[66:69]
	v_mfma_f32_16x16x32_bf16 v[114:117], v[162:165], v[206:209], v[134:137]
	v_mfma_f32_16x16x32_bf16 v[206:209], v[198:201], v[210:213], v[66:69]
	v_mfma_f32_16x16x32_bf16 v[66:69], v[162:165], v[214:217], v[70:73]
	v_mfma_f32_16x16x32_bf16 v[134:137], v[166:169], v[210:213], v[114:117]
	v_mfma_f32_16x16x32_bf16 v[210:213], v[166:169], v[218:221], v[66:69]
	v_mfma_f32_16x16x32_bf16 v[66:69], v[194:197], v[214:217], v[74:77]
	v_mfma_f32_16x16x32_bf16 v[214:217], v[198:201], v[218:221], v[66:69]
	v_mfma_f32_16x16x32_bf16 v[66:69], v[162:165], v[222:225], v[78:81]
	v_mfma_f32_16x16x32_bf16 v[76:79], v[166:169], v[226:229], v[66:69]
	v_mfma_f32_16x16x32_bf16 v[66:69], v[194:197], v[222:225], v[82:85]
	v_mfma_f32_16x16x32_bf16 v[80:83], v[198:201], v[226:229], v[66:69]
	v_mfma_f32_16x16x32_bf16 v[66:69], v[162:165], v[230:233], v[86:89]
	v_mfma_f32_16x16x32_bf16 v[218:221], v[166:169], v[234:237], v[66:69]
	v_mfma_f32_16x16x32_bf16 v[66:69], v[194:197], v[230:233], v[90:93]
	v_mfma_f32_16x16x32_bf16 v[222:225], v[198:201], v[234:237], v[66:69]
	s_barrier
; #define PG8_STAGE(bufoff, gbase, voff) do { _Pragma("unroll") for (int _i = 0; _i < 2; ++_i) \
;         __builtin_amdgcn_global_load_lds((const unsigned*)((const char*)(gbase) + (voff)[_i]), (PG8_LAS unsigned*)(lds + (bufoff) + ldsw + _i * 8192), 16, 0, 0); } while (0)
; #define PG8_LDA(dst, b, h) do { _Pragma("unroll") for (int m = 0; m < 4; ++m) _Pragma("unroll") for (int k = 0; k < 2; ++k) dst[m][k] = *(const PG8_LAS bf16x8*)(lds + PG8_SA(b, h) + aoff + m * 2048 + k * 1024); } while (0)
; #define PG8_LDB(dst, b, h) do { _Pragma("unroll") for (int n = 0; n < 2; ++n) _Pragma("unroll") for (int k = 0; k < 2; ++k) dst[n][k] = *(const PG8_LAS bf16x8*)(lds + PG8_SB(b, h) + boff + n * 2048 + k * 1024); } while (0)
; #define PG8_MMA(ai, bj, At, Bt) do { __builtin_amdgcn_s_setprio(1); _Pragma("unroll") for (int m = 0; m < 4; ++m) _Pragma("unroll") for (int n = 0; n < 2; ++n) _Pragma("unroll") for (int k = 0; k < 2; ++k) \
;         acc[ai][bj][m][n] = __builtin_amdgcn_mfma_f32_16x16x32_bf16(Bt[n][k], At[m][k], acc[ai][bj][m][n], 0, 0, 0); __builtin_amdgcn_s_setprio(0); } while (0)
; #define PG8_WAIT_V(n) asm volatile("s_waitcnt vmcnt(" #n ")" ::: "memory")
; #define PG8_WAIT_L(n) asm volatile("s_waitcnt lgkmcnt(" #n ")" ::: "memory")
; #define PG8_BAR __builtin_amdgcn_s_barrier()
; #define PG8_SCHED __builtin_amdgcn_sched_barrier(0)
; template <class Epi, class Sched, bool ALIGN_EPI = false, bool SP2 = false>
; __device__ __forceinline__ void gemm_phase(PG8_LAS unsigned char* lds, const Gemm g, const Sched& S, const Epi& E, const int wv0) {
;     ...
;             PG8_LDA(At, 0, 1); PG8_STAGE(PG8_SB(0, 0), b2, voffB); PG8_STAGE(PG8_SB(0, 1), b2 + hstepB, voffB); PG8_STAGE(PG8_SA(0, 0), a2, voffA);
;             PG8_WAIT_V(8); PG8_WAIT_L(0); PG8_BAR; PG8_MMA(1, 0, At, B0); PG8_MMA(1, 1, At, B1); PG8_BAR; PG8_SCHED;
;             PG8_LDB(B0, 1, 0); PG8_LDB(B1, 1, 1); PG8_SCHED; PG8_LDA(At, 1, 0); PG8_STAGE(PG8_SA(0, 1), a2 + hstepA, voffA);
;             PG8_WAIT_V(8); PG8_WAIT_L(0); PG8_BAR; PG8_MMA(0, 0, At, B0); PG8_MMA(0, 1, At, B1); PG8_BAR; PG8_SCHED;
	s_mov_b32 m0, s64
	s_nop 3
	ds_read_b128 v[66:69], v203 offset:16384
	ds_read_b128 v[70:73], v203 offset:17408
	ds_read_b128 v[84:87], v203 offset:18432
	ds_read_b128 v[88:91], v203 offset:19456
	ds_read_b128 v[114:117], v203 offset:20480
	ds_read_b128 v[118:121], v203 offset:21504
	ds_read_b128 v[226:229], v203 offset:22528
	ds_read_b128 v[230:233], v203 offset:23552
	global_load_lds_dwordx4 v[26:27], off
	s_mov_b32 m0, s65
	s_nop 0
	global_load_lds_dwordx4 v[28:29], off
	s_mov_b32 m0, s66
	s_nop 0
	global_load_lds_dwordx4 v[24:25], off
	s_mov_b32 m0, s67
	s_nop 0
	global_load_lds_dwordx4 v[18:19], off
	s_mov_b32 m0, s61
	s_nop 0
	global_load_lds_dwordx4 v[20:21], off
	s_mov_b32 m0, s62
	s_nop 0
	global_load_lds_dwordx4 v[22:23], off
	s_waitcnt vmcnt(8)
	s_waitcnt lgkmcnt(0)
	s_barrier
	v_mfma_f32_16x16x32_bf16 v[16:19], v[146:149], v[66:69], v[170:173]
	v_mfma_f32_16x16x32_bf16 v[20:23], v[154:157], v[66:69], v[174:177]
	v_mfma_f32_16x16x32_bf16 v[24:27], v[146:149], v[84:87], v[178:181]
	v_mfma_f32_16x16x32_bf16 v[28:31], v[154:157], v[84:87], v[182:185]
	v_mfma_f32_16x16x32_bf16 v[32:35], v[146:149], v[226:229], v[32:35]
	v_mfma_f32_16x16x32_bf16 v[16:19], v[150:153], v[70:73], v[16:19]
	v_mfma_f32_16x16x32_bf16 v[20:23], v[158:161], v[70:73], v[20:23]
	v_mfma_f32_16x16x32_bf16 v[24:27], v[150:153], v[88:91], v[24:27]
	v_mfma_f32_16x16x32_bf16 v[28:31], v[158:161], v[88:91], v[28:31]
	v_mfma_f32_16x16x32_bf16 v[170:173], v[146:149], v[114:117], v[186:189]
	v_mfma_f32_16x16x32_bf16 v[174:177], v[154:157], v[114:117], v[190:193]
	v_mfma_f32_16x16x32_bf16 v[32:35], v[150:153], v[230:233], v[32:35]
	v_mfma_f32_16x16x32_bf16 v[36:39], v[154:157], v[226:229], v[36:39]
	v_mfma_f32_16x16x32_bf16 v[170:173], v[150:153], v[118:121], v[170:173]
	v_mfma_f32_16x16x32_bf16 v[174:177], v[158:161], v[118:121], v[174:177]
	v_mfma_f32_16x16x32_bf16 v[146:149], v[158:161], v[230:233], v[36:39]
	v_mfma_f32_16x16x32_bf16 v[36:39], v[162:165], v[66:69], v[40:43]
	v_mfma_f32_16x16x32_bf16 v[150:153], v[166:169], v[70:73], v[36:39]
	v_mfma_f32_16x16x32_bf16 v[36:39], v[194:197], v[66:69], v[44:47]
	v_mfma_f32_16x16x32_bf16 v[44:47], v[198:201], v[70:73], v[36:39]
	v_mfma_f32_16x16x32_bf16 v[36:39], v[162:165], v[84:87], v[58:61]
	v_mfma_f32_16x16x32_bf16 v[154:157], v[166:169], v[88:91], v[36:39]
	v_mfma_f32_16x16x32_bf16 v[36:39], v[194:197], v[84:87], v[62:65]
	v_mfma_f32_16x16x32_bf16 v[158:161], v[198:201], v[88:91], v[36:39]
	v_mfma_f32_16x16x32_bf16 v[36:39], v[162:165], v[114:117], v[94:97]
	v_mfma_f32_16x16x32_bf16 v[178:181], v[166:169], v[118:121], v[36:39]
	v_mfma_f32_16x16x32_bf16 v[36:39], v[194:197], v[114:117], v[138:141]
	v_mfma_f32_16x16x32_bf16 v[138:141], v[198:201], v[118:121], v[36:39]
	v_mfma_f32_16x16x32_bf16 v[36:39], v[162:165], v[226:229], v[48:51]
	v_mfma_f32_16x16x32_bf16 v[162:165], v[166:169], v[230:233], v[36:39]
	v_mfma_f32_16x16x32_bf16 v[36:39], v[194:197], v[226:229], v[52:55]
	v_mfma_f32_16x16x32_bf16 v[166:169], v[198:201], v[230:233], v[36:39]
	s_barrier
	ds_read_b128 v[48:51], v247
	ds_read_b128 v[64:67], v247 offset:1024
	ds_read_b128 v[182:185], v247 offset:2048
	ds_read_b128 v[186:189], v247 offset:3072
	ds_read_b128 v[190:193], v246
	ds_read_b128 v[194:197], v246 offset:1024
	ds_read_b128 v[198:201], v246 offset:2048
	ds_read_b128 v[226:229], v246 offset:3072
	s_mov_b32 m0, s57
	ds_read_b128 v[36:39], v203 offset:32768
	ds_read_b128 v[40:43], v203 offset:33792
	ds_read_b128 v[52:55], v203 offset:34816
	ds_read_b128 v[56:59], v203 offset:35840
	ds_read_b128 v[60:63], v203 offset:36864
	ds_read_b128 v[230:233], v203 offset:37888
	ds_read_b128 v[234:237], v203 offset:38912
	ds_read_b128 v[246:249], v203 offset:39936
	global_load_lds_dwordx4 v[12:13], off
	s_mov_b32 m0, s59
	s_nop 0
	global_load_lds_dwordx4 v[14:15], off
	s_waitcnt vmcnt(8)
	s_waitcnt lgkmcnt(0)
	s_barrier
; #define PG8_STAGE(bufoff, gbase, voff) do { _Pragma("unroll") for (int _i = 0; _i < 2; ++_i) \
;         __builtin_amdgcn_global_load_lds((const unsigned*)((const char*)(gbase) + (voff)[_i]), (PG8_LAS unsigned*)(lds + (bufoff) + ldsw + _i * 8192), 16, 0, 0); } while (0)
; #define PG8_LDA(dst, b, h) do { _Pragma("unroll") for (int m = 0; m < 4; ++m) _Pragma("unroll") for (int k = 0; k < 2; ++k) dst[m][k] = *(const PG8_LAS bf16x8*)(lds + PG8_SA(b, h) + aoff + m * 2048 + k * 1024); } while (0)
; #define PG8_LDB(dst, b, h) do { _Pragma("unroll") for (int n = 0; n < 2; ++n) _Pragma("unroll") for (int k = 0; k < 2; ++k) dst[n][k] = *(const PG8_LAS bf16x8*)(lds + PG8_SB(b, h) + boff + n * 2048 + k * 1024); } while (0)
; #define PG8_MMA(ai, bj, At, Bt) do { __builtin_amdgcn_s_setprio(1); _Pragma("unroll") for (int m = 0; m < 4; ++m) _Pragma("unroll") for (int n = 0; n < 2; ++n) _Pragma("unroll") for (int k = 0; k < 2; ++k) \
;         acc[ai][bj][m][n] = __builtin_amdgcn_mfma_f32_16x16x32_bf16(Bt[n][k], At[m][k], acc[ai][bj][m][n], 0, 0, 0); __builtin_amdgcn_s_setprio(0); } while (0)
; #define PG8_WAIT_V(n) asm volatile("s_waitcnt vmcnt(" #n ")" ::: "memory")
; #define PG8_WAIT_L(n) asm volatile("s_waitcnt lgkmcnt(" #n ")" ::: "memory")
; #define PG8_BAR __builtin_amdgcn_s_barrier()
; #define PG8_SCHED __builtin_amdgcn_sched_barrier(0)
; template <class Epi, class Sched, bool ALIGN_EPI = false, bool SP2 = false>
; __device__ __forceinline__ void gemm_phase(PG8_LAS unsigned char* lds, const Gemm g, const Sched& S, const Epi& E, const int wv0) {
;     ...
;             PG8_LDB(B0, 1, 0); PG8_LDB(B1, 1, 1); PG8_SCHED; PG8_LDA(At, 1, 0); PG8_STAGE(PG8_SA(0, 1), a2 + hstepA, voffA);
;             PG8_WAIT_V(8); PG8_WAIT_L(0); PG8_BAR; PG8_MMA(0, 0, At, B0); PG8_MMA(0, 1, At, B1); PG8_BAR; PG8_SCHED;
;             PG8_LDA(At, 1, 1); PG8_STAGE(PG8_SB(1, 0), b3, voffB); PG8_STAGE(PG8_SB(1, 1), b3 + hstepB, voffB); PG8_STAGE(PG8_SA(1, 0), a3, voffA);
;             PG8_WAIT_V(8); PG8_WAIT_L(0); PG8_BAR; PG8_MMA(1, 0, At, B0); PG8_MMA(1, 1, At, B1); PG8_BAR; PG8_SCHED;
;     ...
;     PG8_WAIT_V(0);
;     if constexpr (!ALIGN_EPI) { if (wr == 0) PG8_BAR; }
	v_mfma_f32_16x16x32_bf16 v[12:15], v[48:51], v[36:39], v[98:101]
	v_mfma_f32_16x16x32_bf16 v[120:123], v[64:67], v[40:43], v[12:15]
	v_mfma_f32_16x16x32_bf16 v[12:15], v[182:185], v[36:39], v[102:105]
	v_mfma_f32_16x16x32_bf16 v[116:119], v[186:189], v[40:43], v[12:15]
	v_mfma_f32_16x16x32_bf16 v[12:15], v[48:51], v[52:55], v[106:109]
	v_mfma_f32_16x16x32_bf16 v[104:107], v[64:67], v[56:59], v[12:15]
	v_mfma_f32_16x16x32_bf16 v[12:15], v[182:185], v[52:55], v[110:113]
	v_mfma_f32_16x16x32_bf16 v[100:103], v[186:189], v[56:59], v[12:15]
	v_mfma_f32_16x16x32_bf16 v[12:15], v[48:51], v[60:63], v[238:241]
	v_mfma_f32_16x16x32_bf16 v[88:91], v[64:67], v[230:233], v[12:15]
	v_mfma_f32_16x16x32_bf16 v[12:15], v[182:185], v[60:63], v[242:245]
	v_mfma_f32_16x16x32_bf16 v[84:87], v[186:189], v[230:233], v[12:15]
	v_mfma_f32_16x16x32_bf16 v[12:15], v[48:51], v[234:237], v[124:127]
	v_mfma_f32_16x16x32_bf16 v[72:75], v[64:67], v[246:249], v[12:15]
	v_mfma_f32_16x16x32_bf16 v[12:15], v[182:185], v[234:237], v[130:133]
	v_mfma_f32_16x16x32_bf16 v[68:71], v[186:189], v[246:249], v[12:15]
	v_mfma_f32_16x16x32_bf16 v[12:15], v[190:193], v[36:39], v[134:137]
	v_mfma_f32_16x16x32_bf16 v[124:127], v[194:197], v[40:43], v[12:15]
	v_mfma_f32_16x16x32_bf16 v[12:15], v[198:201], v[36:39], v[206:209]
	v_mfma_f32_16x16x32_bf16 v[112:115], v[226:229], v[40:43], v[12:15]
	v_mfma_f32_16x16x32_bf16 v[12:15], v[190:193], v[52:55], v[210:213]
	v_mfma_f32_16x16x32_bf16 v[108:111], v[194:197], v[56:59], v[12:15]
	v_mfma_f32_16x16x32_bf16 v[12:15], v[198:201], v[52:55], v[214:217]
	v_mfma_f32_16x16x32_bf16 v[96:99], v[226:229], v[56:59], v[12:15]
	v_mfma_f32_16x16x32_bf16 v[12:15], v[190:193], v[60:63], v[76:79]
	v_mfma_f32_16x16x32_bf16 v[92:95], v[194:197], v[230:233], v[12:15]
	v_mfma_f32_16x16x32_bf16 v[12:15], v[198:201], v[60:63], v[80:83]
	v_mfma_f32_16x16x32_bf16 v[80:83], v[226:229], v[230:233], v[12:15]
	v_mfma_f32_16x16x32_bf16 v[12:15], v[190:193], v[234:237], v[218:221]
	v_mfma_f32_16x16x32_bf16 v[76:79], v[194:197], v[246:249], v[12:15]
	v_mfma_f32_16x16x32_bf16 v[12:15], v[198:201], v[234:237], v[222:225]
	v_mfma_f32_16x16x32_bf16 v[56:59], v[226:229], v[246:249], v[12:15]
	s_barrier
	s_mov_b32 m0, s53
	s_nop 3
	ds_read_b128 v[12:15], v203 offset:49152
	ds_read_b128 v[130:133], v203 offset:50176
	ds_read_b128 v[134:137], v203 offset:51200
	ds_read_b128 v[206:209], v203 offset:52224
	ds_read_b128 v[210:213], v203 offset:53248
	ds_read_b128 v[214:217], v203 offset:54272
	ds_read_b128 v[218:221], v203 offset:55296
	ds_read_b128 v[222:225], v203 offset:56320
	global_load_lds_dwordx4 v[2:3], off
	s_mov_b32 m0, s55
	s_nop 0
	global_load_lds_dwordx4 v[4:5], off
	s_mov_b32 m0, s58
	s_nop 0
	global_load_lds_dwordx4 v[8:9], off
	s_mov_b32 m0, s60
	s_nop 0
	global_load_lds_dwordx4 v[10:11], off
	s_mov_b32 m0, s54
	s_nop 0
	global_load_lds_dwordx4 v[0:1], off
	s_mov_b32 m0, s56
	s_nop 0
	global_load_lds_dwordx4 v[6:7], off
	s_waitcnt vmcnt(8)
	s_waitcnt lgkmcnt(0)
	s_barrier
	v_mfma_f32_16x16x32_bf16 v[0:3], v[48:51], v[12:15], v[16:19]
	v_mfma_f32_16x16x32_bf16 v[60:63], v[64:67], v[130:133], v[0:3]
	v_mfma_f32_16x16x32_bf16 v[0:3], v[182:185], v[12:15], v[20:23]
	v_mfma_f32_16x16x32_bf16 v[52:55], v[186:189], v[130:133], v[0:3]
	v_mfma_f32_16x16x32_bf16 v[0:3], v[48:51], v[134:137], v[24:27]
	v_mfma_f32_16x16x32_bf16 v[40:43], v[64:67], v[206:209], v[0:3]
	v_mfma_f32_16x16x32_bf16 v[0:3], v[182:185], v[134:137], v[28:31]
	v_mfma_f32_16x16x32_bf16 v[36:39], v[186:189], v[206:209], v[0:3]
	v_mfma_f32_16x16x32_bf16 v[0:3], v[48:51], v[210:213], v[170:173]
	v_mfma_f32_16x16x32_bf16 v[24:27], v[64:67], v[214:217], v[0:3]
	v_mfma_f32_16x16x32_bf16 v[0:3], v[182:185], v[210:213], v[174:177]
	v_mfma_f32_16x16x32_bf16 v[20:23], v[186:189], v[214:217], v[0:3]
	v_mfma_f32_16x16x32_bf16 v[0:3], v[48:51], v[218:221], v[32:35]
	v_mfma_f32_16x16x32_bf16 v[8:11], v[64:67], v[222:225], v[0:3]
	v_mfma_f32_16x16x32_bf16 v[0:3], v[182:185], v[218:221], v[146:149]
	v_mfma_f32_16x16x32_bf16 v[4:7], v[186:189], v[222:225], v[0:3]
	v_mfma_f32_16x16x32_bf16 v[0:3], v[190:193], v[12:15], v[150:153]
	v_mfma_f32_16x16x32_bf16 v[64:67], v[194:197], v[130:133], v[0:3]
	v_mfma_f32_16x16x32_bf16 v[0:3], v[198:201], v[12:15], v[44:47]
	v_mfma_f32_16x16x32_bf16 v[48:51], v[226:229], v[130:133], v[0:3]
	v_mfma_f32_16x16x32_bf16 v[0:3], v[190:193], v[134:137], v[154:157]
	v_mfma_f32_16x16x32_bf16 v[44:47], v[194:197], v[206:209], v[0:3]
	v_mfma_f32_16x16x32_bf16 v[0:3], v[198:201], v[134:137], v[158:161]
	v_mfma_f32_16x16x32_bf16 v[32:35], v[226:229], v[206:209], v[0:3]
	v_mfma_f32_16x16x32_bf16 v[0:3], v[190:193], v[210:213], v[178:181]
	v_mfma_f32_16x16x32_bf16 v[28:31], v[194:197], v[214:217], v[0:3]
	v_mfma_f32_16x16x32_bf16 v[0:3], v[198:201], v[210:213], v[138:141]
	v_mfma_f32_16x16x32_bf16 v[16:19], v[226:229], v[214:217], v[0:3]
	v_mfma_f32_16x16x32_bf16 v[0:3], v[190:193], v[218:221], v[162:165]
	v_mfma_f32_16x16x32_bf16 v[12:15], v[194:197], v[222:225], v[0:3]
	v_mfma_f32_16x16x32_bf16 v[0:3], v[198:201], v[218:221], v[166:169]
	v_mfma_f32_16x16x32_bf16 v[0:3], v[226:229], v[222:225], v[0:3]
	s_barrier
	s_waitcnt vmcnt(0)
	s_cmpk_gt_u32 s52, 0xff
	s_cbranch_scc1 .LBB0_360
	s_barrier

;     __device__ __forceinline__ bool next(int i, Unit& u) const { int pm, pn; if (!to.get((long)i * G + c, pm, pn)) return false; u.pm = pm; u.pn = pn; u.aux = 0; u.a = A + (size_t)pm * ta; u.b = B + (size_t)pn * tb; return true; }
; template <class Epi, class Sched, bool ALIGN_EPI = false, bool SP2 = false>
; __device__ __forceinline__ void gemm_phase(PG8_LAS unsigned char* lds, const Gemm g, const Sched& S, const Epi& E, const int wv0) {
;     ...
;         PG8_STAGE(PG8_SB(0, 0), cB, voffB); PG8_STAGE(PG8_SB(0, 1), cB + hstepB, voffB); PG8_STAGE(PG8_SA(0, 0), cA, voffA); PG8_STAGE(PG8_SA(0, 1), cA + hstepA, voffA);
;         if (wr == 1) PG8_BAR;
;         PG8_WAIT_V(2); PG8_BAR;
;         PG8_STAGE(PG8_SB(1, 0), cB + kstep, voffB); PG8_STAGE(PG8_SA(1, 0), cA + kstep, voffA); PG8_STAGE(PG8_SB(1, 1), cB + hstepB + kstep, voffB);
;         PG8_WAIT_V(6); PG8_BAR;
;     } else {
;         PG8_STAGE(PG8_SB(0, 0), cB, voffB); PG8_STAGE(PG8_SA(0, 0), cA, voffA); PG8_STAGE(PG8_SB(0, 1), cB + hstepB, voffB); PG8_STAGE(PG8_SA(0, 1), cA + hstepA, voffA);
;         if (wr == 1) PG8_BAR;
;         PG8_WAIT_V(4); PG8_BAR;
;         PG8_STAGE(PG8_SB(1, 0), cB + kstep, voffB); PG8_STAGE(PG8_SA(1, 0), cA + kstep, voffA); PG8_STAGE(PG8_SB(1, 1), cB + hstepB + kstep, voffB);
;         PG8_WAIT_V(6); PG8_BAR;
;     }
;     for (;;) {
;         const bool has_next = S.next(ui + 1, nxt);
;         const char* nA = has_next ? nxt.a : cA; const char* nB = has_next ? nxt.b : cB;
;         for (int t = 0; t < nt; t += 2) {
;             const bool last = (t == nt - 2);
;             const char* a1 = cA + (size_t)(t + 1) * kstep;
;             const char* a2 = last ? nA : cA + (size_t)(t + 2) * kstep; const char* b2 = last ? nB : cB + (size_t)(t + 2) * kstep;
;             const char* a3 = a2 + kstep; const char* b3 = b2 + kstep;
;             if constexpr (SP2) {
;             PG8_LDB(B0, 0, 0); PG8_LDB(B1, 0, 1); PG8_SCHED; PG8_LDA(At, 0, 0); PG8_STAGE(PG8_SA(1, 1), a1 + hstepA, voffA);
;             PG8_WAIT_V(8); PG8_WAIT_L(0); PG8_BAR; PG8_MMA(0, 0, At, B0); PG8_MMA(0, 1, At, B1); PG8_BAR; PG8_SCHED;
;             PG8_LDA(At, 0, 1); PG8_STAGE(PG8_SB(0, 0), b2, voffB); PG8_STAGE(PG8_SB(0, 1), b2 + hstepB, voffB); PG8_STAGE(PG8_SA(0, 0), a2, voffA);
;             PG8_WAIT_V(8); PG8_WAIT_L(0); PG8_BAR; PG8_MMA(1, 0, At, B0); PG8_MMA(1, 1, At, B1); PG8_BAR; PG8_SCHED;
.LBB0_378:
	s_lshl_b32 s50, s50, 5
	s_add_i32 s51, s36, s63
	s_and_b32 s50, s50, 0x60
	v_lshl_add_u64 v[2:3], v[26:27], 0, s[8:9]
	s_mov_b32 m0, s51
	s_add_i32 s53, s51, 0x2000
	s_lshl_b32 s62, s61, 13
	s_lshl_b32 s66, s50, 7
	s_waitcnt vmcnt(2)
	s_barrier
	global_load_lds_dwordx4 v[2:3], off
	v_lshl_add_u64 v[4:5], v[28:29], 0, s[8:9]
	s_mov_b32 m0, s53
	s_add_i32 s52, s59, 0x8000
	s_add_i32 s54, s59, 0xa000
	global_load_lds_dwordx4 v[4:5], off
	v_lshl_add_u64 v[0:1], v[20:21], 0, s[8:9]
	s_mov_b32 m0, s52
	s_add_u32 s64, s22, 0x10080
	global_load_lds_dwordx4 v[0:1], off
	v_lshl_add_u64 v[6:7], v[22:23], 0, s[8:9]
	s_mov_b32 m0, s54
	s_addc_u32 s65, s23, 0
	s_add_i32 s57, s37, s63
	global_load_lds_dwordx4 v[6:7], off
	v_lshl_add_u64 v[8:9], s[64:65], 0, v[128:129]
	s_mov_b32 m0, s57
	s_add_i32 s58, s57, 0x2000
	global_load_lds_dwordx4 v[8:9], off
	v_lshl_add_u64 v[10:11], s[64:65], 0, v[32:33]
	s_mov_b32 m0, s58
	v_lshrrev_b32_e32 v37, 1, v34
	global_load_lds_dwordx4 v[10:11], off
	v_and_b32_e32 v37, 24, v37
	v_and_b32_e32 v35, 15, v34
	v_lshlrev_b32_e32 v38, 1, v37
	v_lshlrev_b32_e32 v34, 2, v34
	v_lshl_or_b32 v36, s61, 6, v35
	v_lshl_or_b32 v35, v35, 6, v38
	v_and_b32_e32 v34, 32, v34
	v_bitop3_b32 v70, v35, s66, v34 bitop3:0xde
	v_add_u32_e32 v127, s48, v70
	s_waitcnt vmcnt(6)
	s_barrier
	v_add_u32_e32 v126, s47, v70
	ds_read_b128 v[38:41], v127
	ds_read_b128 v[42:45], v127 offset:1024
	ds_read_b128 v[46:49], v127 offset:2048
	ds_read_b128 v[50:53], v127 offset:3072
	ds_read_b128 v[54:57], v126
	ds_read_b128 v[58:61], v126 offset:1024
	ds_read_b128 v[62:65], v126 offset:2048
	ds_read_b128 v[66:69], v126 offset:3072
	v_bitop3_b32 v34, v35, s62, v34 bitop3:0xde
	v_add_u32_e32 v143, 0, v34
	v_add_u32_e32 v238, s37, v70
	v_add_u32_e32 v239, s36, v70
	s_add_u32 s66, s20, 0x40080
	s_addc_u32 s67, s21, 0
	s_add_i32 s64, s59, 0xc000
	v_lshl_add_u64 v[34:35], s[66:67], 0, v[16:17]
	s_mov_b32 m0, s64
	s_add_i32 s61, s59, 0xe000
	ds_read_b128 v[70:73], v143
	ds_read_b128 v[74:77], v143 offset:1024
	ds_read_b128 v[78:81], v143 offset:2048
	ds_read_b128 v[82:85], v143 offset:3072
	ds_read_b128 v[86:89], v143 offset:4096
	ds_read_b128 v[90:93], v143 offset:5120
	ds_read_b128 v[94:97], v143 offset:6144
	ds_read_b128 v[98:101], v143 offset:7168
	global_load_lds_dwordx4 v[34:35], off
	v_lshl_add_u64 v[34:35], s[66:67], 0, v[30:31]
	s_mov_b32 m0, s61
	s_nop 0
	global_load_lds_dwordx4 v[34:35], off
	s_waitcnt vmcnt(8)
	s_waitcnt lgkmcnt(0)
	s_barrier
	v_mfma_f32_16x16x32_bf16 v[102:105], v[38:41], v[70:73], 0
	v_mfma_f32_16x16x32_bf16 v[106:109], v[46:49], v[70:73], 0
	v_mfma_f32_16x16x32_bf16 v[110:113], v[38:41], v[78:81], 0
	v_mfma_f32_16x16x32_bf16 v[114:117], v[46:49], v[78:81], 0
	v_mfma_f32_16x16x32_bf16 v[118:121], v[38:41], v[86:89], 0
	v_mfma_f32_16x16x32_bf16 v[122:125], v[46:49], v[86:89], 0
	v_mfma_f32_16x16x32_bf16 v[130:133], v[38:41], v[94:97], 0
	v_mfma_f32_16x16x32_bf16 v[134:137], v[46:49], v[94:97], 0
	v_mfma_f32_16x16x32_bf16 v[102:105], v[42:45], v[74:77], v[102:105]
	v_mfma_f32_16x16x32_bf16 v[106:109], v[50:53], v[74:77], v[106:109]
	v_mfma_f32_16x16x32_bf16 v[110:113], v[42:45], v[82:85], v[110:113]
	v_mfma_f32_16x16x32_bf16 v[114:117], v[50:53], v[82:85], v[114:117]
	v_mfma_f32_16x16x32_bf16 v[118:121], v[42:45], v[90:93], v[118:121]
	v_mfma_f32_16x16x32_bf16 v[122:125], v[50:53], v[90:93], v[122:125]
	v_mfma_f32_16x16x32_bf16 v[130:133], v[42:45], v[98:101], v[130:133]
	v_mfma_f32_16x16x32_bf16 v[134:137], v[50:53], v[98:101], v[134:137]
	v_mfma_f32_16x16x32_bf16 v[138:141], v[54:57], v[70:73], 0
	v_mfma_f32_16x16x32_bf16 v[70:73], v[62:65], v[70:73], 0
	v_mfma_f32_16x16x32_bf16 v[138:141], v[58:61], v[74:77], v[138:141]
	v_mfma_f32_16x16x32_bf16 v[70:73], v[66:69], v[74:77], v[70:73]
	v_mfma_f32_16x16x32_bf16 v[74:77], v[54:57], v[78:81], 0
	v_mfma_f32_16x16x32_bf16 v[78:81], v[62:65], v[78:81], 0
	v_mfma_f32_16x16x32_bf16 v[74:77], v[58:61], v[82:85], v[74:77]
	v_mfma_f32_16x16x32_bf16 v[78:81], v[66:69], v[82:85], v[78:81]
	v_mfma_f32_16x16x32_bf16 v[82:85], v[54:57], v[86:89], 0
	v_mfma_f32_16x16x32_bf16 v[86:89], v[62:65], v[86:89], 0
	v_mfma_f32_16x16x32_bf16 v[82:85], v[58:61], v[90:93], v[82:85]
	v_mfma_f32_16x16x32_bf16 v[86:89], v[66:69], v[90:93], v[86:89]
	v_mfma_f32_16x16x32_bf16 v[90:93], v[54:57], v[94:97], 0
	v_mfma_f32_16x16x32_bf16 v[94:97], v[62:65], v[94:97], 0
	v_mfma_f32_16x16x32_bf16 v[90:93], v[58:61], v[98:101], v[90:93]
	v_mfma_f32_16x16x32_bf16 v[94:97], v[66:69], v[98:101], v[94:97]
	s_barrier
	s_add_i32 s48, s48, s63
	s_add_i32 s62, s48, 0x2000
	v_lshl_add_u64 v[34:35], v[26:27], 0, s[10:11]
	s_mov_b32 m0, s48
	s_add_u32 s66, s22, 0x10100
	ds_read_b128 v[98:101], v143 offset:16384
	ds_read_b128 v[144:147], v143 offset:17408
	ds_read_b128 v[148:151], v143 offset:18432
	ds_read_b128 v[152:155], v143 offset:19456
	ds_read_b128 v[156:159], v143 offset:20480
	ds_read_b128 v[160:163], v143 offset:21504
	ds_read_b128 v[164:167], v143 offset:22528
	ds_read_b128 v[168:171], v143 offset:23552
	global_load_lds_dwordx4 v[34:35], off
	v_lshl_add_u64 v[34:35], v[28:29], 0, s[10:11]
	s_mov_b32 m0, s62
	s_addc_u32 s67, s23, 0
	s_add_i32 s47, s47, s63
	global_load_lds_dwordx4 v[34:35], off
	v_lshl_add_u64 v[34:35], s[66:67], 0, v[128:129]
	s_mov_b32 m0, s47
	s_add_i32 s63, s47, 0x2000
	global_load_lds_dwordx4 v[34:35], off
	v_lshl_add_u64 v[34:35], s[66:67], 0, v[32:33]
	s_mov_b32 m0, s63
	s_nop 0
	global_load_lds_dwordx4 v[34:35], off
	v_lshl_add_u64 v[34:35], v[20:21], 0, s[10:11]
	s_mov_b32 m0, s59
	s_nop 0
	global_load_lds_dwordx4 v[34:35], off
	v_lshl_add_u64 v[34:35], v[22:23], 0, s[10:11]
	s_mov_b32 m0, s60
	s_nop 0
	global_load_lds_dwordx4 v[34:35], off
	s_waitcnt vmcnt(8)
	s_waitcnt lgkmcnt(0)
	s_barrier
; #define PG8_STAGE(bufoff, gbase, voff) do { _Pragma("unroll") for (int _i = 0; _i < 2; ++_i) \
;         __builtin_amdgcn_global_load_lds((const unsigned*)((const char*)(gbase) + (voff)[_i]), (PG8_LAS unsigned*)(lds + (bufoff) + ldsw + _i * 8192), 16, 0, 0); } while (0)
; #define PG8_LDA(dst, b, h) do { _Pragma("unroll") for (int m = 0; m < 4; ++m) _Pragma("unroll") for (int k = 0; k < 2; ++k) dst[m][k] = *(const PG8_LAS bf16x8*)(lds + PG8_SA(b, h) + aoff + m * 2048 + k * 1024); } while (0)
; #define PG8_LDB(dst, b, h) do { _Pragma("unroll") for (int n = 0; n < 2; ++n) _Pragma("unroll") for (int k = 0; k < 2; ++k) dst[n][k] = *(const PG8_LAS bf16x8*)(lds + PG8_SB(b, h) + boff + n * 2048 + k * 1024); } while (0)
; #define PG8_MMA(ai, bj, At, Bt) do { __builtin_amdgcn_s_setprio(1); _Pragma("unroll") for (int m = 0; m < 4; ++m) _Pragma("unroll") for (int n = 0; n < 2; ++n) _Pragma("unroll") for (int k = 0; k < 2; ++k) \
;         acc[ai][bj][m][n] = __builtin_amdgcn_mfma_f32_16x16x32_bf16(Bt[n][k], At[m][k], acc[ai][bj][m][n], 0, 0, 0); __builtin_amdgcn_s_setprio(0); } while (0)
; #define PG8_WAIT_V(n) asm volatile("s_waitcnt vmcnt(" #n ")" ::: "memory")
; #define PG8_WAIT_L(n) asm volatile("s_waitcnt lgkmcnt(" #n ")" ::: "memory")
; #define PG8_BAR __builtin_amdgcn_s_barrier()
; #define PG8_SCHED __builtin_amdgcn_sched_barrier(0)
; template <class Epi, class Sched, bool ALIGN_EPI = false, bool SP2 = false>
; __device__ __forceinline__ void gemm_phase(PG8_LAS unsigned char* lds, const Gemm g, const Sched& S, const Epi& E, const int wv0) {
;     ...
;             PG8_LDA(At, 0, 1); PG8_STAGE(PG8_SB(0, 0), b2, voffB); PG8_STAGE(PG8_SB(0, 1), b2 + hstepB, voffB); PG8_STAGE(PG8_SA(0, 0), a2, voffA);
;             PG8_WAIT_V(8); PG8_WAIT_L(0); PG8_BAR; PG8_MMA(1, 0, At, B0); PG8_MMA(1, 1, At, B1); PG8_BAR; PG8_SCHED;
;             PG8_LDB(B0, 1, 0); PG8_LDB(B1, 1, 1); PG8_SCHED; PG8_LDA(At, 1, 0); PG8_STAGE(PG8_SA(0, 1), a2 + hstepA, voffA);
;             PG8_WAIT_V(8); PG8_WAIT_L(0); PG8_BAR; PG8_MMA(0, 0, At, B0); PG8_MMA(0, 1, At, B1); PG8_BAR; PG8_SCHED;
	v_mfma_f32_16x16x32_bf16 v[172:175], v[38:41], v[98:101], 0
	v_mfma_f32_16x16x32_bf16 v[180:183], v[38:41], v[148:151], 0
	v_mfma_f32_16x16x32_bf16 v[188:191], v[38:41], v[156:159], 0
	v_mfma_f32_16x16x32_bf16 v[38:41], v[38:41], v[164:167], 0
	v_mfma_f32_16x16x32_bf16 v[172:175], v[42:45], v[144:147], v[172:175]
	v_mfma_f32_16x16x32_bf16 v[176:179], v[46:49], v[98:101], 0
	v_mfma_f32_16x16x32_bf16 v[180:183], v[42:45], v[152:155], v[180:183]
	v_mfma_f32_16x16x32_bf16 v[184:187], v[46:49], v[148:151], 0
	v_mfma_f32_16x16x32_bf16 v[188:191], v[42:45], v[160:163], v[188:191]
	v_mfma_f32_16x16x32_bf16 v[192:195], v[46:49], v[156:159], 0
	v_mfma_f32_16x16x32_bf16 v[38:41], v[42:45], v[168:171], v[38:41]
	v_mfma_f32_16x16x32_bf16 v[42:45], v[46:49], v[164:167], 0
	v_mfma_f32_16x16x32_bf16 v[176:179], v[50:53], v[144:147], v[176:179]
	v_mfma_f32_16x16x32_bf16 v[184:187], v[50:53], v[152:155], v[184:187]
	v_mfma_f32_16x16x32_bf16 v[192:195], v[50:53], v[160:163], v[192:195]
	v_mfma_f32_16x16x32_bf16 v[42:45], v[50:53], v[168:171], v[42:45]
	v_mfma_f32_16x16x32_bf16 v[46:49], v[54:57], v[98:101], 0
	v_mfma_f32_16x16x32_bf16 v[50:53], v[62:65], v[98:101], 0
	v_mfma_f32_16x16x32_bf16 v[46:49], v[58:61], v[144:147], v[46:49]
	v_mfma_f32_16x16x32_bf16 v[50:53], v[66:69], v[144:147], v[50:53]
	v_mfma_f32_16x16x32_bf16 v[98:101], v[54:57], v[148:151], 0
	v_mfma_f32_16x16x32_bf16 v[144:147], v[62:65], v[148:151], 0
	v_mfma_f32_16x16x32_bf16 v[148:151], v[54:57], v[156:159], 0
	v_mfma_f32_16x16x32_bf16 v[54:57], v[54:57], v[164:167], 0
	v_mfma_f32_16x16x32_bf16 v[98:101], v[58:61], v[152:155], v[98:101]
	v_mfma_f32_16x16x32_bf16 v[144:147], v[66:69], v[152:155], v[144:147]
	v_mfma_f32_16x16x32_bf16 v[148:151], v[58:61], v[160:163], v[148:151]
	v_mfma_f32_16x16x32_bf16 v[152:155], v[62:65], v[156:159], 0
	v_mfma_f32_16x16x32_bf16 v[54:57], v[58:61], v[168:171], v[54:57]
	v_mfma_f32_16x16x32_bf16 v[58:61], v[62:65], v[164:167], 0
	v_mfma_f32_16x16x32_bf16 v[152:155], v[66:69], v[160:163], v[152:155]
	v_mfma_f32_16x16x32_bf16 v[58:61], v[66:69], v[168:171], v[58:61]
	s_barrier
	ds_read_b128 v[62:65], v239
	ds_read_b128 v[66:69], v239 offset:1024
	ds_read_b128 v[156:159], v239 offset:2048
	ds_read_b128 v[160:163], v239 offset:3072
	ds_read_b128 v[164:167], v238
	ds_read_b128 v[168:171], v238 offset:1024
	ds_read_b128 v[196:199], v238 offset:2048
	ds_read_b128 v[200:203], v238 offset:3072
	s_add_u32 s66, s20, 0x40100
	s_addc_u32 s67, s21, 0
	s_mov_b32 m0, s55
	v_lshl_add_u64 v[34:35], s[66:67], 0, v[16:17]
	ds_read_b128 v[206:209], v143 offset:32768
	ds_read_b128 v[210:213], v143 offset:33792
	ds_read_b128 v[214:217], v143 offset:34816
	ds_read_b128 v[218:221], v143 offset:35840
	ds_read_b128 v[222:225], v143 offset:36864
	ds_read_b128 v[226:229], v143 offset:37888
	ds_read_b128 v[230:233], v143 offset:38912
	ds_read_b128 v[234:237], v143 offset:39936
	global_load_lds_dwordx4 v[34:35], off
	v_lshl_add_u64 v[34:35], s[66:67], 0, v[30:31]
	s_mov_b32 m0, s56
	s_nop 0
	global_load_lds_dwordx4 v[34:35], off
	s_waitcnt vmcnt(8)
	s_waitcnt lgkmcnt(0)
	s_barrier
	v_mfma_f32_16x16x32_bf16 v[102:105], v[62:65], v[206:209], v[102:105]
	v_mfma_f32_16x16x32_bf16 v[106:109], v[156:159], v[206:209], v[106:109]
	v_mfma_f32_16x16x32_bf16 v[110:113], v[62:65], v[214:217], v[110:113]
	v_mfma_f32_16x16x32_bf16 v[114:117], v[156:159], v[214:217], v[114:117]
	v_mfma_f32_16x16x32_bf16 v[118:121], v[62:65], v[222:225], v[118:121]
	v_mfma_f32_16x16x32_bf16 v[122:125], v[156:159], v[222:225], v[122:125]
	v_mfma_f32_16x16x32_bf16 v[130:133], v[62:65], v[230:233], v[130:133]
	v_mfma_f32_16x16x32_bf16 v[134:137], v[156:159], v[230:233], v[134:137]
	v_mfma_f32_16x16x32_bf16 v[102:105], v[66:69], v[210:213], v[102:105]
	v_mfma_f32_16x16x32_bf16 v[106:109], v[160:163], v[210:213], v[106:109]
	v_mfma_f32_16x16x32_bf16 v[110:113], v[66:69], v[218:221], v[110:113]
	v_mfma_f32_16x16x32_bf16 v[114:117], v[160:163], v[218:221], v[114:117]
	v_mfma_f32_16x16x32_bf16 v[118:121], v[66:69], v[226:229], v[118:121]
	v_mfma_f32_16x16x32_bf16 v[122:125], v[160:163], v[226:229], v[122:125]
	v_mfma_f32_16x16x32_bf16 v[130:133], v[66:69], v[234:237], v[130:133]
	v_mfma_f32_16x16x32_bf16 v[134:137], v[160:163], v[234:237], v[134:137]
	v_mfma_f32_16x16x32_bf16 v[138:141], v[164:167], v[206:209], v[138:141]
	v_mfma_f32_16x16x32_bf16 v[70:73], v[196:199], v[206:209], v[70:73]
	v_mfma_f32_16x16x32_bf16 v[74:77], v[164:167], v[214:217], v[74:77]
	v_mfma_f32_16x16x32_bf16 v[78:81], v[196:199], v[214:217], v[78:81]
	v_mfma_f32_16x16x32_bf16 v[82:85], v[164:167], v[222:225], v[82:85]
	v_mfma_f32_16x16x32_bf16 v[86:89], v[196:199], v[222:225], v[86:89]
	v_mfma_f32_16x16x32_bf16 v[90:93], v[164:167], v[230:233], v[90:93]
	v_mfma_f32_16x16x32_bf16 v[94:97], v[196:199], v[230:233], v[94:97]
	v_mfma_f32_16x16x32_bf16 v[138:141], v[168:171], v[210:213], v[138:141]
	v_mfma_f32_16x16x32_bf16 v[70:73], v[200:203], v[210:213], v[70:73]
	v_mfma_f32_16x16x32_bf16 v[74:77], v[168:171], v[218:221], v[74:77]
	v_mfma_f32_16x16x32_bf16 v[78:81], v[200:203], v[218:221], v[78:81]
	v_mfma_f32_16x16x32_bf16 v[82:85], v[168:171], v[226:229], v[82:85]
	v_mfma_f32_16x16x32_bf16 v[86:89], v[200:203], v[226:229], v[86:89]
	v_mfma_f32_16x16x32_bf16 v[90:93], v[168:171], v[234:237], v[90:93]
	v_mfma_f32_16x16x32_bf16 v[94:97], v[200:203], v[234:237], v[94:97]
	s_barrier
; #define PG8_STAGE(bufoff, gbase, voff) do { _Pragma("unroll") for (int _i = 0; _i < 2; ++_i) \
;         __builtin_amdgcn_global_load_lds((const unsigned*)((const char*)(gbase) + (voff)[_i]), (PG8_LAS unsigned*)(lds + (bufoff) + ldsw + _i * 8192), 16, 0, 0); } while (0)
; #define PG8_LDA(dst, b, h) do { _Pragma("unroll") for (int m = 0; m < 4; ++m) _Pragma("unroll") for (int k = 0; k < 2; ++k) dst[m][k] = *(const PG8_LAS bf16x8*)(lds + PG8_SA(b, h) + aoff + m * 2048 + k * 1024); } while (0)
; #define PG8_MMA(ai, bj, At, Bt) do { __builtin_amdgcn_s_setprio(1); _Pragma("unroll") for (int m = 0; m < 4; ++m) _Pragma("unroll") for (int n = 0; n < 2; ++n) _Pragma("unroll") for (int k = 0; k < 2; ++k) \
;         acc[ai][bj][m][n] = __builtin_amdgcn_mfma_f32_16x16x32_bf16(Bt[n][k], At[m][k], acc[ai][bj][m][n], 0, 0, 0); __builtin_amdgcn_s_setprio(0); } while (0)
; #define PG8_WAIT_V(n) asm volatile("s_waitcnt vmcnt(" #n ")" ::: "memory")
; #define PG8_WAIT_L(n) asm volatile("s_waitcnt lgkmcnt(" #n ")" ::: "memory")
; #define PG8_BAR __builtin_amdgcn_s_barrier()
; #define PG8_SCHED __builtin_amdgcn_sched_barrier(0)
; template <class Epi, class Sched, bool ALIGN_EPI = false, bool SP2 = false>
; __device__ __forceinline__ void gemm_phase(PG8_LAS unsigned char* lds, const Gemm g, const Sched& S, const Epi& E, const int wv0) {
;     ...
;             PG8_WAIT_V(8); PG8_WAIT_L(0); PG8_BAR; PG8_MMA(0, 0, At, B0); PG8_MMA(0, 1, At, B1); PG8_BAR; PG8_SCHED;
;             PG8_LDA(At, 1, 1); PG8_STAGE(PG8_SB(1, 0), b3, voffB); PG8_STAGE(PG8_SB(1, 1), b3 + hstepB, voffB); PG8_STAGE(PG8_SA(1, 0), a3, voffA);
;             PG8_WAIT_V(8); PG8_WAIT_L(0); PG8_BAR; PG8_MMA(1, 0, At, B0); PG8_MMA(1, 1, At, B1); PG8_BAR; PG8_SCHED;
	s_mov_b32 m0, s51
	v_lshl_add_u64 v[34:35], v[26:27], 0, s[12:13]
	s_add_u32 s22, s22, 0x10180
	ds_read_b128 v[206:209], v143 offset:49152
	ds_read_b128 v[210:213], v143 offset:50176
	ds_read_b128 v[214:217], v143 offset:51200
	ds_read_b128 v[218:221], v143 offset:52224
	ds_read_b128 v[222:225], v143 offset:53248
	ds_read_b128 v[226:229], v143 offset:54272
	ds_read_b128 v[230:233], v143 offset:55296
	ds_read_b128 v[234:237], v143 offset:56320
	global_load_lds_dwordx4 v[34:35], off
	v_lshl_add_u64 v[34:35], v[28:29], 0, s[12:13]
	s_mov_b32 m0, s53
	s_addc_u32 s23, s23, 0
	global_load_lds_dwordx4 v[34:35], off
	v_lshl_add_u64 v[34:35], s[22:23], 0, v[128:129]
	s_mov_b32 m0, s57
	v_lshl_add_u64 v[32:33], s[22:23], 0, v[32:33]
	global_load_lds_dwordx4 v[34:35], off
	s_mov_b32 m0, s58
	s_nop 0
	global_load_lds_dwordx4 v[32:33], off
	v_lshl_add_u64 v[32:33], v[20:21], 0, s[12:13]
	s_mov_b32 m0, s52
	s_nop 0
	global_load_lds_dwordx4 v[32:33], off
	v_lshl_add_u64 v[32:33], v[22:23], 0, s[12:13]
	s_mov_b32 m0, s54
	s_nop 0
	global_load_lds_dwordx4 v[32:33], off
	s_waitcnt vmcnt(8)
	s_waitcnt lgkmcnt(0)
	s_barrier
	v_mfma_f32_16x16x32_bf16 v[32:35], v[62:65], v[206:209], v[172:175]
	v_mfma_f32_16x16x32_bf16 v[172:175], v[156:159], v[206:209], v[176:179]
	v_mfma_f32_16x16x32_bf16 v[176:179], v[62:65], v[214:217], v[180:183]
	v_mfma_f32_16x16x32_bf16 v[180:183], v[156:159], v[214:217], v[184:187]
	v_mfma_f32_16x16x32_bf16 v[184:187], v[62:65], v[222:225], v[188:191]
	v_mfma_f32_16x16x32_bf16 v[188:191], v[156:159], v[222:225], v[192:195]
	v_mfma_f32_16x16x32_bf16 v[38:41], v[62:65], v[230:233], v[38:41]
	v_mfma_f32_16x16x32_bf16 v[42:45], v[156:159], v[230:233], v[42:45]
	v_mfma_f32_16x16x32_bf16 v[32:35], v[66:69], v[210:213], v[32:35]
	v_mfma_f32_16x16x32_bf16 v[172:175], v[160:163], v[210:213], v[172:175]
	v_mfma_f32_16x16x32_bf16 v[176:179], v[66:69], v[218:221], v[176:179]
	v_mfma_f32_16x16x32_bf16 v[180:183], v[160:163], v[218:221], v[180:183]
	v_mfma_f32_16x16x32_bf16 v[184:187], v[66:69], v[226:229], v[184:187]
	v_mfma_f32_16x16x32_bf16 v[188:191], v[160:163], v[226:229], v[188:191]
	v_mfma_f32_16x16x32_bf16 v[38:41], v[66:69], v[234:237], v[38:41]
	v_mfma_f32_16x16x32_bf16 v[42:45], v[160:163], v[234:237], v[42:45]
	v_mfma_f32_16x16x32_bf16 v[46:49], v[164:167], v[206:209], v[46:49]
	v_mfma_f32_16x16x32_bf16 v[50:53], v[196:199], v[206:209], v[50:53]
	v_mfma_f32_16x16x32_bf16 v[62:65], v[164:167], v[214:217], v[98:101]
	v_mfma_f32_16x16x32_bf16 v[66:69], v[196:199], v[214:217], v[144:147]
	v_mfma_f32_16x16x32_bf16 v[98:101], v[164:167], v[222:225], v[148:151]
	v_mfma_f32_16x16x32_bf16 v[144:147], v[196:199], v[222:225], v[152:155]
	v_mfma_f32_16x16x32_bf16 v[54:57], v[164:167], v[230:233], v[54:57]
	v_mfma_f32_16x16x32_bf16 v[58:61], v[196:199], v[230:233], v[58:61]
	v_mfma_f32_16x16x32_bf16 v[46:49], v[168:171], v[210:213], v[46:49]
	v_mfma_f32_16x16x32_bf16 v[50:53], v[200:203], v[210:213], v[50:53]
	v_mfma_f32_16x16x32_bf16 v[62:65], v[168:171], v[218:221], v[62:65]
	v_mfma_f32_16x16x32_bf16 v[66:69], v[200:203], v[218:221], v[66:69]
	v_mfma_f32_16x16x32_bf16 v[98:101], v[168:171], v[226:229], v[98:101]
	v_mfma_f32_16x16x32_bf16 v[144:147], v[200:203], v[226:229], v[144:147]
	v_mfma_f32_16x16x32_bf16 v[54:57], v[168:171], v[234:237], v[54:57]
	v_mfma_f32_16x16x32_bf16 v[58:61], v[200:203], v[234:237], v[58:61]
	s_barrier
	ds_read_b128 v[148:151], v127
	ds_read_b128 v[152:155], v127 offset:1024
	ds_read_b128 v[156:159], v127 offset:2048
	ds_read_b128 v[160:163], v127 offset:3072
	ds_read_b128 v[164:167], v126
	ds_read_b128 v[168:171], v126 offset:1024
	ds_read_b128 v[192:195], v126 offset:2048
	ds_read_b128 v[196:199], v126 offset:3072
	s_add_u32 s20, s20, 0x40180
	s_addc_u32 s21, s21, 0
	s_mov_b32 m0, s64
	v_lshl_add_u64 v[16:17], s[20:21], 0, v[16:17]
	ds_read_b128 v[200:203], v143
	ds_read_b128 v[206:209], v143 offset:1024
	ds_read_b128 v[210:213], v143 offset:2048
	ds_read_b128 v[214:217], v143 offset:3072
	ds_read_b128 v[218:221], v143 offset:4096
	ds_read_b128 v[222:225], v143 offset:5120
	ds_read_b128 v[226:229], v143 offset:6144
	ds_read_b128 v[230:233], v143 offset:7168
	global_load_lds_dwordx4 v[16:17], off
	v_lshl_add_u64 v[16:17], s[20:21], 0, v[30:31]
	s_mov_b32 m0, s61
	s_nop 0
	global_load_lds_dwordx4 v[16:17], off
	s_waitcnt vmcnt(8)
	s_waitcnt lgkmcnt(0)
	s_barrier
	v_mfma_f32_16x16x32_bf16 v[102:105], v[148:151], v[200:203], v[102:105]
	v_mfma_f32_16x16x32_bf16 v[106:109], v[156:159], v[200:203], v[106:109]
	v_mfma_f32_16x16x32_bf16 v[110:113], v[148:151], v[210:213], v[110:113]
	v_mfma_f32_16x16x32_bf16 v[114:117], v[156:159], v[210:213], v[114:117]
	v_mfma_f32_16x16x32_bf16 v[118:121], v[148:151], v[218:221], v[118:121]
	v_mfma_f32_16x16x32_bf16 v[122:125], v[156:159], v[218:221], v[122:125]
	v_mfma_f32_16x16x32_bf16 v[130:133], v[148:151], v[226:229], v[130:133]
	v_mfma_f32_16x16x32_bf16 v[134:137], v[156:159], v[226:229], v[134:137]
	v_mfma_f32_16x16x32_bf16 v[102:105], v[152:155], v[206:209], v[102:105]
	v_mfma_f32_16x16x32_bf16 v[106:109], v[160:163], v[206:209], v[106:109]
	v_mfma_f32_16x16x32_bf16 v[110:113], v[152:155], v[214:217], v[110:113]
	v_mfma_f32_16x16x32_bf16 v[114:117], v[160:163], v[214:217], v[114:117]
	v_mfma_f32_16x16x32_bf16 v[118:121], v[152:155], v[222:225], v[118:121]
	v_mfma_f32_16x16x32_bf16 v[122:125], v[160:163], v[222:225], v[122:125]
	v_mfma_f32_16x16x32_bf16 v[130:133], v[152:155], v[230:233], v[130:133]
	v_mfma_f32_16x16x32_bf16 v[134:137], v[160:163], v[230:233], v[134:137]
	v_mfma_f32_16x16x32_bf16 v[138:141], v[164:167], v[200:203], v[138:141]
	v_mfma_f32_16x16x32_bf16 v[70:73], v[192:195], v[200:203], v[70:73]
	v_mfma_f32_16x16x32_bf16 v[74:77], v[164:167], v[210:213], v[74:77]
	v_mfma_f32_16x16x32_bf16 v[78:81], v[192:195], v[210:213], v[78:81]
	v_mfma_f32_16x16x32_bf16 v[82:85], v[164:167], v[218:221], v[82:85]
	v_mfma_f32_16x16x32_bf16 v[86:89], v[192:195], v[218:221], v[86:89]
	v_mfma_f32_16x16x32_bf16 v[90:93], v[164:167], v[226:229], v[90:93]
	v_mfma_f32_16x16x32_bf16 v[94:97], v[192:195], v[226:229], v[94:97]
	v_mfma_f32_16x16x32_bf16 v[138:141], v[168:171], v[206:209], v[138:141]
	v_mfma_f32_16x16x32_bf16 v[70:73], v[196:199], v[206:209], v[70:73]
	v_mfma_f32_16x16x32_bf16 v[74:77], v[168:171], v[214:217], v[74:77]
	v_mfma_f32_16x16x32_bf16 v[78:81], v[196:199], v[214:217], v[78:81]
	v_mfma_f32_16x16x32_bf16 v[82:85], v[168:171], v[222:225], v[82:85]
	v_mfma_f32_16x16x32_bf16 v[86:89], v[196:199], v[222:225], v[86:89]
	v_mfma_f32_16x16x32_bf16 v[90:93], v[168:171], v[230:233], v[90:93]
	v_mfma_f32_16x16x32_bf16 v[94:97], v[196:199], v[230:233], v[94:97]
	s_barrier
; #define PG8_STAGE(bufoff, gbase, voff) do { _Pragma("unroll") for (int _i = 0; _i < 2; ++_i) \
;         __builtin_amdgcn_global_load_lds((const unsigned*)((const char*)(gbase) + (voff)[_i]), (PG8_LAS unsigned*)(lds + (bufoff) + ldsw + _i * 8192), 16, 0, 0); } while (0)
; #define PG8_LDA(dst, b, h) do { _Pragma("unroll") for (int m = 0; m < 4; ++m) _Pragma("unroll") for (int k = 0; k < 2; ++k) dst[m][k] = *(const PG8_LAS bf16x8*)(lds + PG8_SA(b, h) + aoff + m * 2048 + k * 1024); } while (0)
; #define PG8_LDB(dst, b, h) do { _Pragma("unroll") for (int n = 0; n < 2; ++n) _Pragma("unroll") for (int k = 0; k < 2; ++k) dst[n][k] = *(const PG8_LAS bf16x8*)(lds + PG8_SB(b, h) + boff + n * 2048 + k * 1024); } while (0)
; #define PG8_MMA(ai, bj, At, Bt) do { __builtin_amdgcn_s_setprio(1); _Pragma("unroll") for (int m = 0; m < 4; ++m) _Pragma("unroll") for (int n = 0; n < 2; ++n) _Pragma("unroll") for (int k = 0; k < 2; ++k) \
;         acc[ai][bj][m][n] = __builtin_amdgcn_mfma_f32_16x16x32_bf16(Bt[n][k], At[m][k], acc[ai][bj][m][n], 0, 0, 0); __builtin_amdgcn_s_setprio(0); } while (0)
; #define PG8_WAIT_V(n) asm volatile("s_waitcnt vmcnt(" #n ")" ::: "memory")
; #define PG8_WAIT_L(n) asm volatile("s_waitcnt lgkmcnt(" #n ")" ::: "memory")
; #define PG8_BAR __builtin_amdgcn_s_barrier()
; #define PG8_SCHED __builtin_amdgcn_sched_barrier(0)
; template <class Epi, class Sched, bool ALIGN_EPI = false, bool SP2 = false>
; __device__ __forceinline__ void gemm_phase(PG8_LAS unsigned char* lds, const Gemm g, const Sched& S, const Epi& E, const int wv0) {
;     ...
;             PG8_LDA(At, 0, 1); PG8_STAGE(PG8_SB(0, 0), b2, voffB); PG8_STAGE(PG8_SB(0, 1), b2 + hstepB, voffB); PG8_STAGE(PG8_SA(0, 0), a2, voffA);
;             PG8_WAIT_V(8); PG8_WAIT_L(0); PG8_BAR; PG8_MMA(1, 0, At, B0); PG8_MMA(1, 1, At, B1); PG8_BAR; PG8_SCHED;
;             PG8_LDB(B0, 1, 0); PG8_LDB(B1, 1, 1); PG8_SCHED; PG8_LDA(At, 1, 0); PG8_STAGE(PG8_SA(0, 1), a2 + hstepA, voffA);
;             PG8_WAIT_V(8); PG8_WAIT_L(0); PG8_BAR; PG8_MMA(0, 0, At, B0); PG8_MMA(0, 1, At, B1); PG8_BAR; PG8_SCHED;
	s_mov_b32 m0, s48
	ds_read_b128 v[200:203], v143 offset:16384
	ds_read_b128 v[206:209], v143 offset:17408
	ds_read_b128 v[210:213], v143 offset:18432
	ds_read_b128 v[214:217], v143 offset:19456
	ds_read_b128 v[218:221], v143 offset:20480
	ds_read_b128 v[222:225], v143 offset:21504
	ds_read_b128 v[226:229], v143 offset:22528
	ds_read_b128 v[230:233], v143 offset:23552
	global_load_lds_dwordx4 v[26:27], off
	s_mov_b32 m0, s62
	s_nop 0
	global_load_lds_dwordx4 v[28:29], off
	s_mov_b32 m0, s47
	s_nop 0
	global_load_lds_dwordx4 v[24:25], off
	s_mov_b32 m0, s63
	s_nop 0
	global_load_lds_dwordx4 v[18:19], off
	s_mov_b32 m0, s59
	s_nop 0
	global_load_lds_dwordx4 v[20:21], off
	s_mov_b32 m0, s60
	s_nop 0
	global_load_lds_dwordx4 v[22:23], off
	s_waitcnt vmcnt(8)
	s_waitcnt lgkmcnt(0)
	s_barrier
	v_mfma_f32_16x16x32_bf16 v[16:19], v[148:151], v[200:203], v[32:35]
	v_mfma_f32_16x16x32_bf16 v[20:23], v[156:159], v[200:203], v[172:175]
	v_mfma_f32_16x16x32_bf16 v[24:27], v[148:151], v[210:213], v[176:179]
	v_mfma_f32_16x16x32_bf16 v[28:31], v[156:159], v[210:213], v[180:183]
	v_mfma_f32_16x16x32_bf16 v[32:35], v[148:151], v[218:221], v[184:187]
	v_mfma_f32_16x16x32_bf16 v[172:175], v[156:159], v[218:221], v[188:191]
	v_mfma_f32_16x16x32_bf16 v[38:41], v[148:151], v[226:229], v[38:41]
	v_mfma_f32_16x16x32_bf16 v[42:45], v[156:159], v[226:229], v[42:45]
	v_mfma_f32_16x16x32_bf16 v[16:19], v[152:155], v[206:209], v[16:19]
	v_mfma_f32_16x16x32_bf16 v[20:23], v[160:163], v[206:209], v[20:23]
	v_mfma_f32_16x16x32_bf16 v[24:27], v[152:155], v[214:217], v[24:27]
	v_mfma_f32_16x16x32_bf16 v[28:31], v[160:163], v[214:217], v[28:31]
	v_mfma_f32_16x16x32_bf16 v[32:35], v[152:155], v[222:225], v[32:35]
	v_mfma_f32_16x16x32_bf16 v[172:175], v[160:163], v[222:225], v[172:175]
	v_mfma_f32_16x16x32_bf16 v[38:41], v[152:155], v[230:233], v[38:41]
	v_mfma_f32_16x16x32_bf16 v[42:45], v[160:163], v[230:233], v[42:45]
	v_mfma_f32_16x16x32_bf16 v[46:49], v[164:167], v[200:203], v[46:49]
	v_mfma_f32_16x16x32_bf16 v[50:53], v[192:195], v[200:203], v[50:53]
	v_mfma_f32_16x16x32_bf16 v[62:65], v[164:167], v[210:213], v[62:65]
	v_mfma_f32_16x16x32_bf16 v[66:69], v[192:195], v[210:213], v[66:69]
	v_mfma_f32_16x16x32_bf16 v[98:101], v[164:167], v[218:221], v[98:101]
	v_mfma_f32_16x16x32_bf16 v[144:147], v[192:195], v[218:221], v[144:147]
	v_mfma_f32_16x16x32_bf16 v[54:57], v[164:167], v[226:229], v[54:57]
	v_mfma_f32_16x16x32_bf16 v[58:61], v[192:195], v[226:229], v[58:61]
	v_mfma_f32_16x16x32_bf16 v[46:49], v[168:171], v[206:209], v[46:49]
	v_mfma_f32_16x16x32_bf16 v[50:53], v[196:199], v[206:209], v[50:53]
	v_mfma_f32_16x16x32_bf16 v[62:65], v[168:171], v[214:217], v[62:65]
	v_mfma_f32_16x16x32_bf16 v[66:69], v[196:199], v[214:217], v[66:69]
	v_mfma_f32_16x16x32_bf16 v[98:101], v[168:171], v[222:225], v[98:101]
	v_mfma_f32_16x16x32_bf16 v[144:147], v[196:199], v[222:225], v[144:147]
	v_mfma_f32_16x16x32_bf16 v[54:57], v[168:171], v[230:233], v[54:57]
	v_mfma_f32_16x16x32_bf16 v[58:61], v[196:199], v[230:233], v[58:61]
	s_barrier
	ds_read_b128 v[148:151], v239
	ds_read_b128 v[152:155], v239 offset:1024
	ds_read_b128 v[156:159], v239 offset:2048
	ds_read_b128 v[160:163], v239 offset:3072
	ds_read_b128 v[164:167], v238
	ds_read_b128 v[168:171], v238 offset:1024
	ds_read_b128 v[176:179], v238 offset:2048
	ds_read_b128 v[180:183], v238 offset:3072
	s_mov_b32 m0, s55
	ds_read_b128 v[184:187], v143 offset:32768
	ds_read_b128 v[188:191], v143 offset:33792
	ds_read_b128 v[192:195], v143 offset:34816
	ds_read_b128 v[196:199], v143 offset:35840
	ds_read_b128 v[200:203], v143 offset:36864
	ds_read_b128 v[206:209], v143 offset:37888
	ds_read_b128 v[210:213], v143 offset:38912
	ds_read_b128 v[214:217], v143 offset:39936
	global_load_lds_dwordx4 v[12:13], off
	s_mov_b32 m0, s56
	s_nop 0
	global_load_lds_dwordx4 v[14:15], off
	s_waitcnt vmcnt(8)
	s_waitcnt lgkmcnt(0)
	s_barrier
	v_mfma_f32_16x16x32_bf16 v[12:15], v[148:151], v[184:187], v[102:105]
	v_mfma_f32_16x16x32_bf16 v[102:105], v[152:155], v[188:191], v[12:15]
	v_mfma_f32_16x16x32_bf16 v[12:15], v[156:159], v[184:187], v[106:109]
	v_mfma_f32_16x16x32_bf16 v[106:109], v[160:163], v[188:191], v[12:15]
	v_mfma_f32_16x16x32_bf16 v[12:15], v[148:151], v[192:195], v[110:113]
	v_mfma_f32_16x16x32_bf16 v[110:113], v[152:155], v[196:199], v[12:15]
	v_mfma_f32_16x16x32_bf16 v[12:15], v[156:159], v[192:195], v[114:117]
	v_mfma_f32_16x16x32_bf16 v[114:117], v[160:163], v[196:199], v[12:15]
	v_mfma_f32_16x16x32_bf16 v[12:15], v[148:151], v[200:203], v[118:121]
	v_mfma_f32_16x16x32_bf16 v[118:121], v[152:155], v[206:209], v[12:15]
	v_mfma_f32_16x16x32_bf16 v[12:15], v[156:159], v[200:203], v[122:125]
	v_mfma_f32_16x16x32_bf16 v[122:125], v[160:163], v[206:209], v[12:15]
	v_mfma_f32_16x16x32_bf16 v[12:15], v[148:151], v[210:213], v[130:133]
	v_mfma_f32_16x16x32_bf16 v[130:133], v[152:155], v[214:217], v[12:15]
	v_mfma_f32_16x16x32_bf16 v[12:15], v[156:159], v[210:213], v[134:137]
	v_mfma_f32_16x16x32_bf16 v[134:137], v[160:163], v[214:217], v[12:15]
	v_mfma_f32_16x16x32_bf16 v[12:15], v[164:167], v[184:187], v[138:141]
	v_mfma_f32_16x16x32_bf16 v[138:141], v[168:171], v[188:191], v[12:15]
	v_mfma_f32_16x16x32_bf16 v[12:15], v[176:179], v[184:187], v[70:73]
	v_mfma_f32_16x16x32_bf16 v[70:73], v[180:183], v[188:191], v[12:15]
	v_mfma_f32_16x16x32_bf16 v[12:15], v[164:167], v[192:195], v[74:77]
	v_mfma_f32_16x16x32_bf16 v[74:77], v[168:171], v[196:199], v[12:15]
	v_mfma_f32_16x16x32_bf16 v[12:15], v[176:179], v[192:195], v[78:81]
	v_mfma_f32_16x16x32_bf16 v[78:81], v[180:183], v[196:199], v[12:15]
	v_mfma_f32_16x16x32_bf16 v[12:15], v[164:167], v[200:203], v[82:85]
	v_mfma_f32_16x16x32_bf16 v[82:85], v[168:171], v[206:209], v[12:15]
	v_mfma_f32_16x16x32_bf16 v[12:15], v[176:179], v[200:203], v[86:89]
	v_mfma_f32_16x16x32_bf16 v[86:89], v[180:183], v[206:209], v[12:15]
	v_mfma_f32_16x16x32_bf16 v[12:15], v[164:167], v[210:213], v[90:93]
	v_mfma_f32_16x16x32_bf16 v[90:93], v[168:171], v[214:217], v[12:15]
	v_mfma_f32_16x16x32_bf16 v[12:15], v[176:179], v[210:213], v[94:97]
	v_mfma_f32_16x16x32_bf16 v[94:97], v[180:183], v[214:217], v[12:15]
	s_barrier
; #define PG8_STAGE(bufoff, gbase, voff) do { _Pragma("unroll") for (int _i = 0; _i < 2; ++_i) \
;         __builtin_amdgcn_global_load_lds((const unsigned*)((const char*)(gbase) + (voff)[_i]), (PG8_LAS unsigned*)(lds + (bufoff) + ldsw + _i * 8192), 16, 0, 0); } while (0)
; #define PG8_LDA(dst, b, h) do { _Pragma("unroll") for (int m = 0; m < 4; ++m) _Pragma("unroll") for (int k = 0; k < 2; ++k) dst[m][k] = *(const PG8_LAS bf16x8*)(lds + PG8_SA(b, h) + aoff + m * 2048 + k * 1024); } while (0)
; #define PG8_MMA(ai, bj, At, Bt) do { __builtin_amdgcn_s_setprio(1); _Pragma("unroll") for (int m = 0; m < 4; ++m) _Pragma("unroll") for (int n = 0; n < 2; ++n) _Pragma("unroll") for (int k = 0; k < 2; ++k) \
;         acc[ai][bj][m][n] = __builtin_amdgcn_mfma_f32_16x16x32_bf16(Bt[n][k], At[m][k], acc[ai][bj][m][n], 0, 0, 0); __builtin_amdgcn_s_setprio(0); } while (0)
; #define PG8_WAIT_V(n) asm volatile("s_waitcnt vmcnt(" #n ")" ::: "memory")
; #define PG8_WAIT_L(n) asm volatile("s_waitcnt lgkmcnt(" #n ")" ::: "memory")
; #define PG8_BAR __builtin_amdgcn_s_barrier()
; #define PG8_SCHED __builtin_amdgcn_sched_barrier(0)
; template <class Epi, class Sched, bool ALIGN_EPI = false, bool SP2 = false>
; __device__ __forceinline__ void gemm_phase(PG8_LAS unsigned char* lds, const Gemm g, const Sched& S, const Epi& E, const int wv0) {
;     ...
;             PG8_LDA(At, 1, 1); PG8_STAGE(PG8_SB(1, 0), b3, voffB); PG8_STAGE(PG8_SB(1, 1), b3 + hstepB, voffB); PG8_STAGE(PG8_SA(1, 0), a3, voffA);
;             PG8_WAIT_V(8); PG8_WAIT_L(0); PG8_BAR; PG8_MMA(1, 0, At, B0); PG8_MMA(1, 1, At, B1); PG8_BAR; PG8_SCHED;
	s_mov_b32 m0, s51
	ds_read_b128 v[184:187], v143 offset:49152
	ds_read_b128 v[188:191], v143 offset:50176
	ds_read_b128 v[192:195], v143 offset:51200
	ds_read_b128 v[196:199], v143 offset:52224
	ds_read_b128 v[200:203], v143 offset:53248
	ds_read_b128 v[206:209], v143 offset:54272
	ds_read_b128 v[210:213], v143 offset:55296
	ds_read_b128 v[214:217], v143 offset:56320
	global_load_lds_dwordx4 v[2:3], off
	s_mov_b32 m0, s53
	s_nop 0
	global_load_lds_dwordx4 v[4:5], off
	s_mov_b32 m0, s57
	s_nop 0
	global_load_lds_dwordx4 v[8:9], off
	s_mov_b32 m0, s58
	s_nop 0
	global_load_lds_dwordx4 v[10:11], off
	s_mov_b32 m0, s52
	s_nop 0
	global_load_lds_dwordx4 v[0:1], off
	s_mov_b32 m0, s54
	s_nop 0
	global_load_lds_dwordx4 v[6:7], off
	s_waitcnt vmcnt(8)
	s_waitcnt lgkmcnt(0)
	s_barrier
	v_mfma_f32_16x16x32_bf16 v[0:3], v[148:151], v[184:187], v[16:19]
	v_mfma_f32_16x16x32_bf16 v[218:221], v[152:155], v[188:191], v[0:3]
	v_mfma_f32_16x16x32_bf16 v[0:3], v[156:159], v[184:187], v[20:23]
	v_mfma_f32_16x16x32_bf16 v[222:225], v[160:163], v[188:191], v[0:3]
	v_mfma_f32_16x16x32_bf16 v[0:3], v[148:151], v[192:195], v[24:27]
	v_mfma_f32_16x16x32_bf16 v[226:229], v[152:155], v[196:199], v[0:3]
	v_mfma_f32_16x16x32_bf16 v[0:3], v[156:159], v[192:195], v[28:31]
	v_mfma_f32_16x16x32_bf16 v[230:233], v[160:163], v[196:199], v[0:3]
	v_mfma_f32_16x16x32_bf16 v[0:3], v[148:151], v[200:203], v[32:35]
	v_mfma_f32_16x16x32_bf16 v[28:31], v[152:155], v[206:209], v[0:3]
	v_mfma_f32_16x16x32_bf16 v[0:3], v[156:159], v[200:203], v[172:175]
	v_mfma_f32_16x16x32_bf16 v[20:23], v[160:163], v[206:209], v[0:3]
	v_mfma_f32_16x16x32_bf16 v[0:3], v[148:151], v[210:213], v[38:41]
	v_mfma_f32_16x16x32_bf16 v[12:15], v[152:155], v[214:217], v[0:3]
	v_mfma_f32_16x16x32_bf16 v[0:3], v[156:159], v[210:213], v[42:45]
	v_mfma_f32_16x16x32_bf16 v[4:7], v[160:163], v[214:217], v[0:3]
	v_mfma_f32_16x16x32_bf16 v[0:3], v[164:167], v[184:187], v[46:49]
	v_mfma_f32_16x16x32_bf16 v[38:41], v[168:171], v[188:191], v[0:3]
	v_mfma_f32_16x16x32_bf16 v[0:3], v[176:179], v[184:187], v[50:53]
	v_mfma_f32_16x16x32_bf16 v[42:45], v[180:183], v[188:191], v[0:3]
	v_mfma_f32_16x16x32_bf16 v[0:3], v[164:167], v[192:195], v[62:65]
	v_mfma_f32_16x16x32_bf16 v[46:49], v[168:171], v[196:199], v[0:3]
	v_mfma_f32_16x16x32_bf16 v[0:3], v[176:179], v[192:195], v[66:69]
	v_mfma_f32_16x16x32_bf16 v[32:35], v[180:183], v[196:199], v[0:3]
	v_mfma_f32_16x16x32_bf16 v[0:3], v[164:167], v[200:203], v[98:101]
	v_mfma_f32_16x16x32_bf16 v[24:27], v[168:171], v[206:209], v[0:3]
	v_mfma_f32_16x16x32_bf16 v[0:3], v[176:179], v[200:203], v[144:147]
	v_mfma_f32_16x16x32_bf16 v[16:19], v[180:183], v[206:209], v[0:3]
	v_mfma_f32_16x16x32_bf16 v[0:3], v[164:167], v[210:213], v[54:57]
	v_mfma_f32_16x16x32_bf16 v[8:11], v[168:171], v[214:217], v[0:3]
	v_mfma_f32_16x16x32_bf16 v[0:3], v[176:179], v[210:213], v[58:61]
	v_mfma_f32_16x16x32_bf16 v[0:3], v[180:183], v[214:217], v[0:3]
	s_barrier
; __device__ __forceinline__ unsigned cvtpk(float lo, float hi) { unsigned r; asm volatile("v_cvt_pk_bf16_f32 %0, %1, %2" : "=v"(r) : "v"(lo), "v"(hi)); return r; }
;     __device__ __forceinline__ void operator()(const f32x4 (&acc)[2][2][4][2], const Unit& u, int wr, int wc, int fr, int fq) const {
;         const int row0 = u.pm * BM + wr * 64 + fr; const int col0 = u.pn * BM + wc * 32 + 8 * fq;
; #pragma unroll
;         for (int ai = 0; ai < 2; ++ai)
; #pragma unroll
;             for (int m = 0; m < 4; ++m) { bf16* rowp = O + (size_t)(row0 + ai * HALF + m * 16) * ldc + col0;
; #pragma unroll
;                 for (int bj = 0; bj < 2; ++bj) { const f32x4 v0 = acc[ai][bj][m][0], v1 = acc[ai][bj][m][1];
;                     u32x4 w; w.x = cvtpk(v0[0], v0[1]); w.y = cvtpk(v0[2], v0[3]); w.z = cvtpk(v1[0], v1[1]); w.w = cvtpk(v1[2], v1[3]);
;                     *(u32x4*)(rowp + bj * HALF) = w; } }
	v_add_u32_e32 v54, s24, v36
	v_or_b32_e32 v36, s49, v37
	v_ashrrev_i32_e32 v55, 31, v54
	v_or_b32_e32 v50, s50, v36
	v_lshlrev_b64 v[36:37], 11, v[54:55]
	v_lshl_add_u64 v[36:37], s[4:5], 0, v[36:37]
	v_lshlrev_b32_e32 v128, 1, v50
	v_lshl_add_u64 v[36:37], v[36:37], 0, v[128:129]
	v_cvt_pk_bf16_f32 v50, v102, v103
	v_cvt_pk_bf16_f32 v51, v104, v105
	v_cvt_pk_bf16_f32 v52, v106, v107
	v_cvt_pk_bf16_f32 v53, v108, v109
	global_store_dwordx4 v[36:37], v[50:53], off
	s_cmpk_gt_u32 s25, 0xff
	s_nop 0
	v_cvt_pk_bf16_f32 v50, v138, v139
	v_cvt_pk_bf16_f32 v51, v140, v141
	v_cvt_pk_bf16_f32 v52, v70, v71
	v_cvt_pk_bf16_f32 v53, v72, v73
	global_store_dwordx4 v[36:37], v[50:53], off offset:256
	s_nop 1
	v_or_b32_e32 v50, 16, v54
	v_ashrrev_i32_e32 v51, 31, v50
	v_lshlrev_b64 v[50:51], 11, v[50:51]
	v_lshl_add_u64 v[50:51], s[4:5], 0, v[50:51]
	v_lshl_add_u64 v[56:57], v[50:51], 0, v[128:129]
	v_cvt_pk_bf16_f32 v50, v110, v111
	v_cvt_pk_bf16_f32 v51, v112, v113
	v_cvt_pk_bf16_f32 v52, v114, v115
	v_cvt_pk_bf16_f32 v53, v116, v117
	global_store_dwordx4 v[56:57], v[50:53], off
	s_nop 1
	v_cvt_pk_bf16_f32 v50, v74, v75
	v_cvt_pk_bf16_f32 v51, v76, v77
	v_cvt_pk_bf16_f32 v52, v78, v79
	v_cvt_pk_bf16_f32 v53, v80, v81
	global_store_dwordx4 v[56:57], v[50:53], off offset:256
	s_nop 1
	v_or_b32_e32 v50, 32, v54
	v_ashrrev_i32_e32 v51, 31, v50
	v_lshlrev_b64 v[50:51], 11, v[50:51]
	v_lshl_add_u64 v[50:51], s[4:5], 0, v[50:51]
	v_lshl_add_u64 v[56:57], v[50:51], 0, v[128:129]
	v_cvt_pk_bf16_f32 v50, v118, v119
	v_cvt_pk_bf16_f32 v51, v120, v121
	v_cvt_pk_bf16_f32 v52, v122, v123
	v_cvt_pk_bf16_f32 v53, v124, v125
	global_store_dwordx4 v[56:57], v[50:53], off
	s_nop 1
	v_cvt_pk_bf16_f32 v50, v82, v83
	v_cvt_pk_bf16_f32 v51, v84, v85
	v_cvt_pk_bf16_f32 v52, v86, v87
	v_cvt_pk_bf16_f32 v53, v88, v89
	global_store_dwordx4 v[56:57], v[50:53], off offset:256
	v_add_co_u32_e32 v56, vcc, s39, v36
	s_nop 0
	v_or_b32_e32 v50, 48, v54
	v_ashrrev_i32_e32 v51, 31, v50
	v_lshlrev_b64 v[50:51], 11, v[50:51]
	v_lshl_add_u64 v[50:51], s[4:5], 0, v[50:51]
	v_lshl_add_u64 v[54:55], v[50:51], 0, v[128:129]
	v_cvt_pk_bf16_f32 v50, v130, v131
	v_cvt_pk_bf16_f32 v51, v132, v133
	v_cvt_pk_bf16_f32 v52, v134, v135
	v_cvt_pk_bf16_f32 v53, v136, v137
	global_store_dwordx4 v[54:55], v[50:53], off
	v_addc_co_u32_e32 v57, vcc, 0, v37, vcc
	s_nop 0
	v_cvt_pk_bf16_f32 v50, v90, v91
	v_cvt_pk_bf16_f32 v51, v92, v93
	v_cvt_pk_bf16_f32 v52, v94, v95
	v_cvt_pk_bf16_f32 v53, v96, v97
	global_store_dwordx4 v[54:55], v[50:53], off offset:256
	v_lshl_add_u64 v[54:55], v[36:37], 0, s[6:7]
	s_nop 0
	v_cvt_pk_bf16_f32 v50, v218, v219
	v_cvt_pk_bf16_f32 v51, v220, v221
	v_cvt_pk_bf16_f32 v52, v222, v223
	v_cvt_pk_bf16_f32 v53, v224, v225
	global_store_dwordx4 v[56:57], v[50:53], off
	v_cvt_pk_bf16_f32 v38, v38, v39
	v_cvt_pk_bf16_f32 v39, v40, v41
	v_cvt_pk_bf16_f32 v40, v42, v43
	v_cvt_pk_bf16_f32 v41, v44, v45
	v_add_co_u32_e32 v44, vcc, s40, v36
	global_store_dwordx4 v[54:55], v[38:41], off offset:256
	v_lshl_add_u64 v[42:43], v[36:37], 0, s[14:15]
	v_addc_co_u32_e32 v45, vcc, 0, v37, vcc
	v_cvt_pk_bf16_f32 v38, v226, v227
	v_cvt_pk_bf16_f32 v39, v228, v229
	v_cvt_pk_bf16_f32 v40, v230, v231
	v_cvt_pk_bf16_f32 v41, v232, v233
	global_store_dwordx4 v[44:45], v[38:41], off
	s_nop 1
	v_cvt_pk_bf16_f32 v38, v46, v47
	v_cvt_pk_bf16_f32 v39, v48, v49
	v_cvt_pk_bf16_f32 v40, v32, v33
	v_cvt_pk_bf16_f32 v41, v34, v35
	global_store_dwordx4 v[42:43], v[38:41], off offset:256
	v_cvt_pk_bf16_f32 v28, v28, v29
	v_cvt_pk_bf16_f32 v29, v30, v31
	v_cvt_pk_bf16_f32 v30, v20, v21
	v_add_co_u32_e32 v20, vcc, s41, v36
	v_lshl_add_u64 v[32:33], v[36:37], 0, s[16:17]
	s_nop 0
	v_addc_co_u32_e32 v21, vcc, 0, v37, vcc
	v_cvt_pk_bf16_f32 v31, v22, v23
	global_store_dwordx4 v[20:21], v[28:31], off
	v_cvt_pk_bf16_f32 v20, v24, v25
	v_cvt_pk_bf16_f32 v21, v26, v27
	v_cvt_pk_bf16_f32 v22, v16, v17
	v_cvt_pk_bf16_f32 v23, v18, v19
	global_store_dwordx4 v[32:33], v[20:23], off offset:256
	v_cvt_pk_bf16_f32 v12, v12, v13
	v_cvt_pk_bf16_f32 v13, v14, v15
	v_cvt_pk_bf16_f32 v14, v4, v5
	v_add_co_u32_e32 v4, vcc, s45, v36
	v_lshl_add_u64 v[16:17], v[36:37], 0, s[18:19]
	s_nop 0
	v_addc_co_u32_e32 v5, vcc, 0, v37, vcc
	v_cvt_pk_bf16_f32 v15, v6, v7
	global_store_dwordx4 v[4:5], v[12:15], off
	v_cvt_pk_bf16_f32 v4, v8, v9
	v_cvt_pk_bf16_f32 v5, v10, v11
	v_cvt_pk_bf16_f32 v6, v0, v1
	v_cvt_pk_bf16_f32 v7, v2, v3
	global_store_dwordx4 v[16:17], v[4:7], off offset:256
	s_waitcnt vmcnt(0)
	s_cbranch_scc1 .LBB0_355
	s_barrier
	s_branch .LBB0_355

; #define PG8_STAGE(bufoff, gbase, voff) do { _Pragma("unroll") for (int _i = 0; _i < 2; ++_i) \
;         __builtin_amdgcn_global_load_lds((const unsigned*)((const char*)(gbase) + (voff)[_i]), (PG8_LAS unsigned*)(lds + (bufoff) + ldsw + _i * 8192), 16, 0, 0); } while (0)
; #define PG8_LDA(dst, b, h) do { _Pragma("unroll") for (int m = 0; m < 4; ++m) _Pragma("unroll") for (int k = 0; k < 2; ++k) dst[m][k] = *(const PG8_LAS bf16x8*)(lds + PG8_SA(b, h) + aoff + m * 2048 + k * 1024); } while (0)
; #define PG8_LDB(dst, b, h) do { _Pragma("unroll") for (int n = 0; n < 2; ++n) _Pragma("unroll") for (int k = 0; k < 2; ++k) dst[n][k] = *(const PG8_LAS bf16x8*)(lds + PG8_SB(b, h) + boff + n * 2048 + k * 1024); } while (0)
; #define PG8_MMA(ai, bj, At, Bt) do { __builtin_amdgcn_s_setprio(1); _Pragma("unroll") for (int m = 0; m < 4; ++m) _Pragma("unroll") for (int n = 0; n < 2; ++n) _Pragma("unroll") for (int k = 0; k < 2; ++k) \
;         acc[ai][bj][m][n] = __builtin_amdgcn_mfma_f32_16x16x32_bf16(Bt[n][k], At[m][k], acc[ai][bj][m][n], 0, 0, 0); __builtin_amdgcn_s_setprio(0); } while (0)
; #define PG8_WAIT_V(n) asm volatile("s_waitcnt vmcnt(" #n ")" ::: "memory")
; #define PG8_BAR __builtin_amdgcn_s_barrier()
; template <class Epi, class Sched, bool ALIGN_EPI = false, bool SP2 = false>
; __device__ __forceinline__ void gemm_phase(PG8_LAS unsigned char* lds, const Gemm g, const Sched& S, const Epi& E, const int wv0) {
;     ...
;         PG8_STAGE(PG8_SB(0, 0), cB, voffB); PG8_STAGE(PG8_SB(0, 1), cB + hstepB, voffB); PG8_STAGE(PG8_SA(0, 0), cA, voffA); PG8_STAGE(PG8_SA(0, 1), cA + hstepA, voffA);
;         if (wr == 1) PG8_BAR;
;         PG8_WAIT_V(2); PG8_BAR;
;         PG8_STAGE(PG8_SB(1, 0), cB + kstep, voffB); PG8_STAGE(PG8_SA(1, 0), cA + kstep, voffA); PG8_STAGE(PG8_SB(1, 1), cB + hstepB + kstep, voffB);
;         PG8_WAIT_V(6); PG8_BAR;
;     ...
;             PG8_LDB(B0, 0, 0); PG8_LDB(B1, 0, 1); PG8_SCHED; PG8_LDA(At, 0, 0); PG8_STAGE(PG8_SA(1, 1), a1 + hstepA, voffA);
;             PG8_WAIT_V(8); PG8_WAIT_L(0); PG8_BAR; PG8_MMA(0, 0, At, B0); PG8_MMA(0, 1, At, B1); PG8_BAR; PG8_SCHED;
;             PG8_LDA(At, 0, 1); PG8_STAGE(PG8_SB(0, 0), b2, voffB); PG8_STAGE(PG8_SB(0, 1), b2 + hstepB, voffB); PG8_STAGE(PG8_SA(0, 0), a2, voffA);
;             PG8_WAIT_V(8); PG8_WAIT_L(0); PG8_BAR; PG8_MMA(1, 0, At, B0); PG8_MMA(1, 1, At, B1); PG8_BAR; PG8_SCHED;
.LBB0_1299:
	s_and_b32 s51, s47, 3
	s_lshl_b32 s47, s50, 13
	s_lshl_b32 s48, s51, 12
	s_add_u32 s64, s61, 0x2e280080
	s_addc_u32 s65, s62, 0
	s_add_i32 s26, s36, s66
	v_lshl_add_u64 v[2:3], s[64:65], 0, v[128:129]
	s_mov_b32 m0, s26
	s_add_i32 s53, s26, 0x2000
	s_waitcnt vmcnt(2)
	s_barrier
	global_load_lds_dwordx4 v[2:3], off
	v_lshl_add_u64 v[4:5], s[64:65], 0, v[32:33]
	s_mov_b32 m0, s53
	s_add_i32 s27, s59, 0x8000
	s_add_i32 s54, s59, 0xa000
	global_load_lds_dwordx4 v[4:5], off
	v_lshl_add_u64 v[0:1], v[20:21], 0, s[10:11]
	s_mov_b32 m0, s27
	s_add_u32 s64, s61, 0x2e290080
	global_load_lds_dwordx4 v[0:1], off
	v_lshl_add_u64 v[6:7], v[22:23], 0, s[10:11]
	s_mov_b32 m0, s54
	s_addc_u32 s65, s62, 0
	s_add_i32 s57, s37, s66
	global_load_lds_dwordx4 v[6:7], off
	v_lshl_add_u64 v[8:9], s[64:65], 0, v[128:129]
	s_mov_b32 m0, s57
	s_add_i32 s58, s57, 0x2000
	global_load_lds_dwordx4 v[8:9], off
	v_lshl_add_u64 v[10:11], s[64:65], 0, v[32:33]
	s_mov_b32 m0, s58
	v_bfe_u32 v144, v34, 4, 2
	global_load_lds_dwordx4 v[10:11], off
	v_and_b32_e32 v143, 15, v34
	v_lshlrev_b32_e32 v35, 4, v144
	v_lshlrev_b32_e32 v34, 2, v34
	v_lshl_or_b32 v35, v143, 6, v35
	v_and_b32_e32 v34, 32, v34
	v_bitop3_b32 v66, v35, s48, v34 bitop3:0xde
	s_add_i32 s48, 0, 0x10000
	v_bitop3_b32 v36, v35, s47, v34 bitop3:0xde
	s_add_i32 s47, 0, 0x14000
	v_add_u32_e32 v203, s48, v66
	s_waitcnt vmcnt(6)
	s_barrier
	v_add_u32_e32 v145, 0, v36
	v_add_u32_e32 v202, s47, v66
	ds_read_b128 v[34:37], v203
	ds_read_b128 v[38:41], v203 offset:1024
	ds_read_b128 v[42:45], v203 offset:2048
	ds_read_b128 v[46:49], v203 offset:3072
	ds_read_b128 v[50:53], v202
	ds_read_b128 v[54:57], v202 offset:1024
	ds_read_b128 v[58:61], v202 offset:2048
	ds_read_b128 v[62:65], v202 offset:3072
	s_add_u32 s70, s61, 0x2e280100
	v_add_u32_e32 v246, s37, v66
	v_add_u32_e32 v247, s36, v66
	s_addc_u32 s71, s62, 0
	s_add_u32 s64, s24, 0x40080
	s_addc_u32 s65, s25, 0
	s_add_i32 s68, s59, 0xc000
	v_lshl_add_u64 v[98:99], s[64:65], 0, v[16:17]
	s_mov_b32 m0, s68
	s_add_i32 s63, s59, 0xe000
	ds_read_b128 v[66:69], v145
	ds_read_b128 v[70:73], v145 offset:1024
	ds_read_b128 v[74:77], v145 offset:2048
	ds_read_b128 v[78:81], v145 offset:3072
	ds_read_b128 v[82:85], v145 offset:4096
	ds_read_b128 v[86:89], v145 offset:5120
	ds_read_b128 v[90:93], v145 offset:6144
	ds_read_b128 v[94:97], v145 offset:7168
	global_load_lds_dwordx4 v[98:99], off
	v_lshl_add_u64 v[98:99], s[64:65], 0, v[30:31]
	s_mov_b32 m0, s63
	s_nop 0
	global_load_lds_dwordx4 v[98:99], off
	s_waitcnt vmcnt(8)
	s_waitcnt lgkmcnt(0)
	s_barrier
	v_mfma_f32_16x16x32_bf16 v[98:101], v[34:37], v[66:69], 0
	v_mfma_f32_16x16x32_bf16 v[102:105], v[42:45], v[66:69], 0
	v_mfma_f32_16x16x32_bf16 v[106:109], v[34:37], v[74:77], 0
	v_mfma_f32_16x16x32_bf16 v[110:113], v[42:45], v[74:77], 0
	v_mfma_f32_16x16x32_bf16 v[114:117], v[34:37], v[82:85], 0
	v_mfma_f32_16x16x32_bf16 v[118:121], v[42:45], v[82:85], 0
	v_mfma_f32_16x16x32_bf16 v[122:125], v[34:37], v[90:93], 0
	v_mfma_f32_16x16x32_bf16 v[98:101], v[38:41], v[70:73], v[98:101]
	v_mfma_f32_16x16x32_bf16 v[102:105], v[46:49], v[70:73], v[102:105]
	v_mfma_f32_16x16x32_bf16 v[106:109], v[38:41], v[78:81], v[106:109]
	v_mfma_f32_16x16x32_bf16 v[110:113], v[46:49], v[78:81], v[110:113]
	v_mfma_f32_16x16x32_bf16 v[114:117], v[38:41], v[86:89], v[114:117]
	v_mfma_f32_16x16x32_bf16 v[118:121], v[46:49], v[86:89], v[118:121]
	v_mfma_f32_16x16x32_bf16 v[122:125], v[38:41], v[94:97], v[122:125]
	v_mfma_f32_16x16x32_bf16 v[130:133], v[42:45], v[90:93], 0
	v_mfma_f32_16x16x32_bf16 v[130:133], v[46:49], v[94:97], v[130:133]
	v_mfma_f32_16x16x32_bf16 v[134:137], v[50:53], v[66:69], 0
	v_mfma_f32_16x16x32_bf16 v[66:69], v[58:61], v[66:69], 0
	v_mfma_f32_16x16x32_bf16 v[134:137], v[54:57], v[70:73], v[134:137]
	v_mfma_f32_16x16x32_bf16 v[66:69], v[62:65], v[70:73], v[66:69]
	v_mfma_f32_16x16x32_bf16 v[70:73], v[50:53], v[74:77], 0
	v_mfma_f32_16x16x32_bf16 v[74:77], v[58:61], v[74:77], 0
	v_mfma_f32_16x16x32_bf16 v[70:73], v[54:57], v[78:81], v[70:73]
	v_mfma_f32_16x16x32_bf16 v[74:77], v[62:65], v[78:81], v[74:77]
	v_mfma_f32_16x16x32_bf16 v[78:81], v[50:53], v[82:85], 0
	v_mfma_f32_16x16x32_bf16 v[82:85], v[58:61], v[82:85], 0
	v_mfma_f32_16x16x32_bf16 v[78:81], v[54:57], v[86:89], v[78:81]
	v_mfma_f32_16x16x32_bf16 v[82:85], v[62:65], v[86:89], v[82:85]
	v_mfma_f32_16x16x32_bf16 v[86:89], v[50:53], v[90:93], 0
	v_mfma_f32_16x16x32_bf16 v[90:93], v[58:61], v[90:93], 0
	v_mfma_f32_16x16x32_bf16 v[86:89], v[54:57], v[94:97], v[86:89]
	v_mfma_f32_16x16x32_bf16 v[90:93], v[62:65], v[94:97], v[90:93]
	s_barrier
	s_add_i32 s64, s48, s66
	v_lshl_add_u64 v[126:127], s[70:71], 0, v[128:129]
	s_mov_b32 m0, s64
	s_add_i32 s65, s64, 0x2000
	ds_read_b128 v[94:97], v145 offset:16384
	ds_read_b128 v[138:141], v145 offset:17408
	ds_read_b128 v[146:149], v145 offset:18432
	ds_read_b128 v[150:153], v145 offset:19456
	ds_read_b128 v[154:157], v145 offset:20480
	ds_read_b128 v[158:161], v145 offset:21504
	ds_read_b128 v[162:165], v145 offset:22528
	ds_read_b128 v[166:169], v145 offset:23552
	global_load_lds_dwordx4 v[126:127], off
	v_lshl_add_u64 v[126:127], s[70:71], 0, v[32:33]
	s_add_u32 s70, s61, 0x2e290100
	s_mov_b32 m0, s65
	s_addc_u32 s71, s62, 0
	s_add_i32 s66, s47, s66
	global_load_lds_dwordx4 v[126:127], off
	v_lshl_add_u64 v[126:127], s[70:71], 0, v[128:129]
	s_mov_b32 m0, s66
	s_add_i32 s67, s66, 0x2000
	global_load_lds_dwordx4 v[126:127], off
	v_lshl_add_u64 v[126:127], s[70:71], 0, v[32:33]
	s_mov_b32 m0, s67
	s_nop 0
	global_load_lds_dwordx4 v[126:127], off
	v_lshl_add_u64 v[126:127], v[20:21], 0, s[12:13]
	s_mov_b32 m0, s59
	s_nop 0
	global_load_lds_dwordx4 v[126:127], off
	v_lshl_add_u64 v[126:127], v[22:23], 0, s[12:13]
	s_mov_b32 m0, s60
	s_nop 0
	global_load_lds_dwordx4 v[126:127], off
	s_waitcnt vmcnt(8)
	s_waitcnt lgkmcnt(0)
	s_barrier
; #define PG8_STAGE(bufoff, gbase, voff) do { _Pragma("unroll") for (int _i = 0; _i < 2; ++_i) \
;         __builtin_amdgcn_global_load_lds((const unsigned*)((const char*)(gbase) + (voff)[_i]), (PG8_LAS unsigned*)(lds + (bufoff) + ldsw + _i * 8192), 16, 0, 0); } while (0)
; #define PG8_LDA(dst, b, h) do { _Pragma("unroll") for (int m = 0; m < 4; ++m) _Pragma("unroll") for (int k = 0; k < 2; ++k) dst[m][k] = *(const PG8_LAS bf16x8*)(lds + PG8_SA(b, h) + aoff + m * 2048 + k * 1024); } while (0)
; #define PG8_LDB(dst, b, h) do { _Pragma("unroll") for (int n = 0; n < 2; ++n) _Pragma("unroll") for (int k = 0; k < 2; ++k) dst[n][k] = *(const PG8_LAS bf16x8*)(lds + PG8_SB(b, h) + boff + n * 2048 + k * 1024); } while (0)
; #define PG8_MMA(ai, bj, At, Bt) do { __builtin_amdgcn_s_setprio(1); _Pragma("unroll") for (int m = 0; m < 4; ++m) _Pragma("unroll") for (int n = 0; n < 2; ++n) _Pragma("unroll") for (int k = 0; k < 2; ++k) \
;         acc[ai][bj][m][n] = __builtin_amdgcn_mfma_f32_16x16x32_bf16(Bt[n][k], At[m][k], acc[ai][bj][m][n], 0, 0, 0); __builtin_amdgcn_s_setprio(0); } while (0)
; #define PG8_WAIT_V(n) asm volatile("s_waitcnt vmcnt(" #n ")" ::: "memory")
; #define PG8_WAIT_L(n) asm volatile("s_waitcnt lgkmcnt(" #n ")" ::: "memory")
; #define PG8_BAR __builtin_amdgcn_s_barrier()
; #define PG8_SCHED __builtin_amdgcn_sched_barrier(0)
; template <class Epi, class Sched, bool ALIGN_EPI = false, bool SP2 = false>
; __device__ __forceinline__ void gemm_phase(PG8_LAS unsigned char* lds, const Gemm g, const Sched& S, const Epi& E, const int wv0) {
;     ...
;             PG8_WAIT_V(8); PG8_WAIT_L(0); PG8_BAR; PG8_MMA(1, 0, At, B0); PG8_MMA(1, 1, At, B1); PG8_BAR; PG8_SCHED;
;             PG8_LDB(B0, 1, 0); PG8_LDB(B1, 1, 1); PG8_SCHED; PG8_LDA(At, 1, 0); PG8_STAGE(PG8_SA(0, 1), a2 + hstepA, voffA);
;             PG8_WAIT_V(8); PG8_WAIT_L(0); PG8_BAR; PG8_MMA(0, 0, At, B0); PG8_MMA(0, 1, At, B1); PG8_BAR; PG8_SCHED;
	v_mfma_f32_16x16x32_bf16 v[170:173], v[34:37], v[94:97], 0
	v_mfma_f32_16x16x32_bf16 v[178:181], v[34:37], v[146:149], 0
	v_mfma_f32_16x16x32_bf16 v[186:189], v[34:37], v[154:157], 0
	v_mfma_f32_16x16x32_bf16 v[34:37], v[34:37], v[162:165], 0
	v_mfma_f32_16x16x32_bf16 v[170:173], v[38:41], v[138:141], v[170:173]
	v_mfma_f32_16x16x32_bf16 v[178:181], v[38:41], v[150:153], v[178:181]
	v_mfma_f32_16x16x32_bf16 v[186:189], v[38:41], v[158:161], v[186:189]
	v_mfma_f32_16x16x32_bf16 v[34:37], v[38:41], v[166:169], v[34:37]
	v_mfma_f32_16x16x32_bf16 v[38:41], v[42:45], v[162:165], 0
	v_mfma_f32_16x16x32_bf16 v[174:177], v[42:45], v[94:97], 0
	v_mfma_f32_16x16x32_bf16 v[182:185], v[42:45], v[146:149], 0
	v_mfma_f32_16x16x32_bf16 v[190:193], v[42:45], v[154:157], 0
	v_mfma_f32_16x16x32_bf16 v[38:41], v[46:49], v[166:169], v[38:41]
	v_mfma_f32_16x16x32_bf16 v[174:177], v[46:49], v[138:141], v[174:177]
	v_mfma_f32_16x16x32_bf16 v[182:185], v[46:49], v[150:153], v[182:185]
	v_mfma_f32_16x16x32_bf16 v[190:193], v[46:49], v[158:161], v[190:193]
	v_mfma_f32_16x16x32_bf16 v[42:45], v[50:53], v[94:97], 0
	v_mfma_f32_16x16x32_bf16 v[46:49], v[58:61], v[94:97], 0
	v_mfma_f32_16x16x32_bf16 v[42:45], v[54:57], v[138:141], v[42:45]
	v_mfma_f32_16x16x32_bf16 v[46:49], v[62:65], v[138:141], v[46:49]
	v_mfma_f32_16x16x32_bf16 v[94:97], v[50:53], v[146:149], 0
	v_mfma_f32_16x16x32_bf16 v[138:141], v[58:61], v[146:149], 0
	v_mfma_f32_16x16x32_bf16 v[146:149], v[50:53], v[154:157], 0
	v_mfma_f32_16x16x32_bf16 v[50:53], v[50:53], v[162:165], 0
	v_mfma_f32_16x16x32_bf16 v[94:97], v[54:57], v[150:153], v[94:97]
	v_mfma_f32_16x16x32_bf16 v[146:149], v[54:57], v[158:161], v[146:149]
	v_mfma_f32_16x16x32_bf16 v[50:53], v[54:57], v[166:169], v[50:53]
	v_mfma_f32_16x16x32_bf16 v[54:57], v[58:61], v[162:165], 0
	v_mfma_f32_16x16x32_bf16 v[138:141], v[62:65], v[150:153], v[138:141]
	v_mfma_f32_16x16x32_bf16 v[150:153], v[58:61], v[154:157], 0
	v_mfma_f32_16x16x32_bf16 v[54:57], v[62:65], v[166:169], v[54:57]
	v_mfma_f32_16x16x32_bf16 v[150:153], v[62:65], v[158:161], v[150:153]
	s_barrier
	ds_read_b128 v[58:61], v247
	ds_read_b128 v[62:65], v247 offset:1024
	ds_read_b128 v[154:157], v247 offset:2048
	ds_read_b128 v[158:161], v247 offset:3072
	ds_read_b128 v[162:165], v246
	ds_read_b128 v[166:169], v246 offset:1024
	ds_read_b128 v[194:197], v246 offset:2048
	ds_read_b128 v[198:201], v246 offset:3072
	s_add_u32 s70, s24, 0x40100
	s_addc_u32 s71, s25, 0
	s_mov_b32 m0, s55
	v_lshl_add_u64 v[126:127], s[70:71], 0, v[16:17]
	ds_read_b128 v[206:209], v145 offset:32768
	ds_read_b128 v[210:213], v145 offset:33792
	ds_read_b128 v[214:217], v145 offset:34816
	ds_read_b128 v[218:221], v145 offset:35840
	ds_read_b128 v[222:225], v145 offset:36864
	ds_read_b128 v[226:229], v145 offset:37888
	ds_read_b128 v[230:233], v145 offset:38912
	ds_read_b128 v[234:237], v145 offset:39936
	global_load_lds_dwordx4 v[126:127], off
	v_lshl_add_u64 v[126:127], s[70:71], 0, v[30:31]
	s_mov_b32 m0, s56
	s_nop 0
	global_load_lds_dwordx4 v[126:127], off
	s_waitcnt vmcnt(8)
	s_waitcnt lgkmcnt(0)
	s_barrier
	v_mfma_f32_16x16x32_bf16 v[98:101], v[58:61], v[206:209], v[98:101]
	v_mfma_f32_16x16x32_bf16 v[102:105], v[154:157], v[206:209], v[102:105]
	v_mfma_f32_16x16x32_bf16 v[106:109], v[58:61], v[214:217], v[106:109]
	v_mfma_f32_16x16x32_bf16 v[110:113], v[154:157], v[214:217], v[110:113]
	v_mfma_f32_16x16x32_bf16 v[114:117], v[58:61], v[222:225], v[114:117]
	v_mfma_f32_16x16x32_bf16 v[118:121], v[154:157], v[222:225], v[118:121]
	v_mfma_f32_16x16x32_bf16 v[122:125], v[58:61], v[230:233], v[122:125]
	v_mfma_f32_16x16x32_bf16 v[98:101], v[62:65], v[210:213], v[98:101]
	v_mfma_f32_16x16x32_bf16 v[102:105], v[158:161], v[210:213], v[102:105]
	v_mfma_f32_16x16x32_bf16 v[106:109], v[62:65], v[218:221], v[106:109]
	v_mfma_f32_16x16x32_bf16 v[110:113], v[158:161], v[218:221], v[110:113]
	v_mfma_f32_16x16x32_bf16 v[114:117], v[62:65], v[226:229], v[114:117]
	v_mfma_f32_16x16x32_bf16 v[118:121], v[158:161], v[226:229], v[118:121]
	v_mfma_f32_16x16x32_bf16 v[122:125], v[62:65], v[234:237], v[122:125]
	v_mfma_f32_16x16x32_bf16 v[130:133], v[154:157], v[230:233], v[130:133]
	v_mfma_f32_16x16x32_bf16 v[130:133], v[158:161], v[234:237], v[130:133]
	v_mfma_f32_16x16x32_bf16 v[66:69], v[194:197], v[206:209], v[66:69]
	v_mfma_f32_16x16x32_bf16 v[70:73], v[162:165], v[214:217], v[70:73]
	v_mfma_f32_16x16x32_bf16 v[74:77], v[194:197], v[214:217], v[74:77]
	v_mfma_f32_16x16x32_bf16 v[78:81], v[162:165], v[222:225], v[78:81]
	v_mfma_f32_16x16x32_bf16 v[82:85], v[194:197], v[222:225], v[82:85]
	v_mfma_f32_16x16x32_bf16 v[86:89], v[162:165], v[230:233], v[86:89]
	v_mfma_f32_16x16x32_bf16 v[90:93], v[194:197], v[230:233], v[90:93]
	v_mfma_f32_16x16x32_bf16 v[134:137], v[162:165], v[206:209], v[134:137]
	v_mfma_f32_16x16x32_bf16 v[66:69], v[198:201], v[210:213], v[66:69]
	v_mfma_f32_16x16x32_bf16 v[70:73], v[166:169], v[218:221], v[70:73]
	v_mfma_f32_16x16x32_bf16 v[74:77], v[198:201], v[218:221], v[74:77]
	v_mfma_f32_16x16x32_bf16 v[78:81], v[166:169], v[226:229], v[78:81]
	v_mfma_f32_16x16x32_bf16 v[82:85], v[198:201], v[226:229], v[82:85]
	v_mfma_f32_16x16x32_bf16 v[86:89], v[166:169], v[234:237], v[86:89]
	v_mfma_f32_16x16x32_bf16 v[90:93], v[198:201], v[234:237], v[90:93]
	v_mfma_f32_16x16x32_bf16 v[134:137], v[166:169], v[210:213], v[134:137]
	s_barrier
; #define PG8_STAGE(bufoff, gbase, voff) do { _Pragma("unroll") for (int _i = 0; _i < 2; ++_i) \
;         __builtin_amdgcn_global_load_lds((const unsigned*)((const char*)(gbase) + (voff)[_i]), (PG8_LAS unsigned*)(lds + (bufoff) + ldsw + _i * 8192), 16, 0, 0); } while (0)
; #define PG8_LDA(dst, b, h) do { _Pragma("unroll") for (int m = 0; m < 4; ++m) _Pragma("unroll") for (int k = 0; k < 2; ++k) dst[m][k] = *(const PG8_LAS bf16x8*)(lds + PG8_SA(b, h) + aoff + m * 2048 + k * 1024); } while (0)
; #define PG8_LDB(dst, b, h) do { _Pragma("unroll") for (int n = 0; n < 2; ++n) _Pragma("unroll") for (int k = 0; k < 2; ++k) dst[n][k] = *(const PG8_LAS bf16x8*)(lds + PG8_SB(b, h) + boff + n * 2048 + k * 1024); } while (0)
; #define PG8_MMA(ai, bj, At, Bt) do { __builtin_amdgcn_s_setprio(1); _Pragma("unroll") for (int m = 0; m < 4; ++m) _Pragma("unroll") for (int n = 0; n < 2; ++n) _Pragma("unroll") for (int k = 0; k < 2; ++k) \
;         acc[ai][bj][m][n] = __builtin_amdgcn_mfma_f32_16x16x32_bf16(Bt[n][k], At[m][k], acc[ai][bj][m][n], 0, 0, 0); __builtin_amdgcn_s_setprio(0); } while (0)
; #define PG8_BAR __builtin_amdgcn_s_barrier()
; template <class Epi, class Sched, bool ALIGN_EPI = false, bool SP2 = false>
; __device__ __forceinline__ void gemm_phase(PG8_LAS unsigned char* lds, const Gemm g, const Sched& S, const Epi& E, const int wv0) {
;     ...
;             PG8_LDB(B0, 0, 0); PG8_LDB(B1, 0, 1); PG8_SCHED; PG8_LDA(At, 0, 0); PG8_STAGE(PG8_SA(1, 1), a1 + hstepA, voffA);
;             PG8_WAIT_V(8); PG8_WAIT_L(0); PG8_BAR; PG8_MMA(0, 0, At, B0); PG8_MMA(0, 1, At, B1); PG8_BAR; PG8_SCHED;
;             PG8_LDA(At, 0, 1); PG8_STAGE(PG8_SB(0, 0), b2, voffB); PG8_STAGE(PG8_SB(0, 1), b2 + hstepB, voffB); PG8_STAGE(PG8_SA(0, 0), a2, voffA);
;             PG8_WAIT_V(8); PG8_WAIT_L(0); PG8_BAR; PG8_MMA(1, 0, At, B0); PG8_MMA(1, 1, At, B1); PG8_BAR; PG8_SCHED;
;             PG8_LDB(B0, 1, 0); PG8_LDB(B1, 1, 1); PG8_SCHED; PG8_LDA(At, 1, 0); PG8_STAGE(PG8_SA(0, 1), a2 + hstepA, voffA);
;             PG8_WAIT_V(8); PG8_WAIT_L(0); PG8_BAR; PG8_MMA(0, 0, At, B0); PG8_MMA(0, 1, At, B1); PG8_BAR; PG8_SCHED;
;             PG8_LDA(At, 1, 1); PG8_STAGE(PG8_SB(1, 0), b3, voffB); PG8_STAGE(PG8_SB(1, 1), b3 + hstepB, voffB); PG8_STAGE(PG8_SA(1, 0), a3, voffA);
;             PG8_WAIT_V(8); PG8_WAIT_L(0); PG8_BAR; PG8_MMA(1, 0, At, B0); PG8_MMA(1, 1, At, B1); PG8_BAR; PG8_SCHED;
	s_add_u32 s70, s61, 0x2e280180
	s_addc_u32 s71, s62, 0
	s_mov_b32 m0, s26
	v_lshl_add_u64 v[126:127], s[70:71], 0, v[128:129]
	ds_read_b128 v[206:209], v145 offset:49152
	ds_read_b128 v[210:213], v145 offset:50176
	ds_read_b128 v[214:217], v145 offset:51200
	ds_read_b128 v[218:221], v145 offset:52224
	ds_read_b128 v[222:225], v145 offset:53248
	ds_read_b128 v[226:229], v145 offset:54272
	ds_read_b128 v[230:233], v145 offset:55296
	ds_read_b128 v[234:237], v145 offset:56320
	global_load_lds_dwordx4 v[126:127], off
	v_lshl_add_u64 v[126:127], s[70:71], 0, v[32:33]
	s_add_u32 s70, s61, 0x2e290180
	s_mov_b32 m0, s53
	s_addc_u32 s71, s62, 0
	global_load_lds_dwordx4 v[126:127], off
	v_lshl_add_u64 v[126:127], s[70:71], 0, v[128:129]
	s_mov_b32 m0, s57
	v_lshl_add_u64 v[32:33], s[70:71], 0, v[32:33]
	global_load_lds_dwordx4 v[126:127], off
	s_mov_b32 m0, s58
	s_nop 0
	global_load_lds_dwordx4 v[32:33], off
	v_lshl_add_u64 v[32:33], v[20:21], 0, s[14:15]
	s_mov_b32 m0, s27
	s_nop 0
	global_load_lds_dwordx4 v[32:33], off
	v_lshl_add_u64 v[32:33], v[22:23], 0, s[14:15]
	s_mov_b32 m0, s54
	s_nop 0
	global_load_lds_dwordx4 v[32:33], off
	s_waitcnt vmcnt(8)
	s_waitcnt lgkmcnt(0)
	s_barrier
	v_mfma_f32_16x16x32_bf16 v[32:35], v[58:61], v[230:233], v[34:37]
	v_mfma_f32_16x16x32_bf16 v[36:39], v[154:157], v[230:233], v[38:41]
	v_mfma_f32_16x16x32_bf16 v[170:173], v[58:61], v[206:209], v[170:173]
	v_mfma_f32_16x16x32_bf16 v[174:177], v[154:157], v[206:209], v[174:177]
	v_mfma_f32_16x16x32_bf16 v[178:181], v[58:61], v[214:217], v[178:181]
	v_mfma_f32_16x16x32_bf16 v[182:185], v[154:157], v[214:217], v[182:185]
	v_mfma_f32_16x16x32_bf16 v[186:189], v[58:61], v[222:225], v[186:189]
	v_mfma_f32_16x16x32_bf16 v[190:193], v[154:157], v[222:225], v[190:193]
	v_mfma_f32_16x16x32_bf16 v[32:35], v[62:65], v[234:237], v[32:35]
	v_mfma_f32_16x16x32_bf16 v[36:39], v[158:161], v[234:237], v[36:39]
	v_mfma_f32_16x16x32_bf16 v[170:173], v[62:65], v[210:213], v[170:173]
	v_mfma_f32_16x16x32_bf16 v[174:177], v[158:161], v[210:213], v[174:177]
	v_mfma_f32_16x16x32_bf16 v[178:181], v[62:65], v[218:221], v[178:181]
	v_mfma_f32_16x16x32_bf16 v[182:185], v[158:161], v[218:221], v[182:185]
	v_mfma_f32_16x16x32_bf16 v[186:189], v[62:65], v[226:229], v[186:189]
	v_mfma_f32_16x16x32_bf16 v[190:193], v[158:161], v[226:229], v[190:193]
	v_mfma_f32_16x16x32_bf16 v[40:43], v[162:165], v[206:209], v[42:45]
	v_mfma_f32_16x16x32_bf16 v[44:47], v[194:197], v[206:209], v[46:49]
	v_mfma_f32_16x16x32_bf16 v[58:61], v[162:165], v[214:217], v[94:97]
	v_mfma_f32_16x16x32_bf16 v[62:65], v[194:197], v[214:217], v[138:141]
	v_mfma_f32_16x16x32_bf16 v[94:97], v[162:165], v[222:225], v[146:149]
	v_mfma_f32_16x16x32_bf16 v[48:51], v[162:165], v[230:233], v[50:53]
	v_mfma_f32_16x16x32_bf16 v[52:55], v[194:197], v[230:233], v[54:57]
	v_mfma_f32_16x16x32_bf16 v[40:43], v[166:169], v[210:213], v[40:43]
	v_mfma_f32_16x16x32_bf16 v[44:47], v[198:201], v[210:213], v[44:47]
	v_mfma_f32_16x16x32_bf16 v[58:61], v[166:169], v[218:221], v[58:61]
	v_mfma_f32_16x16x32_bf16 v[62:65], v[198:201], v[218:221], v[62:65]
	v_mfma_f32_16x16x32_bf16 v[94:97], v[166:169], v[226:229], v[94:97]
	v_mfma_f32_16x16x32_bf16 v[138:141], v[194:197], v[222:225], v[150:153]
	v_mfma_f32_16x16x32_bf16 v[48:51], v[166:169], v[234:237], v[48:51]
	v_mfma_f32_16x16x32_bf16 v[52:55], v[198:201], v[234:237], v[52:55]
	v_mfma_f32_16x16x32_bf16 v[138:141], v[198:201], v[226:229], v[138:141]
	s_barrier
	ds_read_b128 v[146:149], v203
	ds_read_b128 v[150:153], v203 offset:1024
	ds_read_b128 v[154:157], v203 offset:2048
	ds_read_b128 v[158:161], v203 offset:3072
	ds_read_b128 v[162:165], v202
	ds_read_b128 v[166:169], v202 offset:1024
	ds_read_b128 v[194:197], v202 offset:2048
	ds_read_b128 v[198:201], v202 offset:3072
	s_add_u32 s24, s24, 0x40180
	s_addc_u32 s25, s25, 0
	s_mov_b32 m0, s68
	v_lshl_add_u64 v[16:17], s[24:25], 0, v[16:17]
	ds_read_b128 v[206:209], v145
	ds_read_b128 v[210:213], v145 offset:1024
	ds_read_b128 v[214:217], v145 offset:2048
	ds_read_b128 v[218:221], v145 offset:3072
	ds_read_b128 v[222:225], v145 offset:4096
	ds_read_b128 v[226:229], v145 offset:5120
	ds_read_b128 v[230:233], v145 offset:6144
	ds_read_b128 v[234:237], v145 offset:7168
	global_load_lds_dwordx4 v[16:17], off
	v_lshl_add_u64 v[16:17], s[24:25], 0, v[30:31]
	s_mov_b32 m0, s63
	s_nop 0
	global_load_lds_dwordx4 v[16:17], off
	s_waitcnt vmcnt(8)
	s_waitcnt lgkmcnt(0)
	s_barrier
	v_mfma_f32_16x16x32_bf16 v[114:117], v[146:149], v[222:225], v[114:117]
	v_mfma_f32_16x16x32_bf16 v[238:241], v[150:153], v[226:229], v[114:117]
	v_mfma_f32_16x16x32_bf16 v[114:117], v[154:157], v[222:225], v[118:121]
	v_mfma_f32_16x16x32_bf16 v[98:101], v[146:149], v[206:209], v[98:101]
	v_mfma_f32_16x16x32_bf16 v[102:105], v[154:157], v[206:209], v[102:105]
	v_mfma_f32_16x16x32_bf16 v[106:109], v[146:149], v[214:217], v[106:109]
	v_mfma_f32_16x16x32_bf16 v[110:113], v[154:157], v[214:217], v[110:113]
	v_mfma_f32_16x16x32_bf16 v[242:245], v[158:161], v[226:229], v[114:117]
	v_mfma_f32_16x16x32_bf16 v[114:117], v[146:149], v[230:233], v[122:125]
	v_mfma_f32_16x16x32_bf16 v[98:101], v[150:153], v[210:213], v[98:101]
	v_mfma_f32_16x16x32_bf16 v[102:105], v[158:161], v[210:213], v[102:105]
	v_mfma_f32_16x16x32_bf16 v[106:109], v[150:153], v[218:221], v[106:109]
	v_mfma_f32_16x16x32_bf16 v[110:113], v[158:161], v[218:221], v[110:113]
	v_mfma_f32_16x16x32_bf16 v[124:127], v[150:153], v[234:237], v[114:117]
	v_mfma_f32_16x16x32_bf16 v[114:117], v[154:157], v[230:233], v[130:133]
	v_mfma_f32_16x16x32_bf16 v[130:133], v[158:161], v[234:237], v[114:117]
	v_mfma_f32_16x16x32_bf16 v[66:69], v[194:197], v[206:209], v[66:69]
	v_mfma_f32_16x16x32_bf16 v[114:117], v[162:165], v[206:209], v[134:137]
	v_mfma_f32_16x16x32_bf16 v[206:209], v[198:201], v[210:213], v[66:69]
	v_mfma_f32_16x16x32_bf16 v[66:69], v[162:165], v[214:217], v[70:73]
	v_mfma_f32_16x16x32_bf16 v[134:137], v[166:169], v[210:213], v[114:117]
	v_mfma_f32_16x16x32_bf16 v[210:213], v[166:169], v[218:221], v[66:69]
	v_mfma_f32_16x16x32_bf16 v[66:69], v[194:197], v[214:217], v[74:77]
	v_mfma_f32_16x16x32_bf16 v[214:217], v[198:201], v[218:221], v[66:69]
	v_mfma_f32_16x16x32_bf16 v[66:69], v[162:165], v[222:225], v[78:81]
	v_mfma_f32_16x16x32_bf16 v[76:79], v[166:169], v[226:229], v[66:69]
	v_mfma_f32_16x16x32_bf16 v[66:69], v[194:197], v[222:225], v[82:85]
	v_mfma_f32_16x16x32_bf16 v[80:83], v[198:201], v[226:229], v[66:69]
	v_mfma_f32_16x16x32_bf16 v[66:69], v[162:165], v[230:233], v[86:89]
	v_mfma_f32_16x16x32_bf16 v[218:221], v[166:169], v[234:237], v[66:69]
	v_mfma_f32_16x16x32_bf16 v[66:69], v[194:197], v[230:233], v[90:93]
	v_mfma_f32_16x16x32_bf16 v[222:225], v[198:201], v[234:237], v[66:69]
	s_barrier
; #define PG8_STAGE(bufoff, gbase, voff) do { _Pragma("unroll") for (int _i = 0; _i < 2; ++_i) \
;         __builtin_amdgcn_global_load_lds((const unsigned*)((const char*)(gbase) + (voff)[_i]), (PG8_LAS unsigned*)(lds + (bufoff) + ldsw + _i * 8192), 16, 0, 0); } while (0)
; #define PG8_LDA(dst, b, h) do { _Pragma("unroll") for (int m = 0; m < 4; ++m) _Pragma("unroll") for (int k = 0; k < 2; ++k) dst[m][k] = *(const PG8_LAS bf16x8*)(lds + PG8_SA(b, h) + aoff + m * 2048 + k * 1024); } while (0)
; #define PG8_LDB(dst, b, h) do { _Pragma("unroll") for (int n = 0; n < 2; ++n) _Pragma("unroll") for (int k = 0; k < 2; ++k) dst[n][k] = *(const PG8_LAS bf16x8*)(lds + PG8_SB(b, h) + boff + n * 2048 + k * 1024); } while (0)
; #define PG8_MMA(ai, bj, At, Bt) do { __builtin_amdgcn_s_setprio(1); _Pragma("unroll") for (int m = 0; m < 4; ++m) _Pragma("unroll") for (int n = 0; n < 2; ++n) _Pragma("unroll") for (int k = 0; k < 2; ++k) \
;         acc[ai][bj][m][n] = __builtin_amdgcn_mfma_f32_16x16x32_bf16(Bt[n][k], At[m][k], acc[ai][bj][m][n], 0, 0, 0); __builtin_amdgcn_s_setprio(0); } while (0)
; #define PG8_WAIT_V(n) asm volatile("s_waitcnt vmcnt(" #n ")" ::: "memory")
; #define PG8_WAIT_L(n) asm volatile("s_waitcnt lgkmcnt(" #n ")" ::: "memory")
; #define PG8_BAR __builtin_amdgcn_s_barrier()
; #define PG8_SCHED __builtin_amdgcn_sched_barrier(0)
; template <class Epi, class Sched, bool ALIGN_EPI = false, bool SP2 = false>
; __device__ __forceinline__ void gemm_phase(PG8_LAS unsigned char* lds, const Gemm g, const Sched& S, const Epi& E, const int wv0) {
;     ...
;             PG8_LDA(At, 0, 1); PG8_STAGE(PG8_SB(0, 0), b2, voffB); PG8_STAGE(PG8_SB(0, 1), b2 + hstepB, voffB); PG8_STAGE(PG8_SA(0, 0), a2, voffA);
;             PG8_WAIT_V(8); PG8_WAIT_L(0); PG8_BAR; PG8_MMA(1, 0, At, B0); PG8_MMA(1, 1, At, B1); PG8_BAR; PG8_SCHED;
;             PG8_LDB(B0, 1, 0); PG8_LDB(B1, 1, 1); PG8_SCHED; PG8_LDA(At, 1, 0); PG8_STAGE(PG8_SA(0, 1), a2 + hstepA, voffA);
;             PG8_WAIT_V(8); PG8_WAIT_L(0); PG8_BAR; PG8_MMA(0, 0, At, B0); PG8_MMA(0, 1, At, B1); PG8_BAR; PG8_SCHED;
	s_mov_b32 m0, s64
	s_nop 3
	ds_read_b128 v[66:69], v145 offset:16384
	ds_read_b128 v[70:73], v145 offset:17408
	ds_read_b128 v[84:87], v145 offset:18432
	ds_read_b128 v[88:91], v145 offset:19456
	ds_read_b128 v[114:117], v145 offset:20480
	ds_read_b128 v[118:121], v145 offset:21504
	ds_read_b128 v[226:229], v145 offset:22528
	ds_read_b128 v[230:233], v145 offset:23552
	global_load_lds_dwordx4 v[26:27], off
	s_mov_b32 m0, s65
	s_nop 0
	global_load_lds_dwordx4 v[28:29], off
	s_mov_b32 m0, s66
	s_nop 0
	global_load_lds_dwordx4 v[24:25], off
	s_mov_b32 m0, s67
	s_nop 0
	global_load_lds_dwordx4 v[18:19], off
	s_mov_b32 m0, s59
	s_nop 0
	global_load_lds_dwordx4 v[20:21], off
	s_mov_b32 m0, s60
	s_nop 0
	global_load_lds_dwordx4 v[22:23], off
	s_waitcnt vmcnt(8)
	s_waitcnt lgkmcnt(0)
	s_barrier
	v_mfma_f32_16x16x32_bf16 v[16:19], v[146:149], v[66:69], v[170:173]
	v_mfma_f32_16x16x32_bf16 v[20:23], v[154:157], v[66:69], v[174:177]
	v_mfma_f32_16x16x32_bf16 v[24:27], v[146:149], v[84:87], v[178:181]
	v_mfma_f32_16x16x32_bf16 v[28:31], v[154:157], v[84:87], v[182:185]
	v_mfma_f32_16x16x32_bf16 v[32:35], v[146:149], v[226:229], v[32:35]
	v_mfma_f32_16x16x32_bf16 v[16:19], v[150:153], v[70:73], v[16:19]
	v_mfma_f32_16x16x32_bf16 v[20:23], v[158:161], v[70:73], v[20:23]
	v_mfma_f32_16x16x32_bf16 v[24:27], v[150:153], v[88:91], v[24:27]
	v_mfma_f32_16x16x32_bf16 v[28:31], v[158:161], v[88:91], v[28:31]
	v_mfma_f32_16x16x32_bf16 v[170:173], v[146:149], v[114:117], v[186:189]
	v_mfma_f32_16x16x32_bf16 v[174:177], v[154:157], v[114:117], v[190:193]
	v_mfma_f32_16x16x32_bf16 v[32:35], v[150:153], v[230:233], v[32:35]
	v_mfma_f32_16x16x32_bf16 v[36:39], v[154:157], v[226:229], v[36:39]
	v_mfma_f32_16x16x32_bf16 v[170:173], v[150:153], v[118:121], v[170:173]
	v_mfma_f32_16x16x32_bf16 v[174:177], v[158:161], v[118:121], v[174:177]
	v_mfma_f32_16x16x32_bf16 v[146:149], v[158:161], v[230:233], v[36:39]
	v_mfma_f32_16x16x32_bf16 v[36:39], v[162:165], v[66:69], v[40:43]
	v_mfma_f32_16x16x32_bf16 v[150:153], v[166:169], v[70:73], v[36:39]
	v_mfma_f32_16x16x32_bf16 v[36:39], v[194:197], v[66:69], v[44:47]
	v_mfma_f32_16x16x32_bf16 v[44:47], v[198:201], v[70:73], v[36:39]
	v_mfma_f32_16x16x32_bf16 v[36:39], v[162:165], v[84:87], v[58:61]
	v_mfma_f32_16x16x32_bf16 v[154:157], v[166:169], v[88:91], v[36:39]
	v_mfma_f32_16x16x32_bf16 v[36:39], v[194:197], v[84:87], v[62:65]
	v_mfma_f32_16x16x32_bf16 v[158:161], v[198:201], v[88:91], v[36:39]
	v_mfma_f32_16x16x32_bf16 v[36:39], v[162:165], v[114:117], v[94:97]
	v_mfma_f32_16x16x32_bf16 v[178:181], v[166:169], v[118:121], v[36:39]
	v_mfma_f32_16x16x32_bf16 v[36:39], v[194:197], v[114:117], v[138:141]
	v_mfma_f32_16x16x32_bf16 v[138:141], v[198:201], v[118:121], v[36:39]
	v_mfma_f32_16x16x32_bf16 v[36:39], v[162:165], v[226:229], v[48:51]
	v_mfma_f32_16x16x32_bf16 v[162:165], v[166:169], v[230:233], v[36:39]
	v_mfma_f32_16x16x32_bf16 v[36:39], v[194:197], v[226:229], v[52:55]
	v_mfma_f32_16x16x32_bf16 v[166:169], v[198:201], v[230:233], v[36:39]
	s_barrier
	ds_read_b128 v[48:51], v247
	ds_read_b128 v[64:67], v247 offset:1024
	ds_read_b128 v[182:185], v247 offset:2048
	ds_read_b128 v[186:189], v247 offset:3072
	ds_read_b128 v[190:193], v246
	ds_read_b128 v[194:197], v246 offset:1024
	ds_read_b128 v[198:201], v246 offset:2048
	ds_read_b128 v[226:229], v246 offset:3072
	s_mov_b32 m0, s55
	ds_read_b128 v[36:39], v145 offset:32768
	ds_read_b128 v[40:43], v145 offset:33792
	ds_read_b128 v[52:55], v145 offset:34816
	ds_read_b128 v[56:59], v145 offset:35840
	ds_read_b128 v[60:63], v145 offset:36864
	ds_read_b128 v[230:233], v145 offset:37888
	ds_read_b128 v[234:237], v145 offset:38912
	ds_read_b128 v[246:249], v145 offset:39936
	global_load_lds_dwordx4 v[12:13], off
	s_mov_b32 m0, s56
	s_nop 0
	global_load_lds_dwordx4 v[14:15], off
	s_waitcnt vmcnt(8)
	s_waitcnt lgkmcnt(0)
	s_barrier
; #define PG8_STAGE(bufoff, gbase, voff) do { _Pragma("unroll") for (int _i = 0; _i < 2; ++_i) \
;         __builtin_amdgcn_global_load_lds((const unsigned*)((const char*)(gbase) + (voff)[_i]), (PG8_LAS unsigned*)(lds + (bufoff) + ldsw + _i * 8192), 16, 0, 0); } while (0)
; #define PG8_LDA(dst, b, h) do { _Pragma("unroll") for (int m = 0; m < 4; ++m) _Pragma("unroll") for (int k = 0; k < 2; ++k) dst[m][k] = *(const PG8_LAS bf16x8*)(lds + PG8_SA(b, h) + aoff + m * 2048 + k * 1024); } while (0)
; #define PG8_MMA(ai, bj, At, Bt) do { __builtin_amdgcn_s_setprio(1); _Pragma("unroll") for (int m = 0; m < 4; ++m) _Pragma("unroll") for (int n = 0; n < 2; ++n) _Pragma("unroll") for (int k = 0; k < 2; ++k) \
;         acc[ai][bj][m][n] = __builtin_amdgcn_mfma_f32_16x16x32_bf16(Bt[n][k], At[m][k], acc[ai][bj][m][n], 0, 0, 0); __builtin_amdgcn_s_setprio(0); } while (0)
; #define PG8_WAIT_V(n) asm volatile("s_waitcnt vmcnt(" #n ")" ::: "memory")
; #define PG8_WAIT_L(n) asm volatile("s_waitcnt lgkmcnt(" #n ")" ::: "memory")
; #define PG8_BAR __builtin_amdgcn_s_barrier()
; #define PG8_SCHED __builtin_amdgcn_sched_barrier(0)
; template <class Epi, class Sched, bool ALIGN_EPI = false, bool SP2 = false>
; __device__ __forceinline__ void gemm_phase(PG8_LAS unsigned char* lds, const Gemm g, const Sched& S, const Epi& E, const int wv0) {
;     ...
;             PG8_WAIT_V(8); PG8_WAIT_L(0); PG8_BAR; PG8_MMA(0, 0, At, B0); PG8_MMA(0, 1, At, B1); PG8_BAR; PG8_SCHED;
;             PG8_LDA(At, 1, 1); PG8_STAGE(PG8_SB(1, 0), b3, voffB); PG8_STAGE(PG8_SB(1, 1), b3 + hstepB, voffB); PG8_STAGE(PG8_SA(1, 0), a3, voffA);
;             PG8_WAIT_V(8); PG8_WAIT_L(0); PG8_BAR; PG8_MMA(1, 0, At, B0); PG8_MMA(1, 1, At, B1); PG8_BAR; PG8_SCHED;
;     ...
;     PG8_WAIT_V(0);
;     if constexpr (!ALIGN_EPI) { if (wr == 0) PG8_BAR; }
;     PG8_BAR;
	v_mfma_f32_16x16x32_bf16 v[12:15], v[48:51], v[36:39], v[98:101]
	v_mfma_f32_16x16x32_bf16 v[120:123], v[64:67], v[40:43], v[12:15]
	v_mfma_f32_16x16x32_bf16 v[12:15], v[182:185], v[36:39], v[102:105]
	v_mfma_f32_16x16x32_bf16 v[116:119], v[186:189], v[40:43], v[12:15]
	v_mfma_f32_16x16x32_bf16 v[12:15], v[48:51], v[52:55], v[106:109]
	v_mfma_f32_16x16x32_bf16 v[104:107], v[64:67], v[56:59], v[12:15]
	v_mfma_f32_16x16x32_bf16 v[12:15], v[182:185], v[52:55], v[110:113]
	v_mfma_f32_16x16x32_bf16 v[100:103], v[186:189], v[56:59], v[12:15]
	v_mfma_f32_16x16x32_bf16 v[12:15], v[48:51], v[60:63], v[238:241]
	v_mfma_f32_16x16x32_bf16 v[88:91], v[64:67], v[230:233], v[12:15]
	v_mfma_f32_16x16x32_bf16 v[12:15], v[182:185], v[60:63], v[242:245]
	v_mfma_f32_16x16x32_bf16 v[84:87], v[186:189], v[230:233], v[12:15]
	v_mfma_f32_16x16x32_bf16 v[12:15], v[48:51], v[234:237], v[124:127]
	v_mfma_f32_16x16x32_bf16 v[72:75], v[64:67], v[246:249], v[12:15]
	v_mfma_f32_16x16x32_bf16 v[12:15], v[182:185], v[234:237], v[130:133]
	v_mfma_f32_16x16x32_bf16 v[68:71], v[186:189], v[246:249], v[12:15]
	v_mfma_f32_16x16x32_bf16 v[12:15], v[190:193], v[36:39], v[134:137]
	v_mfma_f32_16x16x32_bf16 v[124:127], v[194:197], v[40:43], v[12:15]
	v_mfma_f32_16x16x32_bf16 v[12:15], v[198:201], v[36:39], v[206:209]
	v_mfma_f32_16x16x32_bf16 v[112:115], v[226:229], v[40:43], v[12:15]
	v_mfma_f32_16x16x32_bf16 v[12:15], v[190:193], v[52:55], v[210:213]
	v_mfma_f32_16x16x32_bf16 v[108:111], v[194:197], v[56:59], v[12:15]
	v_mfma_f32_16x16x32_bf16 v[12:15], v[198:201], v[52:55], v[214:217]
	v_mfma_f32_16x16x32_bf16 v[96:99], v[226:229], v[56:59], v[12:15]
	v_mfma_f32_16x16x32_bf16 v[12:15], v[190:193], v[60:63], v[76:79]
	v_mfma_f32_16x16x32_bf16 v[92:95], v[194:197], v[230:233], v[12:15]
	v_mfma_f32_16x16x32_bf16 v[12:15], v[198:201], v[60:63], v[80:83]
	v_mfma_f32_16x16x32_bf16 v[80:83], v[226:229], v[230:233], v[12:15]
	v_mfma_f32_16x16x32_bf16 v[12:15], v[190:193], v[234:237], v[218:221]
	v_mfma_f32_16x16x32_bf16 v[76:79], v[194:197], v[246:249], v[12:15]
	v_mfma_f32_16x16x32_bf16 v[12:15], v[198:201], v[234:237], v[222:225]
	v_mfma_f32_16x16x32_bf16 v[56:59], v[226:229], v[246:249], v[12:15]
	s_barrier
	s_mov_b32 m0, s26
	s_nop 3
	ds_read_b128 v[12:15], v145 offset:49152
	ds_read_b128 v[130:133], v145 offset:50176
	ds_read_b128 v[134:137], v145 offset:51200
	ds_read_b128 v[206:209], v145 offset:52224
	ds_read_b128 v[210:213], v145 offset:53248
	ds_read_b128 v[214:217], v145 offset:54272
	ds_read_b128 v[218:221], v145 offset:55296
	ds_read_b128 v[222:225], v145 offset:56320
	global_load_lds_dwordx4 v[2:3], off
	s_mov_b32 m0, s53
	s_nop 0
	global_load_lds_dwordx4 v[4:5], off
	s_mov_b32 m0, s57
	s_nop 0
	global_load_lds_dwordx4 v[8:9], off
	s_mov_b32 m0, s58
	s_nop 0
	global_load_lds_dwordx4 v[10:11], off
	s_mov_b32 m0, s27
	s_nop 0
	global_load_lds_dwordx4 v[0:1], off
	s_mov_b32 m0, s54
	s_nop 0
	global_load_lds_dwordx4 v[6:7], off
	s_waitcnt vmcnt(8)
	s_waitcnt lgkmcnt(0)
	s_barrier
	v_mfma_f32_16x16x32_bf16 v[0:3], v[48:51], v[12:15], v[16:19]
	v_mfma_f32_16x16x32_bf16 v[60:63], v[64:67], v[130:133], v[0:3]
	v_mfma_f32_16x16x32_bf16 v[0:3], v[182:185], v[12:15], v[20:23]
	v_mfma_f32_16x16x32_bf16 v[52:55], v[186:189], v[130:133], v[0:3]
	v_mfma_f32_16x16x32_bf16 v[0:3], v[48:51], v[134:137], v[24:27]
	v_mfma_f32_16x16x32_bf16 v[40:43], v[64:67], v[206:209], v[0:3]
	v_mfma_f32_16x16x32_bf16 v[0:3], v[182:185], v[134:137], v[28:31]
	v_mfma_f32_16x16x32_bf16 v[36:39], v[186:189], v[206:209], v[0:3]
	v_mfma_f32_16x16x32_bf16 v[0:3], v[48:51], v[210:213], v[170:173]
	v_mfma_f32_16x16x32_bf16 v[24:27], v[64:67], v[214:217], v[0:3]
	v_mfma_f32_16x16x32_bf16 v[0:3], v[182:185], v[210:213], v[174:177]
	v_mfma_f32_16x16x32_bf16 v[20:23], v[186:189], v[214:217], v[0:3]
	v_mfma_f32_16x16x32_bf16 v[0:3], v[48:51], v[218:221], v[32:35]
	v_mfma_f32_16x16x32_bf16 v[8:11], v[64:67], v[222:225], v[0:3]
	v_mfma_f32_16x16x32_bf16 v[0:3], v[182:185], v[218:221], v[146:149]
	v_mfma_f32_16x16x32_bf16 v[4:7], v[186:189], v[222:225], v[0:3]
	v_mfma_f32_16x16x32_bf16 v[0:3], v[190:193], v[12:15], v[150:153]
	v_mfma_f32_16x16x32_bf16 v[64:67], v[194:197], v[130:133], v[0:3]
	v_mfma_f32_16x16x32_bf16 v[0:3], v[198:201], v[12:15], v[44:47]
	v_mfma_f32_16x16x32_bf16 v[48:51], v[226:229], v[130:133], v[0:3]
	v_mfma_f32_16x16x32_bf16 v[0:3], v[190:193], v[134:137], v[154:157]
	v_mfma_f32_16x16x32_bf16 v[44:47], v[194:197], v[206:209], v[0:3]
	v_mfma_f32_16x16x32_bf16 v[0:3], v[198:201], v[134:137], v[158:161]
	v_mfma_f32_16x16x32_bf16 v[32:35], v[226:229], v[206:209], v[0:3]
	v_mfma_f32_16x16x32_bf16 v[0:3], v[190:193], v[210:213], v[178:181]
	v_mfma_f32_16x16x32_bf16 v[28:31], v[194:197], v[214:217], v[0:3]
	v_mfma_f32_16x16x32_bf16 v[0:3], v[198:201], v[210:213], v[138:141]
	v_mfma_f32_16x16x32_bf16 v[16:19], v[226:229], v[214:217], v[0:3]
	v_mfma_f32_16x16x32_bf16 v[0:3], v[190:193], v[218:221], v[162:165]
	v_mfma_f32_16x16x32_bf16 v[12:15], v[194:197], v[222:225], v[0:3]
	v_mfma_f32_16x16x32_bf16 v[0:3], v[198:201], v[218:221], v[166:169]
	v_mfma_f32_16x16x32_bf16 v[0:3], v[226:229], v[222:225], v[0:3]
	s_barrier
	s_waitcnt vmcnt(0)
	s_cmpk_gt_u32 s52, 0xff
	s_cbranch_scc1 .LBB0_1301
	s_barrier

; #define PG8_STAGE(bufoff, gbase, voff) do { _Pragma("unroll") for (int _i = 0; _i < 2; ++_i) \
;         __builtin_amdgcn_global_load_lds((const unsigned*)((const char*)(gbase) + (voff)[_i]), (PG8_LAS unsigned*)(lds + (bufoff) + ldsw + _i * 8192), 16, 0, 0); } while (0)
; #define PG8_LDA(dst, b, h) do { _Pragma("unroll") for (int m = 0; m < 4; ++m) _Pragma("unroll") for (int k = 0; k < 2; ++k) dst[m][k] = *(const PG8_LAS bf16x8*)(lds + PG8_SA(b, h) + aoff + m * 2048 + k * 1024); } while (0)
; #define PG8_LDB(dst, b, h) do { _Pragma("unroll") for (int n = 0; n < 2; ++n) _Pragma("unroll") for (int k = 0; k < 2; ++k) dst[n][k] = *(const PG8_LAS bf16x8*)(lds + PG8_SB(b, h) + boff + n * 2048 + k * 1024); } while (0)
; #define PG8_MMA(ai, bj, At, Bt) do { __builtin_amdgcn_s_setprio(1); _Pragma("unroll") for (int m = 0; m < 4; ++m) _Pragma("unroll") for (int n = 0; n < 2; ++n) _Pragma("unroll") for (int k = 0; k < 2; ++k) \
;         acc[ai][bj][m][n] = __builtin_amdgcn_mfma_f32_16x16x32_bf16(Bt[n][k], At[m][k], acc[ai][bj][m][n], 0, 0, 0); __builtin_amdgcn_s_setprio(0); } while (0)
; #define PG8_WAIT_V(n) asm volatile("s_waitcnt vmcnt(" #n ")" ::: "memory")
; #define PG8_WAIT_L(n) asm volatile("s_waitcnt lgkmcnt(" #n ")" ::: "memory")
; #define PG8_BAR __builtin_amdgcn_s_barrier()
; #define PG8_SCHED __builtin_amdgcn_sched_barrier(0)
; template <class Epi, class Sched, bool ALIGN_EPI = false, bool SP2 = false>
; __device__ __forceinline__ void gemm_phase(PG8_LAS unsigned char* lds, const Gemm g, const Sched& S, const Epi& E, const int wv0) {
;     ...
;         PG8_STAGE(PG8_SB(0, 0), cB, voffB); PG8_STAGE(PG8_SB(0, 1), cB + hstepB, voffB); PG8_STAGE(PG8_SA(0, 0), cA, voffA); PG8_STAGE(PG8_SA(0, 1), cA + hstepA, voffA);
;         if (wr == 1) PG8_BAR;
;         PG8_WAIT_V(2); PG8_BAR;
;         PG8_STAGE(PG8_SB(1, 0), cB + kstep, voffB); PG8_STAGE(PG8_SA(1, 0), cA + kstep, voffA); PG8_STAGE(PG8_SB(1, 1), cB + hstepB + kstep, voffB);
;         PG8_WAIT_V(6); PG8_BAR;
;     ...
;             PG8_LDB(B0, 0, 0); PG8_LDB(B1, 0, 1); PG8_SCHED; PG8_LDA(At, 0, 0); PG8_STAGE(PG8_SA(1, 1), a1 + hstepA, voffA);
;             PG8_WAIT_V(8); PG8_WAIT_L(0); PG8_BAR; PG8_MMA(0, 0, At, B0); PG8_MMA(0, 1, At, B1); PG8_BAR; PG8_SCHED;
;             PG8_LDA(At, 0, 1); PG8_STAGE(PG8_SB(0, 0), b2, voffB); PG8_STAGE(PG8_SB(0, 1), b2 + hstepB, voffB); PG8_STAGE(PG8_SA(0, 0), a2, voffA);
.LBB0_1319:
	s_lshl_b32 s50, s50, 5
	s_add_i32 s51, s36, s63
	s_and_b32 s50, s50, 0x60
	v_lshl_add_u64 v[2:3], v[26:27], 0, s[10:11]
	s_mov_b32 m0, s51
	s_add_i32 s53, s51, 0x2000
	s_lshl_b32 s62, s61, 13
	s_lshl_b32 s66, s50, 7
	s_waitcnt vmcnt(2)
	s_barrier
	global_load_lds_dwordx4 v[2:3], off
	v_lshl_add_u64 v[4:5], v[28:29], 0, s[10:11]
	s_mov_b32 m0, s53
	s_add_i32 s52, s59, 0x8000
	s_add_i32 s54, s59, 0xa000
	global_load_lds_dwordx4 v[4:5], off
	v_lshl_add_u64 v[0:1], v[20:21], 0, s[10:11]
	s_mov_b32 m0, s52
	s_add_u32 s64, s24, 0x10080
	global_load_lds_dwordx4 v[0:1], off
	v_lshl_add_u64 v[6:7], v[22:23], 0, s[10:11]
	s_mov_b32 m0, s54
	s_addc_u32 s65, s25, 0
	s_add_i32 s57, s37, s63
	global_load_lds_dwordx4 v[6:7], off
	v_lshl_add_u64 v[8:9], s[64:65], 0, v[128:129]
	s_mov_b32 m0, s57
	s_add_i32 s58, s57, 0x2000
	global_load_lds_dwordx4 v[8:9], off
	v_lshl_add_u64 v[10:11], s[64:65], 0, v[32:33]
	s_mov_b32 m0, s58
	v_lshrrev_b32_e32 v37, 1, v34
	global_load_lds_dwordx4 v[10:11], off
	v_and_b32_e32 v37, 24, v37
	v_and_b32_e32 v35, 15, v34
	v_lshlrev_b32_e32 v38, 1, v37
	v_lshlrev_b32_e32 v34, 2, v34
	v_lshl_or_b32 v36, s61, 6, v35
	v_lshl_or_b32 v35, v35, 6, v38
	v_and_b32_e32 v34, 32, v34
	v_bitop3_b32 v70, v35, s66, v34 bitop3:0xde
	v_add_u32_e32 v127, s48, v70
	s_waitcnt vmcnt(6)
	s_barrier
	v_add_u32_e32 v126, s47, v70
	ds_read_b128 v[38:41], v127
	ds_read_b128 v[42:45], v127 offset:1024
	ds_read_b128 v[46:49], v127 offset:2048
	ds_read_b128 v[50:53], v127 offset:3072
	ds_read_b128 v[54:57], v126
	ds_read_b128 v[58:61], v126 offset:1024
	ds_read_b128 v[62:65], v126 offset:2048
	ds_read_b128 v[66:69], v126 offset:3072
	v_bitop3_b32 v34, v35, s62, v34 bitop3:0xde
	v_add_u32_e32 v143, 0, v34
	v_add_u32_e32 v238, s37, v70
	v_add_u32_e32 v239, s36, v70
	s_add_u32 s66, s22, 0x40080
	s_addc_u32 s67, s23, 0
	s_add_i32 s64, s59, 0xc000
	v_lshl_add_u64 v[34:35], s[66:67], 0, v[16:17]
	s_mov_b32 m0, s64
	s_add_i32 s61, s59, 0xe000
	ds_read_b128 v[70:73], v143
	ds_read_b128 v[74:77], v143 offset:1024
	ds_read_b128 v[78:81], v143 offset:2048
	ds_read_b128 v[82:85], v143 offset:3072
	ds_read_b128 v[86:89], v143 offset:4096
	ds_read_b128 v[90:93], v143 offset:5120
	ds_read_b128 v[94:97], v143 offset:6144
	ds_read_b128 v[98:101], v143 offset:7168
	global_load_lds_dwordx4 v[34:35], off
	v_lshl_add_u64 v[34:35], s[66:67], 0, v[30:31]
	s_mov_b32 m0, s61
	s_nop 0
	global_load_lds_dwordx4 v[34:35], off
	s_waitcnt vmcnt(8)
	s_waitcnt lgkmcnt(0)
	s_barrier
	v_mfma_f32_16x16x32_bf16 v[102:105], v[38:41], v[70:73], 0
	v_mfma_f32_16x16x32_bf16 v[106:109], v[46:49], v[70:73], 0
	v_mfma_f32_16x16x32_bf16 v[110:113], v[38:41], v[78:81], 0
	v_mfma_f32_16x16x32_bf16 v[114:117], v[46:49], v[78:81], 0
	v_mfma_f32_16x16x32_bf16 v[118:121], v[38:41], v[86:89], 0
	v_mfma_f32_16x16x32_bf16 v[122:125], v[46:49], v[86:89], 0
	v_mfma_f32_16x16x32_bf16 v[130:133], v[38:41], v[94:97], 0
	v_mfma_f32_16x16x32_bf16 v[134:137], v[46:49], v[94:97], 0
	v_mfma_f32_16x16x32_bf16 v[102:105], v[42:45], v[74:77], v[102:105]
	v_mfma_f32_16x16x32_bf16 v[106:109], v[50:53], v[74:77], v[106:109]
	v_mfma_f32_16x16x32_bf16 v[110:113], v[42:45], v[82:85], v[110:113]
	v_mfma_f32_16x16x32_bf16 v[114:117], v[50:53], v[82:85], v[114:117]
	v_mfma_f32_16x16x32_bf16 v[118:121], v[42:45], v[90:93], v[118:121]
	v_mfma_f32_16x16x32_bf16 v[122:125], v[50:53], v[90:93], v[122:125]
	v_mfma_f32_16x16x32_bf16 v[130:133], v[42:45], v[98:101], v[130:133]
	v_mfma_f32_16x16x32_bf16 v[134:137], v[50:53], v[98:101], v[134:137]
	v_mfma_f32_16x16x32_bf16 v[138:141], v[54:57], v[70:73], 0
	v_mfma_f32_16x16x32_bf16 v[70:73], v[62:65], v[70:73], 0
	v_mfma_f32_16x16x32_bf16 v[138:141], v[58:61], v[74:77], v[138:141]
	v_mfma_f32_16x16x32_bf16 v[70:73], v[66:69], v[74:77], v[70:73]
	v_mfma_f32_16x16x32_bf16 v[74:77], v[54:57], v[78:81], 0
	v_mfma_f32_16x16x32_bf16 v[78:81], v[62:65], v[78:81], 0
	v_mfma_f32_16x16x32_bf16 v[74:77], v[58:61], v[82:85], v[74:77]
	v_mfma_f32_16x16x32_bf16 v[78:81], v[66:69], v[82:85], v[78:81]
	v_mfma_f32_16x16x32_bf16 v[82:85], v[54:57], v[86:89], 0
	v_mfma_f32_16x16x32_bf16 v[86:89], v[62:65], v[86:89], 0
	v_mfma_f32_16x16x32_bf16 v[82:85], v[58:61], v[90:93], v[82:85]
	v_mfma_f32_16x16x32_bf16 v[86:89], v[66:69], v[90:93], v[86:89]
	v_mfma_f32_16x16x32_bf16 v[90:93], v[54:57], v[94:97], 0
	v_mfma_f32_16x16x32_bf16 v[94:97], v[62:65], v[94:97], 0
	v_mfma_f32_16x16x32_bf16 v[90:93], v[58:61], v[98:101], v[90:93]
	v_mfma_f32_16x16x32_bf16 v[94:97], v[66:69], v[98:101], v[94:97]
	s_barrier
	s_add_i32 s48, s48, s63
	s_add_i32 s62, s48, 0x2000
	v_lshl_add_u64 v[34:35], v[26:27], 0, s[12:13]
	s_mov_b32 m0, s48
	s_add_u32 s66, s24, 0x10100
	ds_read_b128 v[98:101], v143 offset:16384
	ds_read_b128 v[144:147], v143 offset:17408
	ds_read_b128 v[148:151], v143 offset:18432
	ds_read_b128 v[152:155], v143 offset:19456
	ds_read_b128 v[156:159], v143 offset:20480
	ds_read_b128 v[160:163], v143 offset:21504
	ds_read_b128 v[164:167], v143 offset:22528
	ds_read_b128 v[168:171], v143 offset:23552
	global_load_lds_dwordx4 v[34:35], off
	v_lshl_add_u64 v[34:35], v[28:29], 0, s[12:13]
	s_mov_b32 m0, s62
	s_addc_u32 s67, s25, 0
	s_add_i32 s47, s47, s63
	global_load_lds_dwordx4 v[34:35], off
	v_lshl_add_u64 v[34:35], s[66:67], 0, v[128:129]
	s_mov_b32 m0, s47
	s_add_i32 s63, s47, 0x2000
	global_load_lds_dwordx4 v[34:35], off
	v_lshl_add_u64 v[34:35], s[66:67], 0, v[32:33]
	s_mov_b32 m0, s63
	s_nop 0
	global_load_lds_dwordx4 v[34:35], off
	v_lshl_add_u64 v[34:35], v[20:21], 0, s[12:13]
	s_mov_b32 m0, s59
	s_nop 0
	global_load_lds_dwordx4 v[34:35], off
	v_lshl_add_u64 v[34:35], v[22:23], 0, s[12:13]
	s_mov_b32 m0, s60
	s_nop 0
	global_load_lds_dwordx4 v[34:35], off
	s_waitcnt vmcnt(8)
	s_waitcnt lgkmcnt(0)
	s_barrier
; #define PG8_STAGE(bufoff, gbase, voff) do { _Pragma("unroll") for (int _i = 0; _i < 2; ++_i) \
;         __builtin_amdgcn_global_load_lds((const unsigned*)((const char*)(gbase) + (voff)[_i]), (PG8_LAS unsigned*)(lds + (bufoff) + ldsw + _i * 8192), 16, 0, 0); } while (0)
; #define PG8_LDA(dst, b, h) do { _Pragma("unroll") for (int m = 0; m < 4; ++m) _Pragma("unroll") for (int k = 0; k < 2; ++k) dst[m][k] = *(const PG8_LAS bf16x8*)(lds + PG8_SA(b, h) + aoff + m * 2048 + k * 1024); } while (0)
; #define PG8_LDB(dst, b, h) do { _Pragma("unroll") for (int n = 0; n < 2; ++n) _Pragma("unroll") for (int k = 0; k < 2; ++k) dst[n][k] = *(const PG8_LAS bf16x8*)(lds + PG8_SB(b, h) + boff + n * 2048 + k * 1024); } while (0)
; #define PG8_MMA(ai, bj, At, Bt) do { __builtin_amdgcn_s_setprio(1); _Pragma("unroll") for (int m = 0; m < 4; ++m) _Pragma("unroll") for (int n = 0; n < 2; ++n) _Pragma("unroll") for (int k = 0; k < 2; ++k) \
;         acc[ai][bj][m][n] = __builtin_amdgcn_mfma_f32_16x16x32_bf16(Bt[n][k], At[m][k], acc[ai][bj][m][n], 0, 0, 0); __builtin_amdgcn_s_setprio(0); } while (0)
; #define PG8_WAIT_V(n) asm volatile("s_waitcnt vmcnt(" #n ")" ::: "memory")
; #define PG8_WAIT_L(n) asm volatile("s_waitcnt lgkmcnt(" #n ")" ::: "memory")
; #define PG8_BAR __builtin_amdgcn_s_barrier()
; #define PG8_SCHED __builtin_amdgcn_sched_barrier(0)
; template <class Epi, class Sched, bool ALIGN_EPI = false, bool SP2 = false>
; __device__ __forceinline__ void gemm_phase(PG8_LAS unsigned char* lds, const Gemm g, const Sched& S, const Epi& E, const int wv0) {
;     ...
;             PG8_WAIT_V(8); PG8_WAIT_L(0); PG8_BAR; PG8_MMA(1, 0, At, B0); PG8_MMA(1, 1, At, B1); PG8_BAR; PG8_SCHED;
;             PG8_LDB(B0, 1, 0); PG8_LDB(B1, 1, 1); PG8_SCHED; PG8_LDA(At, 1, 0); PG8_STAGE(PG8_SA(0, 1), a2 + hstepA, voffA);
;             PG8_WAIT_V(8); PG8_WAIT_L(0); PG8_BAR; PG8_MMA(0, 0, At, B0); PG8_MMA(0, 1, At, B1); PG8_BAR; PG8_SCHED;
	v_mfma_f32_16x16x32_bf16 v[172:175], v[38:41], v[98:101], 0
	v_mfma_f32_16x16x32_bf16 v[180:183], v[38:41], v[148:151], 0
	v_mfma_f32_16x16x32_bf16 v[188:191], v[38:41], v[156:159], 0
	v_mfma_f32_16x16x32_bf16 v[38:41], v[38:41], v[164:167], 0
	v_mfma_f32_16x16x32_bf16 v[172:175], v[42:45], v[144:147], v[172:175]
	v_mfma_f32_16x16x32_bf16 v[176:179], v[46:49], v[98:101], 0
	v_mfma_f32_16x16x32_bf16 v[180:183], v[42:45], v[152:155], v[180:183]
	v_mfma_f32_16x16x32_bf16 v[184:187], v[46:49], v[148:151], 0
	v_mfma_f32_16x16x32_bf16 v[188:191], v[42:45], v[160:163], v[188:191]
	v_mfma_f32_16x16x32_bf16 v[192:195], v[46:49], v[156:159], 0
	v_mfma_f32_16x16x32_bf16 v[38:41], v[42:45], v[168:171], v[38:41]
	v_mfma_f32_16x16x32_bf16 v[42:45], v[46:49], v[164:167], 0
	v_mfma_f32_16x16x32_bf16 v[176:179], v[50:53], v[144:147], v[176:179]
	v_mfma_f32_16x16x32_bf16 v[184:187], v[50:53], v[152:155], v[184:187]
	v_mfma_f32_16x16x32_bf16 v[192:195], v[50:53], v[160:163], v[192:195]
	v_mfma_f32_16x16x32_bf16 v[42:45], v[50:53], v[168:171], v[42:45]
	v_mfma_f32_16x16x32_bf16 v[46:49], v[54:57], v[98:101], 0
	v_mfma_f32_16x16x32_bf16 v[50:53], v[62:65], v[98:101], 0
	v_mfma_f32_16x16x32_bf16 v[46:49], v[58:61], v[144:147], v[46:49]
	v_mfma_f32_16x16x32_bf16 v[50:53], v[66:69], v[144:147], v[50:53]
	v_mfma_f32_16x16x32_bf16 v[98:101], v[54:57], v[148:151], 0
	v_mfma_f32_16x16x32_bf16 v[144:147], v[62:65], v[148:151], 0
	v_mfma_f32_16x16x32_bf16 v[148:151], v[54:57], v[156:159], 0
	v_mfma_f32_16x16x32_bf16 v[54:57], v[54:57], v[164:167], 0
	v_mfma_f32_16x16x32_bf16 v[98:101], v[58:61], v[152:155], v[98:101]
	v_mfma_f32_16x16x32_bf16 v[144:147], v[66:69], v[152:155], v[144:147]
	v_mfma_f32_16x16x32_bf16 v[148:151], v[58:61], v[160:163], v[148:151]
	v_mfma_f32_16x16x32_bf16 v[152:155], v[62:65], v[156:159], 0
	v_mfma_f32_16x16x32_bf16 v[54:57], v[58:61], v[168:171], v[54:57]
	v_mfma_f32_16x16x32_bf16 v[58:61], v[62:65], v[164:167], 0
	v_mfma_f32_16x16x32_bf16 v[152:155], v[66:69], v[160:163], v[152:155]
	v_mfma_f32_16x16x32_bf16 v[58:61], v[66:69], v[168:171], v[58:61]
	s_barrier
	ds_read_b128 v[62:65], v239
	ds_read_b128 v[66:69], v239 offset:1024
	ds_read_b128 v[156:159], v239 offset:2048
	ds_read_b128 v[160:163], v239 offset:3072
	ds_read_b128 v[164:167], v238
	ds_read_b128 v[168:171], v238 offset:1024
	ds_read_b128 v[196:199], v238 offset:2048
	ds_read_b128 v[200:203], v238 offset:3072
	s_add_u32 s66, s22, 0x40100
	s_addc_u32 s67, s23, 0
	s_mov_b32 m0, s55
	v_lshl_add_u64 v[34:35], s[66:67], 0, v[16:17]
	ds_read_b128 v[206:209], v143 offset:32768
	ds_read_b128 v[210:213], v143 offset:33792
	ds_read_b128 v[214:217], v143 offset:34816
	ds_read_b128 v[218:221], v143 offset:35840
	ds_read_b128 v[222:225], v143 offset:36864
	ds_read_b128 v[226:229], v143 offset:37888
	ds_read_b128 v[230:233], v143 offset:38912
	ds_read_b128 v[234:237], v143 offset:39936
	global_load_lds_dwordx4 v[34:35], off
	v_lshl_add_u64 v[34:35], s[66:67], 0, v[30:31]
	s_mov_b32 m0, s56
	s_nop 0
	global_load_lds_dwordx4 v[34:35], off
	s_waitcnt vmcnt(8)
	s_waitcnt lgkmcnt(0)
	s_barrier
	v_mfma_f32_16x16x32_bf16 v[102:105], v[62:65], v[206:209], v[102:105]
	v_mfma_f32_16x16x32_bf16 v[106:109], v[156:159], v[206:209], v[106:109]
	v_mfma_f32_16x16x32_bf16 v[110:113], v[62:65], v[214:217], v[110:113]
	v_mfma_f32_16x16x32_bf16 v[114:117], v[156:159], v[214:217], v[114:117]
	v_mfma_f32_16x16x32_bf16 v[118:121], v[62:65], v[222:225], v[118:121]
	v_mfma_f32_16x16x32_bf16 v[122:125], v[156:159], v[222:225], v[122:125]
	v_mfma_f32_16x16x32_bf16 v[130:133], v[62:65], v[230:233], v[130:133]
	v_mfma_f32_16x16x32_bf16 v[134:137], v[156:159], v[230:233], v[134:137]
	v_mfma_f32_16x16x32_bf16 v[102:105], v[66:69], v[210:213], v[102:105]
	v_mfma_f32_16x16x32_bf16 v[106:109], v[160:163], v[210:213], v[106:109]
	v_mfma_f32_16x16x32_bf16 v[110:113], v[66:69], v[218:221], v[110:113]
	v_mfma_f32_16x16x32_bf16 v[114:117], v[160:163], v[218:221], v[114:117]
	v_mfma_f32_16x16x32_bf16 v[118:121], v[66:69], v[226:229], v[118:121]
	v_mfma_f32_16x16x32_bf16 v[122:125], v[160:163], v[226:229], v[122:125]
	v_mfma_f32_16x16x32_bf16 v[130:133], v[66:69], v[234:237], v[130:133]
	v_mfma_f32_16x16x32_bf16 v[134:137], v[160:163], v[234:237], v[134:137]
	v_mfma_f32_16x16x32_bf16 v[138:141], v[164:167], v[206:209], v[138:141]
	v_mfma_f32_16x16x32_bf16 v[70:73], v[196:199], v[206:209], v[70:73]
	v_mfma_f32_16x16x32_bf16 v[74:77], v[164:167], v[214:217], v[74:77]
	v_mfma_f32_16x16x32_bf16 v[78:81], v[196:199], v[214:217], v[78:81]
	v_mfma_f32_16x16x32_bf16 v[82:85], v[164:167], v[222:225], v[82:85]
	v_mfma_f32_16x16x32_bf16 v[86:89], v[196:199], v[222:225], v[86:89]
	v_mfma_f32_16x16x32_bf16 v[90:93], v[164:167], v[230:233], v[90:93]
	v_mfma_f32_16x16x32_bf16 v[94:97], v[196:199], v[230:233], v[94:97]
	v_mfma_f32_16x16x32_bf16 v[138:141], v[168:171], v[210:213], v[138:141]
	v_mfma_f32_16x16x32_bf16 v[70:73], v[200:203], v[210:213], v[70:73]
	v_mfma_f32_16x16x32_bf16 v[74:77], v[168:171], v[218:221], v[74:77]
	v_mfma_f32_16x16x32_bf16 v[78:81], v[200:203], v[218:221], v[78:81]
	v_mfma_f32_16x16x32_bf16 v[82:85], v[168:171], v[226:229], v[82:85]
	v_mfma_f32_16x16x32_bf16 v[86:89], v[200:203], v[226:229], v[86:89]
	v_mfma_f32_16x16x32_bf16 v[90:93], v[168:171], v[234:237], v[90:93]
	v_mfma_f32_16x16x32_bf16 v[94:97], v[200:203], v[234:237], v[94:97]
	s_barrier
; #define PG8_STAGE(bufoff, gbase, voff) do { _Pragma("unroll") for (int _i = 0; _i < 2; ++_i) \
;         __builtin_amdgcn_global_load_lds((const unsigned*)((const char*)(gbase) + (voff)[_i]), (PG8_LAS unsigned*)(lds + (bufoff) + ldsw + _i * 8192), 16, 0, 0); } while (0)
; #define PG8_LDA(dst, b, h) do { _Pragma("unroll") for (int m = 0; m < 4; ++m) _Pragma("unroll") for (int k = 0; k < 2; ++k) dst[m][k] = *(const PG8_LAS bf16x8*)(lds + PG8_SA(b, h) + aoff + m * 2048 + k * 1024); } while (0)
; #define PG8_LDB(dst, b, h) do { _Pragma("unroll") for (int n = 0; n < 2; ++n) _Pragma("unroll") for (int k = 0; k < 2; ++k) dst[n][k] = *(const PG8_LAS bf16x8*)(lds + PG8_SB(b, h) + boff + n * 2048 + k * 1024); } while (0)
; #define PG8_MMA(ai, bj, At, Bt) do { __builtin_amdgcn_s_setprio(1); _Pragma("unroll") for (int m = 0; m < 4; ++m) _Pragma("unroll") for (int n = 0; n < 2; ++n) _Pragma("unroll") for (int k = 0; k < 2; ++k) \
;         acc[ai][bj][m][n] = __builtin_amdgcn_mfma_f32_16x16x32_bf16(Bt[n][k], At[m][k], acc[ai][bj][m][n], 0, 0, 0); __builtin_amdgcn_s_setprio(0); } while (0)
; #define PG8_WAIT_V(n) asm volatile("s_waitcnt vmcnt(" #n ")" ::: "memory")
; #define PG8_WAIT_L(n) asm volatile("s_waitcnt lgkmcnt(" #n ")" ::: "memory")
; #define PG8_BAR __builtin_amdgcn_s_barrier()
; #define PG8_SCHED __builtin_amdgcn_sched_barrier(0)
; template <class Epi, class Sched, bool ALIGN_EPI = false, bool SP2 = false>
; __device__ __forceinline__ void gemm_phase(PG8_LAS unsigned char* lds, const Gemm g, const Sched& S, const Epi& E, const int wv0) {
;     ...
;             PG8_LDB(B0, 0, 0); PG8_LDB(B1, 0, 1); PG8_SCHED; PG8_LDA(At, 0, 0); PG8_STAGE(PG8_SA(1, 1), a1 + hstepA, voffA);
;             PG8_WAIT_V(8); PG8_WAIT_L(0); PG8_BAR; PG8_MMA(0, 0, At, B0); PG8_MMA(0, 1, At, B1); PG8_BAR; PG8_SCHED;
;     ...
;             PG8_LDA(At, 1, 1); PG8_STAGE(PG8_SB(1, 0), b3, voffB); PG8_STAGE(PG8_SB(1, 1), b3 + hstepB, voffB); PG8_STAGE(PG8_SA(1, 0), a3, voffA);
;             PG8_WAIT_V(8); PG8_WAIT_L(0); PG8_BAR; PG8_MMA(1, 0, At, B0); PG8_MMA(1, 1, At, B1); PG8_BAR; PG8_SCHED;
	s_mov_b32 m0, s51
	v_lshl_add_u64 v[34:35], v[26:27], 0, s[14:15]
	s_add_u32 s24, s24, 0x10180
	ds_read_b128 v[206:209], v143 offset:49152
	ds_read_b128 v[210:213], v143 offset:50176
	ds_read_b128 v[214:217], v143 offset:51200
	ds_read_b128 v[218:221], v143 offset:52224
	ds_read_b128 v[222:225], v143 offset:53248
	ds_read_b128 v[226:229], v143 offset:54272
	ds_read_b128 v[230:233], v143 offset:55296
	ds_read_b128 v[234:237], v143 offset:56320
	global_load_lds_dwordx4 v[34:35], off
	v_lshl_add_u64 v[34:35], v[28:29], 0, s[14:15]
	s_mov_b32 m0, s53
	s_addc_u32 s25, s25, 0
	global_load_lds_dwordx4 v[34:35], off
	v_lshl_add_u64 v[34:35], s[24:25], 0, v[128:129]
	s_mov_b32 m0, s57
	v_lshl_add_u64 v[32:33], s[24:25], 0, v[32:33]
	global_load_lds_dwordx4 v[34:35], off
	s_mov_b32 m0, s58
	s_nop 0
	global_load_lds_dwordx4 v[32:33], off
	v_lshl_add_u64 v[32:33], v[20:21], 0, s[14:15]
	s_mov_b32 m0, s52
	s_nop 0
	global_load_lds_dwordx4 v[32:33], off
	v_lshl_add_u64 v[32:33], v[22:23], 0, s[14:15]
	s_mov_b32 m0, s54
	s_nop 0
	global_load_lds_dwordx4 v[32:33], off
	s_waitcnt vmcnt(8)
	s_waitcnt lgkmcnt(0)
	s_barrier
	v_mfma_f32_16x16x32_bf16 v[32:35], v[62:65], v[206:209], v[172:175]
	v_mfma_f32_16x16x32_bf16 v[172:175], v[156:159], v[206:209], v[176:179]
	v_mfma_f32_16x16x32_bf16 v[176:179], v[62:65], v[214:217], v[180:183]
	v_mfma_f32_16x16x32_bf16 v[180:183], v[156:159], v[214:217], v[184:187]
	v_mfma_f32_16x16x32_bf16 v[184:187], v[62:65], v[222:225], v[188:191]
	v_mfma_f32_16x16x32_bf16 v[188:191], v[156:159], v[222:225], v[192:195]
	v_mfma_f32_16x16x32_bf16 v[38:41], v[62:65], v[230:233], v[38:41]
	v_mfma_f32_16x16x32_bf16 v[42:45], v[156:159], v[230:233], v[42:45]
	v_mfma_f32_16x16x32_bf16 v[32:35], v[66:69], v[210:213], v[32:35]
	v_mfma_f32_16x16x32_bf16 v[172:175], v[160:163], v[210:213], v[172:175]
	v_mfma_f32_16x16x32_bf16 v[176:179], v[66:69], v[218:221], v[176:179]
	v_mfma_f32_16x16x32_bf16 v[180:183], v[160:163], v[218:221], v[180:183]
	v_mfma_f32_16x16x32_bf16 v[184:187], v[66:69], v[226:229], v[184:187]
	v_mfma_f32_16x16x32_bf16 v[188:191], v[160:163], v[226:229], v[188:191]
	v_mfma_f32_16x16x32_bf16 v[38:41], v[66:69], v[234:237], v[38:41]
	v_mfma_f32_16x16x32_bf16 v[42:45], v[160:163], v[234:237], v[42:45]
	v_mfma_f32_16x16x32_bf16 v[46:49], v[164:167], v[206:209], v[46:49]
	v_mfma_f32_16x16x32_bf16 v[50:53], v[196:199], v[206:209], v[50:53]
	v_mfma_f32_16x16x32_bf16 v[62:65], v[164:167], v[214:217], v[98:101]
	v_mfma_f32_16x16x32_bf16 v[66:69], v[196:199], v[214:217], v[144:147]
	v_mfma_f32_16x16x32_bf16 v[98:101], v[164:167], v[222:225], v[148:151]
	v_mfma_f32_16x16x32_bf16 v[144:147], v[196:199], v[222:225], v[152:155]
	v_mfma_f32_16x16x32_bf16 v[54:57], v[164:167], v[230:233], v[54:57]
	v_mfma_f32_16x16x32_bf16 v[58:61], v[196:199], v[230:233], v[58:61]
	v_mfma_f32_16x16x32_bf16 v[46:49], v[168:171], v[210:213], v[46:49]
	v_mfma_f32_16x16x32_bf16 v[50:53], v[200:203], v[210:213], v[50:53]
	v_mfma_f32_16x16x32_bf16 v[62:65], v[168:171], v[218:221], v[62:65]
	v_mfma_f32_16x16x32_bf16 v[66:69], v[200:203], v[218:221], v[66:69]
	v_mfma_f32_16x16x32_bf16 v[98:101], v[168:171], v[226:229], v[98:101]
	v_mfma_f32_16x16x32_bf16 v[144:147], v[200:203], v[226:229], v[144:147]
	v_mfma_f32_16x16x32_bf16 v[54:57], v[168:171], v[234:237], v[54:57]
	v_mfma_f32_16x16x32_bf16 v[58:61], v[200:203], v[234:237], v[58:61]
	s_barrier
	ds_read_b128 v[148:151], v127
	ds_read_b128 v[152:155], v127 offset:1024
	ds_read_b128 v[156:159], v127 offset:2048
	ds_read_b128 v[160:163], v127 offset:3072
	ds_read_b128 v[164:167], v126
	ds_read_b128 v[168:171], v126 offset:1024
	ds_read_b128 v[192:195], v126 offset:2048
	ds_read_b128 v[196:199], v126 offset:3072
	s_add_u32 s22, s22, 0x40180
	s_addc_u32 s23, s23, 0
	s_mov_b32 m0, s64
	v_lshl_add_u64 v[16:17], s[22:23], 0, v[16:17]
	ds_read_b128 v[200:203], v143
	ds_read_b128 v[206:209], v143 offset:1024
	ds_read_b128 v[210:213], v143 offset:2048
	ds_read_b128 v[214:217], v143 offset:3072
	ds_read_b128 v[218:221], v143 offset:4096
	ds_read_b128 v[222:225], v143 offset:5120
	ds_read_b128 v[226:229], v143 offset:6144
	ds_read_b128 v[230:233], v143 offset:7168
	global_load_lds_dwordx4 v[16:17], off
	v_lshl_add_u64 v[16:17], s[22:23], 0, v[30:31]
	s_mov_b32 m0, s61
	s_nop 0
	global_load_lds_dwordx4 v[16:17], off
	s_waitcnt vmcnt(8)
	s_waitcnt lgkmcnt(0)
	s_barrier
	v_mfma_f32_16x16x32_bf16 v[102:105], v[148:151], v[200:203], v[102:105]
	v_mfma_f32_16x16x32_bf16 v[106:109], v[156:159], v[200:203], v[106:109]
	v_mfma_f32_16x16x32_bf16 v[110:113], v[148:151], v[210:213], v[110:113]
	v_mfma_f32_16x16x32_bf16 v[114:117], v[156:159], v[210:213], v[114:117]
	v_mfma_f32_16x16x32_bf16 v[118:121], v[148:151], v[218:221], v[118:121]
	v_mfma_f32_16x16x32_bf16 v[122:125], v[156:159], v[218:221], v[122:125]
	v_mfma_f32_16x16x32_bf16 v[130:133], v[148:151], v[226:229], v[130:133]
	v_mfma_f32_16x16x32_bf16 v[134:137], v[156:159], v[226:229], v[134:137]
	v_mfma_f32_16x16x32_bf16 v[102:105], v[152:155], v[206:209], v[102:105]
	v_mfma_f32_16x16x32_bf16 v[106:109], v[160:163], v[206:209], v[106:109]
	v_mfma_f32_16x16x32_bf16 v[110:113], v[152:155], v[214:217], v[110:113]
	v_mfma_f32_16x16x32_bf16 v[114:117], v[160:163], v[214:217], v[114:117]
	v_mfma_f32_16x16x32_bf16 v[118:121], v[152:155], v[222:225], v[118:121]
	v_mfma_f32_16x16x32_bf16 v[122:125], v[160:163], v[222:225], v[122:125]
	v_mfma_f32_16x16x32_bf16 v[130:133], v[152:155], v[230:233], v[130:133]
	v_mfma_f32_16x16x32_bf16 v[134:137], v[160:163], v[230:233], v[134:137]
	v_mfma_f32_16x16x32_bf16 v[138:141], v[164:167], v[200:203], v[138:141]
	v_mfma_f32_16x16x32_bf16 v[70:73], v[192:195], v[200:203], v[70:73]
	v_mfma_f32_16x16x32_bf16 v[74:77], v[164:167], v[210:213], v[74:77]
	v_mfma_f32_16x16x32_bf16 v[78:81], v[192:195], v[210:213], v[78:81]
	v_mfma_f32_16x16x32_bf16 v[82:85], v[164:167], v[218:221], v[82:85]
	v_mfma_f32_16x16x32_bf16 v[86:89], v[192:195], v[218:221], v[86:89]
	v_mfma_f32_16x16x32_bf16 v[90:93], v[164:167], v[226:229], v[90:93]
	v_mfma_f32_16x16x32_bf16 v[94:97], v[192:195], v[226:229], v[94:97]
	v_mfma_f32_16x16x32_bf16 v[138:141], v[168:171], v[206:209], v[138:141]
	v_mfma_f32_16x16x32_bf16 v[70:73], v[196:199], v[206:209], v[70:73]
	v_mfma_f32_16x16x32_bf16 v[74:77], v[168:171], v[214:217], v[74:77]
	v_mfma_f32_16x16x32_bf16 v[78:81], v[196:199], v[214:217], v[78:81]
	v_mfma_f32_16x16x32_bf16 v[82:85], v[168:171], v[222:225], v[82:85]
	v_mfma_f32_16x16x32_bf16 v[86:89], v[196:199], v[222:225], v[86:89]
	v_mfma_f32_16x16x32_bf16 v[90:93], v[168:171], v[230:233], v[90:93]
	v_mfma_f32_16x16x32_bf16 v[94:97], v[196:199], v[230:233], v[94:97]
	s_barrier
; #define PG8_STAGE(bufoff, gbase, voff) do { _Pragma("unroll") for (int _i = 0; _i < 2; ++_i) \
;         __builtin_amdgcn_global_load_lds((const unsigned*)((const char*)(gbase) + (voff)[_i]), (PG8_LAS unsigned*)(lds + (bufoff) + ldsw + _i * 8192), 16, 0, 0); } while (0)
; #define PG8_LDA(dst, b, h) do { _Pragma("unroll") for (int m = 0; m < 4; ++m) _Pragma("unroll") for (int k = 0; k < 2; ++k) dst[m][k] = *(const PG8_LAS bf16x8*)(lds + PG8_SA(b, h) + aoff + m * 2048 + k * 1024); } while (0)
; #define PG8_LDB(dst, b, h) do { _Pragma("unroll") for (int n = 0; n < 2; ++n) _Pragma("unroll") for (int k = 0; k < 2; ++k) dst[n][k] = *(const PG8_LAS bf16x8*)(lds + PG8_SB(b, h) + boff + n * 2048 + k * 1024); } while (0)
; #define PG8_MMA(ai, bj, At, Bt) do { __builtin_amdgcn_s_setprio(1); _Pragma("unroll") for (int m = 0; m < 4; ++m) _Pragma("unroll") for (int n = 0; n < 2; ++n) _Pragma("unroll") for (int k = 0; k < 2; ++k) \
;         acc[ai][bj][m][n] = __builtin_amdgcn_mfma_f32_16x16x32_bf16(Bt[n][k], At[m][k], acc[ai][bj][m][n], 0, 0, 0); __builtin_amdgcn_s_setprio(0); } while (0)
; #define PG8_WAIT_V(n) asm volatile("s_waitcnt vmcnt(" #n ")" ::: "memory")
; #define PG8_WAIT_L(n) asm volatile("s_waitcnt lgkmcnt(" #n ")" ::: "memory")
; #define PG8_BAR __builtin_amdgcn_s_barrier()
; #define PG8_SCHED __builtin_amdgcn_sched_barrier(0)
; template <class Epi, class Sched, bool ALIGN_EPI = false, bool SP2 = false>
; __device__ __forceinline__ void gemm_phase(PG8_LAS unsigned char* lds, const Gemm g, const Sched& S, const Epi& E, const int wv0) {
;     ...
;             PG8_LDA(At, 0, 1); PG8_STAGE(PG8_SB(0, 0), b2, voffB); PG8_STAGE(PG8_SB(0, 1), b2 + hstepB, voffB); PG8_STAGE(PG8_SA(0, 0), a2, voffA);
;             PG8_WAIT_V(8); PG8_WAIT_L(0); PG8_BAR; PG8_MMA(1, 0, At, B0); PG8_MMA(1, 1, At, B1); PG8_BAR; PG8_SCHED;
;             PG8_LDB(B0, 1, 0); PG8_LDB(B1, 1, 1); PG8_SCHED; PG8_LDA(At, 1, 0); PG8_STAGE(PG8_SA(0, 1), a2 + hstepA, voffA);
;             PG8_WAIT_V(8); PG8_WAIT_L(0); PG8_BAR; PG8_MMA(0, 0, At, B0); PG8_MMA(0, 1, At, B1); PG8_BAR; PG8_SCHED;
	s_mov_b32 m0, s48
	ds_read_b128 v[200:203], v143 offset:16384
	ds_read_b128 v[206:209], v143 offset:17408
	ds_read_b128 v[210:213], v143 offset:18432
	ds_read_b128 v[214:217], v143 offset:19456
	ds_read_b128 v[218:221], v143 offset:20480
	ds_read_b128 v[222:225], v143 offset:21504
	ds_read_b128 v[226:229], v143 offset:22528
	ds_read_b128 v[230:233], v143 offset:23552
	global_load_lds_dwordx4 v[26:27], off
	s_mov_b32 m0, s62
	s_nop 0
	global_load_lds_dwordx4 v[28:29], off
	s_mov_b32 m0, s47
	s_nop 0
	global_load_lds_dwordx4 v[24:25], off
	s_mov_b32 m0, s63
	s_nop 0
	global_load_lds_dwordx4 v[18:19], off
	s_mov_b32 m0, s59
	s_nop 0
	global_load_lds_dwordx4 v[20:21], off
	s_mov_b32 m0, s60
	s_nop 0
	global_load_lds_dwordx4 v[22:23], off
	s_waitcnt vmcnt(8)
	s_waitcnt lgkmcnt(0)
	s_barrier
	v_mfma_f32_16x16x32_bf16 v[16:19], v[148:151], v[200:203], v[32:35]
	v_mfma_f32_16x16x32_bf16 v[20:23], v[156:159], v[200:203], v[172:175]
	v_mfma_f32_16x16x32_bf16 v[24:27], v[148:151], v[210:213], v[176:179]
	v_mfma_f32_16x16x32_bf16 v[28:31], v[156:159], v[210:213], v[180:183]
	v_mfma_f32_16x16x32_bf16 v[32:35], v[148:151], v[218:221], v[184:187]
	v_mfma_f32_16x16x32_bf16 v[172:175], v[156:159], v[218:221], v[188:191]
	v_mfma_f32_16x16x32_bf16 v[38:41], v[148:151], v[226:229], v[38:41]
	v_mfma_f32_16x16x32_bf16 v[42:45], v[156:159], v[226:229], v[42:45]
	v_mfma_f32_16x16x32_bf16 v[16:19], v[152:155], v[206:209], v[16:19]
	v_mfma_f32_16x16x32_bf16 v[20:23], v[160:163], v[206:209], v[20:23]
	v_mfma_f32_16x16x32_bf16 v[24:27], v[152:155], v[214:217], v[24:27]
	v_mfma_f32_16x16x32_bf16 v[28:31], v[160:163], v[214:217], v[28:31]
	v_mfma_f32_16x16x32_bf16 v[32:35], v[152:155], v[222:225], v[32:35]
	v_mfma_f32_16x16x32_bf16 v[172:175], v[160:163], v[222:225], v[172:175]
	v_mfma_f32_16x16x32_bf16 v[38:41], v[152:155], v[230:233], v[38:41]
	v_mfma_f32_16x16x32_bf16 v[42:45], v[160:163], v[230:233], v[42:45]
	v_mfma_f32_16x16x32_bf16 v[46:49], v[164:167], v[200:203], v[46:49]
	v_mfma_f32_16x16x32_bf16 v[50:53], v[192:195], v[200:203], v[50:53]
	v_mfma_f32_16x16x32_bf16 v[62:65], v[164:167], v[210:213], v[62:65]
	v_mfma_f32_16x16x32_bf16 v[66:69], v[192:195], v[210:213], v[66:69]
	v_mfma_f32_16x16x32_bf16 v[98:101], v[164:167], v[218:221], v[98:101]
	v_mfma_f32_16x16x32_bf16 v[144:147], v[192:195], v[218:221], v[144:147]
	v_mfma_f32_16x16x32_bf16 v[54:57], v[164:167], v[226:229], v[54:57]
	v_mfma_f32_16x16x32_bf16 v[58:61], v[192:195], v[226:229], v[58:61]
	v_mfma_f32_16x16x32_bf16 v[46:49], v[168:171], v[206:209], v[46:49]
	v_mfma_f32_16x16x32_bf16 v[50:53], v[196:199], v[206:209], v[50:53]
	v_mfma_f32_16x16x32_bf16 v[62:65], v[168:171], v[214:217], v[62:65]
	v_mfma_f32_16x16x32_bf16 v[66:69], v[196:199], v[214:217], v[66:69]
	v_mfma_f32_16x16x32_bf16 v[98:101], v[168:171], v[222:225], v[98:101]
	v_mfma_f32_16x16x32_bf16 v[144:147], v[196:199], v[222:225], v[144:147]
	v_mfma_f32_16x16x32_bf16 v[54:57], v[168:171], v[230:233], v[54:57]
	v_mfma_f32_16x16x32_bf16 v[58:61], v[196:199], v[230:233], v[58:61]
	s_barrier
	ds_read_b128 v[148:151], v239
	ds_read_b128 v[152:155], v239 offset:1024
	ds_read_b128 v[156:159], v239 offset:2048
	ds_read_b128 v[160:163], v239 offset:3072
	ds_read_b128 v[164:167], v238
	ds_read_b128 v[168:171], v238 offset:1024
	ds_read_b128 v[176:179], v238 offset:2048
	ds_read_b128 v[180:183], v238 offset:3072
	s_mov_b32 m0, s55
	ds_read_b128 v[184:187], v143 offset:32768
	ds_read_b128 v[188:191], v143 offset:33792
	ds_read_b128 v[192:195], v143 offset:34816
	ds_read_b128 v[196:199], v143 offset:35840
	ds_read_b128 v[200:203], v143 offset:36864
	ds_read_b128 v[206:209], v143 offset:37888
	ds_read_b128 v[210:213], v143 offset:38912
	ds_read_b128 v[214:217], v143 offset:39936
	global_load_lds_dwordx4 v[12:13], off
	s_mov_b32 m0, s56
	s_nop 0
	global_load_lds_dwordx4 v[14:15], off
	s_waitcnt vmcnt(8)
	s_waitcnt lgkmcnt(0)
	s_barrier
	v_mfma_f32_16x16x32_bf16 v[12:15], v[148:151], v[184:187], v[102:105]
	v_mfma_f32_16x16x32_bf16 v[102:105], v[152:155], v[188:191], v[12:15]
	v_mfma_f32_16x16x32_bf16 v[12:15], v[156:159], v[184:187], v[106:109]
	v_mfma_f32_16x16x32_bf16 v[106:109], v[160:163], v[188:191], v[12:15]
	v_mfma_f32_16x16x32_bf16 v[12:15], v[148:151], v[192:195], v[110:113]
	v_mfma_f32_16x16x32_bf16 v[110:113], v[152:155], v[196:199], v[12:15]
	v_mfma_f32_16x16x32_bf16 v[12:15], v[156:159], v[192:195], v[114:117]
	v_mfma_f32_16x16x32_bf16 v[114:117], v[160:163], v[196:199], v[12:15]
	v_mfma_f32_16x16x32_bf16 v[12:15], v[148:151], v[200:203], v[118:121]
	v_mfma_f32_16x16x32_bf16 v[118:121], v[152:155], v[206:209], v[12:15]
	v_mfma_f32_16x16x32_bf16 v[12:15], v[156:159], v[200:203], v[122:125]
	v_mfma_f32_16x16x32_bf16 v[122:125], v[160:163], v[206:209], v[12:15]
	v_mfma_f32_16x16x32_bf16 v[12:15], v[148:151], v[210:213], v[130:133]
	v_mfma_f32_16x16x32_bf16 v[130:133], v[152:155], v[214:217], v[12:15]
	v_mfma_f32_16x16x32_bf16 v[12:15], v[156:159], v[210:213], v[134:137]
	v_mfma_f32_16x16x32_bf16 v[134:137], v[160:163], v[214:217], v[12:15]
	v_mfma_f32_16x16x32_bf16 v[12:15], v[164:167], v[184:187], v[138:141]
	v_mfma_f32_16x16x32_bf16 v[138:141], v[168:171], v[188:191], v[12:15]
	v_mfma_f32_16x16x32_bf16 v[12:15], v[176:179], v[184:187], v[70:73]
	v_mfma_f32_16x16x32_bf16 v[70:73], v[180:183], v[188:191], v[12:15]
	v_mfma_f32_16x16x32_bf16 v[12:15], v[164:167], v[192:195], v[74:77]
	v_mfma_f32_16x16x32_bf16 v[74:77], v[168:171], v[196:199], v[12:15]
	v_mfma_f32_16x16x32_bf16 v[12:15], v[176:179], v[192:195], v[78:81]
	v_mfma_f32_16x16x32_bf16 v[78:81], v[180:183], v[196:199], v[12:15]
	v_mfma_f32_16x16x32_bf16 v[12:15], v[164:167], v[200:203], v[82:85]
	v_mfma_f32_16x16x32_bf16 v[82:85], v[168:171], v[206:209], v[12:15]
	v_mfma_f32_16x16x32_bf16 v[12:15], v[176:179], v[200:203], v[86:89]
	v_mfma_f32_16x16x32_bf16 v[86:89], v[180:183], v[206:209], v[12:15]
	v_mfma_f32_16x16x32_bf16 v[12:15], v[164:167], v[210:213], v[90:93]
	v_mfma_f32_16x16x32_bf16 v[90:93], v[168:171], v[214:217], v[12:15]
	v_mfma_f32_16x16x32_bf16 v[12:15], v[176:179], v[210:213], v[94:97]
	v_mfma_f32_16x16x32_bf16 v[94:97], v[180:183], v[214:217], v[12:15]
	s_barrier
; #define PG8_STAGE(bufoff, gbase, voff) do { _Pragma("unroll") for (int _i = 0; _i < 2; ++_i) \
;         __builtin_amdgcn_global_load_lds((const unsigned*)((const char*)(gbase) + (voff)[_i]), (PG8_LAS unsigned*)(lds + (bufoff) + ldsw + _i * 8192), 16, 0, 0); } while (0)
; #define PG8_LDA(dst, b, h) do { _Pragma("unroll") for (int m = 0; m < 4; ++m) _Pragma("unroll") for (int k = 0; k < 2; ++k) dst[m][k] = *(const PG8_LAS bf16x8*)(lds + PG8_SA(b, h) + aoff + m * 2048 + k * 1024); } while (0)
; #define PG8_MMA(ai, bj, At, Bt) do { __builtin_amdgcn_s_setprio(1); _Pragma("unroll") for (int m = 0; m < 4; ++m) _Pragma("unroll") for (int n = 0; n < 2; ++n) _Pragma("unroll") for (int k = 0; k < 2; ++k) \
;         acc[ai][bj][m][n] = __builtin_amdgcn_mfma_f32_16x16x32_bf16(Bt[n][k], At[m][k], acc[ai][bj][m][n], 0, 0, 0); __builtin_amdgcn_s_setprio(0); } while (0)
; #define PG8_WAIT_V(n) asm volatile("s_waitcnt vmcnt(" #n ")" ::: "memory")
; #define PG8_WAIT_L(n) asm volatile("s_waitcnt lgkmcnt(" #n ")" ::: "memory")
; #define PG8_BAR __builtin_amdgcn_s_barrier()
; #define PG8_SCHED __builtin_amdgcn_sched_barrier(0)
; template <class Epi, class Sched, bool ALIGN_EPI = false, bool SP2 = false>
; __device__ __forceinline__ void gemm_phase(PG8_LAS unsigned char* lds, const Gemm g, const Sched& S, const Epi& E, const int wv0) {
;     ...
;             PG8_LDA(At, 1, 1); PG8_STAGE(PG8_SB(1, 0), b3, voffB); PG8_STAGE(PG8_SB(1, 1), b3 + hstepB, voffB); PG8_STAGE(PG8_SA(1, 0), a3, voffA);
;             PG8_WAIT_V(8); PG8_WAIT_L(0); PG8_BAR; PG8_MMA(1, 0, At, B0); PG8_MMA(1, 1, At, B1); PG8_BAR; PG8_SCHED;
	s_mov_b32 m0, s51
	ds_read_b128 v[184:187], v143 offset:49152
	ds_read_b128 v[188:191], v143 offset:50176
	ds_read_b128 v[192:195], v143 offset:51200
	ds_read_b128 v[196:199], v143 offset:52224
	ds_read_b128 v[200:203], v143 offset:53248
	ds_read_b128 v[206:209], v143 offset:54272
	ds_read_b128 v[210:213], v143 offset:55296
	ds_read_b128 v[214:217], v143 offset:56320
	global_load_lds_dwordx4 v[2:3], off
	s_mov_b32 m0, s53
	s_nop 0
	global_load_lds_dwordx4 v[4:5], off
	s_mov_b32 m0, s57
	s_nop 0
	global_load_lds_dwordx4 v[8:9], off
	s_mov_b32 m0, s58
	s_nop 0
	global_load_lds_dwordx4 v[10:11], off
	s_mov_b32 m0, s52
	s_nop 0
	global_load_lds_dwordx4 v[0:1], off
	s_mov_b32 m0, s54
	s_nop 0
	global_load_lds_dwordx4 v[6:7], off
	s_waitcnt vmcnt(8)
	s_waitcnt lgkmcnt(0)
	s_barrier
	v_mfma_f32_16x16x32_bf16 v[0:3], v[148:151], v[184:187], v[16:19]
	v_mfma_f32_16x16x32_bf16 v[218:221], v[152:155], v[188:191], v[0:3]
	v_mfma_f32_16x16x32_bf16 v[0:3], v[156:159], v[184:187], v[20:23]
	v_mfma_f32_16x16x32_bf16 v[222:225], v[160:163], v[188:191], v[0:3]
	v_mfma_f32_16x16x32_bf16 v[0:3], v[148:151], v[192:195], v[24:27]
	v_mfma_f32_16x16x32_bf16 v[226:229], v[152:155], v[196:199], v[0:3]
	v_mfma_f32_16x16x32_bf16 v[0:3], v[156:159], v[192:195], v[28:31]
	v_mfma_f32_16x16x32_bf16 v[230:233], v[160:163], v[196:199], v[0:3]
	v_mfma_f32_16x16x32_bf16 v[0:3], v[148:151], v[200:203], v[32:35]
	v_mfma_f32_16x16x32_bf16 v[28:31], v[152:155], v[206:209], v[0:3]
	v_mfma_f32_16x16x32_bf16 v[0:3], v[156:159], v[200:203], v[172:175]
	v_mfma_f32_16x16x32_bf16 v[20:23], v[160:163], v[206:209], v[0:3]
	v_mfma_f32_16x16x32_bf16 v[0:3], v[148:151], v[210:213], v[38:41]
	v_mfma_f32_16x16x32_bf16 v[12:15], v[152:155], v[214:217], v[0:3]
	v_mfma_f32_16x16x32_bf16 v[0:3], v[156:159], v[210:213], v[42:45]
	v_mfma_f32_16x16x32_bf16 v[4:7], v[160:163], v[214:217], v[0:3]
	v_mfma_f32_16x16x32_bf16 v[0:3], v[164:167], v[184:187], v[46:49]
	v_mfma_f32_16x16x32_bf16 v[38:41], v[168:171], v[188:191], v[0:3]
	v_mfma_f32_16x16x32_bf16 v[0:3], v[176:179], v[184:187], v[50:53]
	v_mfma_f32_16x16x32_bf16 v[42:45], v[180:183], v[188:191], v[0:3]
	v_mfma_f32_16x16x32_bf16 v[0:3], v[164:167], v[192:195], v[62:65]
	v_mfma_f32_16x16x32_bf16 v[46:49], v[168:171], v[196:199], v[0:3]
	v_mfma_f32_16x16x32_bf16 v[0:3], v[176:179], v[192:195], v[66:69]
	v_mfma_f32_16x16x32_bf16 v[32:35], v[180:183], v[196:199], v[0:3]
	v_mfma_f32_16x16x32_bf16 v[0:3], v[164:167], v[200:203], v[98:101]
	v_mfma_f32_16x16x32_bf16 v[24:27], v[168:171], v[206:209], v[0:3]
	v_mfma_f32_16x16x32_bf16 v[0:3], v[176:179], v[200:203], v[144:147]
	v_mfma_f32_16x16x32_bf16 v[16:19], v[180:183], v[206:209], v[0:3]
	v_mfma_f32_16x16x32_bf16 v[0:3], v[164:167], v[210:213], v[54:57]
	v_mfma_f32_16x16x32_bf16 v[8:11], v[168:171], v[214:217], v[0:3]
	v_mfma_f32_16x16x32_bf16 v[0:3], v[176:179], v[210:213], v[58:61]
	v_mfma_f32_16x16x32_bf16 v[0:3], v[180:183], v[214:217], v[0:3]
	s_barrier
; __device__ __forceinline__ unsigned cvtpk(float lo, float hi) { unsigned r; asm volatile("v_cvt_pk_bf16_f32 %0, %1, %2" : "=v"(r) : "v"(lo), "v"(hi)); return r; }
;     __device__ __forceinline__ void operator()(const f32x4 (&acc)[2][2][4][2], const Unit& u, int wr, int wc, int fr, int fq) const {
;         const int row0 = u.pm * BM + wr * 64 + fr; const int col0 = u.pn * BM + wc * 32 + 8 * fq;
; #pragma unroll
;         for (int ai = 0; ai < 2; ++ai)
; #pragma unroll
;             for (int m = 0; m < 4; ++m) { bf16* rowp = O + (size_t)(row0 + ai * HALF + m * 16) * ldc + col0;
; #pragma unroll
;                 for (int bj = 0; bj < 2; ++bj) { const f32x4 v0 = acc[ai][bj][m][0], v1 = acc[ai][bj][m][1];
;                     u32x4 w; w.x = cvtpk(v0[0], v0[1]); w.y = cvtpk(v0[2], v0[3]); w.z = cvtpk(v1[0], v1[1]); w.w = cvtpk(v1[2], v1[3]);
;                     *(u32x4*)(rowp + bj * HALF) = w; } }
	v_add_u32_e32 v54, s26, v36
	v_or_b32_e32 v36, s49, v37
	v_ashrrev_i32_e32 v55, 31, v54
	v_or_b32_e32 v50, s50, v36
	v_lshlrev_b64 v[36:37], 11, v[54:55]
	v_lshl_add_u64 v[36:37], s[6:7], 0, v[36:37]
	v_lshlrev_b32_e32 v128, 1, v50
	v_lshl_add_u64 v[36:37], v[36:37], 0, v[128:129]
	v_cvt_pk_bf16_f32 v50, v102, v103
	v_cvt_pk_bf16_f32 v51, v104, v105
	v_cvt_pk_bf16_f32 v52, v106, v107
	v_cvt_pk_bf16_f32 v53, v108, v109
	global_store_dwordx4 v[36:37], v[50:53], off
	s_cmpk_gt_u32 s27, 0xff
	s_nop 0
	v_cvt_pk_bf16_f32 v50, v138, v139
	v_cvt_pk_bf16_f32 v51, v140, v141
	v_cvt_pk_bf16_f32 v52, v70, v71
	v_cvt_pk_bf16_f32 v53, v72, v73
	global_store_dwordx4 v[36:37], v[50:53], off offset:256
	s_nop 1
	v_or_b32_e32 v50, 16, v54
	v_ashrrev_i32_e32 v51, 31, v50
	v_lshlrev_b64 v[50:51], 11, v[50:51]
	v_lshl_add_u64 v[50:51], s[6:7], 0, v[50:51]
	v_lshl_add_u64 v[56:57], v[50:51], 0, v[128:129]
	v_cvt_pk_bf16_f32 v50, v110, v111
	v_cvt_pk_bf16_f32 v51, v112, v113
	v_cvt_pk_bf16_f32 v52, v114, v115
	v_cvt_pk_bf16_f32 v53, v116, v117
	global_store_dwordx4 v[56:57], v[50:53], off
	s_nop 1
	v_cvt_pk_bf16_f32 v50, v74, v75
	v_cvt_pk_bf16_f32 v51, v76, v77
	v_cvt_pk_bf16_f32 v52, v78, v79
	v_cvt_pk_bf16_f32 v53, v80, v81
	global_store_dwordx4 v[56:57], v[50:53], off offset:256
	s_nop 1
	v_or_b32_e32 v50, 32, v54
	v_ashrrev_i32_e32 v51, 31, v50
	v_lshlrev_b64 v[50:51], 11, v[50:51]
	v_lshl_add_u64 v[50:51], s[6:7], 0, v[50:51]
	v_lshl_add_u64 v[56:57], v[50:51], 0, v[128:129]
	v_cvt_pk_bf16_f32 v50, v118, v119
	v_cvt_pk_bf16_f32 v51, v120, v121
	v_cvt_pk_bf16_f32 v52, v122, v123
	v_cvt_pk_bf16_f32 v53, v124, v125
	global_store_dwordx4 v[56:57], v[50:53], off
	s_nop 1
	v_cvt_pk_bf16_f32 v50, v82, v83
	v_cvt_pk_bf16_f32 v51, v84, v85
	v_cvt_pk_bf16_f32 v52, v86, v87
	v_cvt_pk_bf16_f32 v53, v88, v89
	global_store_dwordx4 v[56:57], v[50:53], off offset:256
	v_add_co_u32_e32 v56, vcc, s39, v36
	s_nop 0
	v_or_b32_e32 v50, 48, v54
	v_ashrrev_i32_e32 v51, 31, v50
	v_lshlrev_b64 v[50:51], 11, v[50:51]
	v_lshl_add_u64 v[50:51], s[6:7], 0, v[50:51]
	v_lshl_add_u64 v[54:55], v[50:51], 0, v[128:129]
	v_cvt_pk_bf16_f32 v50, v130, v131
	v_cvt_pk_bf16_f32 v51, v132, v133
	v_cvt_pk_bf16_f32 v52, v134, v135
	v_cvt_pk_bf16_f32 v53, v136, v137
	global_store_dwordx4 v[54:55], v[50:53], off
	v_addc_co_u32_e32 v57, vcc, 0, v37, vcc
	s_nop 0
	v_cvt_pk_bf16_f32 v50, v90, v91
	v_cvt_pk_bf16_f32 v51, v92, v93
	v_cvt_pk_bf16_f32 v52, v94, v95
	v_cvt_pk_bf16_f32 v53, v96, v97
	global_store_dwordx4 v[54:55], v[50:53], off offset:256
	v_lshl_add_u64 v[54:55], v[36:37], 0, s[8:9]
	s_nop 0
	v_cvt_pk_bf16_f32 v50, v218, v219
	v_cvt_pk_bf16_f32 v51, v220, v221
	v_cvt_pk_bf16_f32 v52, v222, v223
	v_cvt_pk_bf16_f32 v53, v224, v225
	global_store_dwordx4 v[56:57], v[50:53], off
	v_cvt_pk_bf16_f32 v38, v38, v39
	v_cvt_pk_bf16_f32 v39, v40, v41
	v_cvt_pk_bf16_f32 v40, v42, v43
	v_cvt_pk_bf16_f32 v41, v44, v45
	v_add_co_u32_e32 v44, vcc, s40, v36
	global_store_dwordx4 v[54:55], v[38:41], off offset:256
	v_lshl_add_u64 v[42:43], v[36:37], 0, s[16:17]
	v_addc_co_u32_e32 v45, vcc, 0, v37, vcc
	v_cvt_pk_bf16_f32 v38, v226, v227
	v_cvt_pk_bf16_f32 v39, v228, v229
	v_cvt_pk_bf16_f32 v40, v230, v231
	v_cvt_pk_bf16_f32 v41, v232, v233
	global_store_dwordx4 v[44:45], v[38:41], off
	s_nop 1
	v_cvt_pk_bf16_f32 v38, v46, v47
	v_cvt_pk_bf16_f32 v39, v48, v49
	v_cvt_pk_bf16_f32 v40, v32, v33
	v_cvt_pk_bf16_f32 v41, v34, v35
	global_store_dwordx4 v[42:43], v[38:41], off offset:256
	v_cvt_pk_bf16_f32 v28, v28, v29
	v_cvt_pk_bf16_f32 v29, v30, v31
	v_cvt_pk_bf16_f32 v30, v20, v21
	v_add_co_u32_e32 v20, vcc, s41, v36
	v_lshl_add_u64 v[32:33], v[36:37], 0, s[18:19]
	s_nop 0
	v_addc_co_u32_e32 v21, vcc, 0, v37, vcc
	v_cvt_pk_bf16_f32 v31, v22, v23
	global_store_dwordx4 v[20:21], v[28:31], off
	v_cvt_pk_bf16_f32 v20, v24, v25
	v_cvt_pk_bf16_f32 v21, v26, v27
	v_cvt_pk_bf16_f32 v22, v16, v17
	v_cvt_pk_bf16_f32 v23, v18, v19
	global_store_dwordx4 v[32:33], v[20:23], off offset:256
	v_cvt_pk_bf16_f32 v12, v12, v13
	v_cvt_pk_bf16_f32 v13, v14, v15
	v_cvt_pk_bf16_f32 v14, v4, v5
	v_add_co_u32_e32 v4, vcc, s45, v36
	v_lshl_add_u64 v[16:17], v[36:37], 0, s[20:21]
	s_nop 0
	v_addc_co_u32_e32 v5, vcc, 0, v37, vcc
	v_cvt_pk_bf16_f32 v15, v6, v7
	global_store_dwordx4 v[4:5], v[12:15], off
	v_cvt_pk_bf16_f32 v4, v8, v9
	v_cvt_pk_bf16_f32 v5, v10, v11
	v_cvt_pk_bf16_f32 v6, v0, v1
	v_cvt_pk_bf16_f32 v7, v2, v3
	global_store_dwordx4 v[16:17], v[4:7], off offset:256
	s_waitcnt vmcnt(0)
	s_cbranch_scc1 .LBB0_1296
	s_barrier
	s_branch .LBB0_1296
